# v4 plus: 39 GEMM LDS-DMA loads switched to SGPR-base + 32-bit VGPR offset form (64-bit VALU address adds removed)
# baseline (speedup 1.0000x reference)
; #define PG8_STAGE(bufoff, gbase, voff) do { _Pragma("unroll") for (int _i = 0; _i < 2; ++_i) \
;         __builtin_amdgcn_global_load_lds((const unsigned*)((const char*)(gbase) + (voff)[_i]), (PG8_LAS unsigned*)(lds + (bufoff) + ldsw + _i * 8192), 16, 0, 0); } while (0)
; #define PG8_LDA(dst, b, h) do { _Pragma("unroll") for (int m = 0; m < 4; ++m) _Pragma("unroll") for (int k = 0; k < 2; ++k) dst[m][k] = *(const PG8_LAS bf16x8*)(lds + PG8_SA(b, h) + aoff + m * 2048 + k * 1024); } while (0)
; #define PG8_LDB(dst, b, h) do { _Pragma("unroll") for (int n = 0; n < 2; ++n) _Pragma("unroll") for (int k = 0; k < 2; ++k) dst[n][k] = *(const PG8_LAS bf16x8*)(lds + PG8_SB(b, h) + boff + n * 2048 + k * 1024); } while (0)
; #define PG8_MMA(ai, bj, At, Bt) do { __builtin_amdgcn_s_setprio(1); _Pragma("unroll") for (int m = 0; m < 4; ++m) _Pragma("unroll") for (int n = 0; n < 2; ++n) _Pragma("unroll") for (int k = 0; k < 2; ++k) \
;         acc[ai][bj][m][n] = __builtin_amdgcn_mfma_f32_16x16x32_bf16(Bt[n][k], At[m][k], acc[ai][bj][m][n], 0, 0, 0); __builtin_amdgcn_s_setprio(0); } while (0)
; #define PG8_WAIT_V(n) asm volatile("s_waitcnt vmcnt(" #n ")" ::: "memory")
; #define PG8_BAR __builtin_amdgcn_s_barrier()
; template <class Epi, class Sched, bool ALIGN_EPI = false, bool SP2 = false>
; __device__ __forceinline__ void gemm_phase(PG8_LAS unsigned char* lds, const Gemm g, const Sched& S, const Epi& E, const int tid) {
;     ...
;         for (int t = 0; t < nt; t += 2) {
;             const bool last = (t == nt - 2);
;             const char* a1 = cA + (size_t)(t + 1) * kstep;
;             const char* a2 = last ? nA : cA + (size_t)(t + 2) * kstep; const char* b2 = last ? nB : cB + (size_t)(t + 2) * kstep;
;             const char* a3 = a2 + kstep; const char* b3 = b2 + kstep;
;             if (last && has_next) S.a_ready(nxt);
;             if constexpr (SP2) {
;             PG8_LDB(B0, 0, 0); PG8_LDB(B1, 0, 1); PG8_SCHED; PG8_LDA(At, 0, 0); PG8_STAGE(PG8_SA(1, 1), a1 + hstep, voffA);
;             PG8_WAIT_V(8); PG8_WAIT_L(0); PG8_BAR; PG8_MMA(0, 0, At, B0); PG8_MMA(0, 1, At, B1); PG8_BAR; PG8_SCHED;
;             PG8_LDA(At, 0, 1); PG8_STAGE(PG8_SB(0, 0), b2, voffB); PG8_STAGE(PG8_SB(0, 1), b2 + hstep, voffB); PG8_STAGE(PG8_SA(0, 0), a2, voffA);
;             PG8_WAIT_V(8); PG8_WAIT_L(0); PG8_BAR; PG8_MMA(1, 0, At, B0); PG8_MMA(1, 1, At, B1); PG8_BAR; PG8_SCHED;
.LBB0_144:
	s_add_i32 vcc_lo, s66, 2
	s_add_u32 s10, s0, 0x80
	s_addc_u32 s11, s1, 0
	s_add_i32 s12, 0, 0x10000
	s_cmp_eq_u32 s92, s66
	s_cselect_b32 s67, s43, s11
	s_cselect_b32 s66, s42, s10
	v_add_u32_e32 v143, s12, v140
	s_cselect_b32 s11, s65, s9
	s_cselect_b32 s10, s64, s8
	s_add_i32 s13, 0, 0x14000
	ds_read_b128 v[144:147], v143
	ds_read_b128 v[148:151], v143 offset:1024
	ds_read_b128 v[152:155], v143 offset:2048
	ds_read_b128 v[156:159], v143 offset:3072
	v_add_u32_e32 v143, s13, v140
	ds_read_b128 v[160:163], v143
	ds_read_b128 v[164:167], v143 offset:1024
	ds_read_b128 v[168:171], v143 offset:2048
	ds_read_b128 v[172:175], v143 offset:3072
	v_lshl_add_u64 v[212:213], s[0:1], 0, v[134:135]
	s_add_i32 m0, s77, 0xc000
	ds_read_b128 v[176:179], v142
	ds_read_b128 v[180:183], v142 offset:1024
	ds_read_b128 v[184:187], v142 offset:2048
	ds_read_b128 v[188:191], v142 offset:3072
	ds_read_b128 v[196:199], v142 offset:4096
	ds_read_b128 v[200:203], v142 offset:5120
	ds_read_b128 v[204:207], v142 offset:6144
	ds_read_b128 v[208:211], v142 offset:7168
	global_load_lds_dwordx4 v[212:213], off
	v_lshl_add_u64 v[212:213], s[0:1], 0, v[136:137]
	s_add_i32 m0, s77, 0xe000
	s_nop 0
	global_load_lds_dwordx4 v[212:213], off
	s_waitcnt vmcnt(8)
	s_waitcnt lgkmcnt(0)
	s_barrier
	s_setprio 1
	s_waitcnt lgkmcnt(0)
	v_mfma_f32_16x16x32_bf16 v[120:123], v[144:147], v[176:179], v[120:123]
	v_mfma_f32_16x16x32_bf16 v[124:127], v[152:155], v[176:179], v[124:127]
	v_mfma_f32_16x16x32_bf16 v[108:111], v[144:147], v[184:187], v[108:111]
	v_mfma_f32_16x16x32_bf16 v[104:107], v[152:155], v[184:187], v[104:107]
	v_mfma_f32_16x16x32_bf16 v[92:95], v[144:147], v[196:199], v[92:95]
	v_mfma_f32_16x16x32_bf16 v[88:91], v[152:155], v[196:199], v[88:91]
	v_mfma_f32_16x16x32_bf16 v[76:79], v[144:147], v[204:207], v[76:79]
	v_mfma_f32_16x16x32_bf16 v[72:75], v[152:155], v[204:207], v[72:75]
	v_mfma_f32_16x16x32_bf16 v[120:123], v[148:151], v[180:183], v[120:123]
	v_mfma_f32_16x16x32_bf16 v[124:127], v[156:159], v[180:183], v[124:127]
	v_mfma_f32_16x16x32_bf16 v[108:111], v[148:151], v[188:191], v[108:111]
	v_mfma_f32_16x16x32_bf16 v[104:107], v[156:159], v[188:191], v[104:107]
	v_mfma_f32_16x16x32_bf16 v[92:95], v[148:151], v[200:203], v[92:95]
	v_mfma_f32_16x16x32_bf16 v[88:91], v[156:159], v[200:203], v[88:91]
	v_mfma_f32_16x16x32_bf16 v[76:79], v[148:151], v[208:211], v[76:79]
	v_mfma_f32_16x16x32_bf16 v[72:75], v[156:159], v[208:211], v[72:75]
	s_setprio 0
	s_setprio 1
	v_mfma_f32_16x16x32_bf16 v[116:119], v[160:163], v[176:179], v[116:119]
	v_mfma_f32_16x16x32_bf16 v[112:115], v[168:171], v[176:179], v[112:115]
	v_mfma_f32_16x16x32_bf16 v[100:103], v[160:163], v[184:187], v[100:103]
	v_mfma_f32_16x16x32_bf16 v[96:99], v[168:171], v[184:187], v[96:99]
	v_mfma_f32_16x16x32_bf16 v[84:87], v[160:163], v[196:199], v[84:87]
	v_mfma_f32_16x16x32_bf16 v[80:83], v[168:171], v[196:199], v[80:83]
	v_mfma_f32_16x16x32_bf16 v[68:71], v[160:163], v[204:207], v[68:71]
	v_mfma_f32_16x16x32_bf16 v[64:67], v[168:171], v[204:207], v[64:67]
	v_mfma_f32_16x16x32_bf16 v[116:119], v[164:167], v[180:183], v[116:119]
	v_mfma_f32_16x16x32_bf16 v[112:115], v[172:175], v[180:183], v[112:115]
	v_mfma_f32_16x16x32_bf16 v[100:103], v[164:167], v[188:191], v[100:103]
	v_mfma_f32_16x16x32_bf16 v[96:99], v[172:175], v[188:191], v[96:99]
	v_mfma_f32_16x16x32_bf16 v[84:87], v[164:167], v[200:203], v[84:87]
	v_mfma_f32_16x16x32_bf16 v[80:83], v[172:175], v[200:203], v[80:83]
	v_mfma_f32_16x16x32_bf16 v[68:71], v[164:167], v[208:211], v[68:71]
	v_mfma_f32_16x16x32_bf16 v[64:67], v[172:175], v[208:211], v[64:67]
	s_setprio 0
	s_barrier
	s_add_i32 s12, s12, s4
	v_lshl_add_u64 v[212:213], s[10:11], 0, v[192:193]
	s_mov_b32 m0, s12
	ds_read_b128 v[176:179], v142 offset:16384
	ds_read_b128 v[180:183], v142 offset:17408
	ds_read_b128 v[184:187], v142 offset:18432
	ds_read_b128 v[188:191], v142 offset:19456
	ds_read_b128 v[196:199], v142 offset:20480
	ds_read_b128 v[200:203], v142 offset:21504
	ds_read_b128 v[204:207], v142 offset:22528
	ds_read_b128 v[208:211], v142 offset:23552
	global_load_lds_dwordx4 v[212:213], off
	s_add_i32 m0, s12, 0x2000
	v_lshl_add_u64 v[214:215], s[10:11], 0, v[128:129]
	s_add_u32 s10, s10, s30
	s_addc_u32 s11, s11, s31
	s_add_i32 s12, s13, s4
	global_load_lds_dwordx4 v[214:215], off
	v_lshl_add_u64 v[216:217], s[10:11], 0, v[192:193]
	s_mov_b32 m0, s12
	v_lshl_add_u64 v[218:219], s[10:11], 0, v[128:129]
	global_load_lds_dwordx4 v[216:217], off
	s_add_i32 m0, s12, 0x2000
	v_lshl_add_u64 v[220:221], s[66:67], 0, v[132:133]
	global_load_lds_dwordx4 v[218:219], off
	s_mov_b32 m0, s77
	v_lshl_add_u64 v[222:223], s[66:67], 0, v[130:131]
	global_load_lds_dwordx4 v[220:221], off
	s_mov_b32 m0, s82
	s_nop 0
	global_load_lds_dwordx4 v[222:223], off
	s_waitcnt vmcnt(8)
	s_waitcnt lgkmcnt(0)
	s_barrier
; #define PG8_STAGE(bufoff, gbase, voff) do { _Pragma("unroll") for (int _i = 0; _i < 2; ++_i) \
;         __builtin_amdgcn_global_load_lds((const unsigned*)((const char*)(gbase) + (voff)[_i]), (PG8_LAS unsigned*)(lds + (bufoff) + ldsw + _i * 8192), 16, 0, 0); } while (0)
; #define PG8_LDA(dst, b, h) do { _Pragma("unroll") for (int m = 0; m < 4; ++m) _Pragma("unroll") for (int k = 0; k < 2; ++k) dst[m][k] = *(const PG8_LAS bf16x8*)(lds + PG8_SA(b, h) + aoff + m * 2048 + k * 1024); } while (0)
; #define PG8_LDB(dst, b, h) do { _Pragma("unroll") for (int n = 0; n < 2; ++n) _Pragma("unroll") for (int k = 0; k < 2; ++k) dst[n][k] = *(const PG8_LAS bf16x8*)(lds + PG8_SB(b, h) + boff + n * 2048 + k * 1024); } while (0)
; #define PG8_MMA(ai, bj, At, Bt) do { __builtin_amdgcn_s_setprio(1); _Pragma("unroll") for (int m = 0; m < 4; ++m) _Pragma("unroll") for (int n = 0; n < 2; ++n) _Pragma("unroll") for (int k = 0; k < 2; ++k) \
;         acc[ai][bj][m][n] = __builtin_amdgcn_mfma_f32_16x16x32_bf16(Bt[n][k], At[m][k], acc[ai][bj][m][n], 0, 0, 0); __builtin_amdgcn_s_setprio(0); } while (0)
; #define PG8_WAIT_V(n) asm volatile("s_waitcnt vmcnt(" #n ")" ::: "memory")
; #define PG8_WAIT_L(n) asm volatile("s_waitcnt lgkmcnt(" #n ")" ::: "memory")
; #define PG8_BAR __builtin_amdgcn_s_barrier()
; #define PG8_SCHED __builtin_amdgcn_sched_barrier(0)
; template <class Epi, class Sched, bool ALIGN_EPI = false, bool SP2 = false>
; __device__ __forceinline__ void gemm_phase(PG8_LAS unsigned char* lds, const Gemm g, const Sched& S, const Epi& E, const int tid) {
;     ...
;             PG8_WAIT_V(8); PG8_WAIT_L(0); PG8_BAR; PG8_MMA(1, 0, At, B0); PG8_MMA(1, 1, At, B1); PG8_BAR; PG8_SCHED;
;             PG8_LDB(B0, 1, 0); PG8_LDB(B1, 1, 1); PG8_SCHED; PG8_LDA(At, 1, 0); PG8_STAGE(PG8_SA(0, 1), a2 + hstep, voffA);
;             PG8_WAIT_V(8); PG8_WAIT_L(0); PG8_BAR; PG8_MMA(0, 0, At, B0); PG8_MMA(0, 1, At, B1); PG8_BAR; PG8_SCHED;
	s_setprio 1
	s_waitcnt lgkmcnt(0)
	v_mfma_f32_16x16x32_bf16 v[60:63], v[144:147], v[176:179], v[60:63]
	v_mfma_f32_16x16x32_bf16 v[56:59], v[152:155], v[176:179], v[56:59]
	v_mfma_f32_16x16x32_bf16 v[44:47], v[144:147], v[184:187], v[44:47]
	v_mfma_f32_16x16x32_bf16 v[40:43], v[152:155], v[184:187], v[40:43]
	v_mfma_f32_16x16x32_bf16 v[28:31], v[144:147], v[196:199], v[28:31]
	v_mfma_f32_16x16x32_bf16 v[24:27], v[152:155], v[196:199], v[24:27]
	v_mfma_f32_16x16x32_bf16 v[12:15], v[144:147], v[204:207], v[12:15]
	v_mfma_f32_16x16x32_bf16 v[8:11], v[152:155], v[204:207], v[8:11]
	v_mfma_f32_16x16x32_bf16 v[60:63], v[148:151], v[180:183], v[60:63]
	v_mfma_f32_16x16x32_bf16 v[56:59], v[156:159], v[180:183], v[56:59]
	v_mfma_f32_16x16x32_bf16 v[44:47], v[148:151], v[188:191], v[44:47]
	v_mfma_f32_16x16x32_bf16 v[40:43], v[156:159], v[188:191], v[40:43]
	v_mfma_f32_16x16x32_bf16 v[28:31], v[148:151], v[200:203], v[28:31]
	v_mfma_f32_16x16x32_bf16 v[24:27], v[156:159], v[200:203], v[24:27]
	v_mfma_f32_16x16x32_bf16 v[12:15], v[148:151], v[208:211], v[12:15]
	v_mfma_f32_16x16x32_bf16 v[8:11], v[156:159], v[208:211], v[8:11]
	s_setprio 0
	s_setprio 1
	v_mfma_f32_16x16x32_bf16 v[52:55], v[160:163], v[176:179], v[52:55]
	v_mfma_f32_16x16x32_bf16 v[48:51], v[168:171], v[176:179], v[48:51]
	v_mfma_f32_16x16x32_bf16 v[36:39], v[160:163], v[184:187], v[36:39]
	v_mfma_f32_16x16x32_bf16 v[32:35], v[168:171], v[184:187], v[32:35]
	v_mfma_f32_16x16x32_bf16 v[20:23], v[160:163], v[196:199], v[20:23]
	v_mfma_f32_16x16x32_bf16 v[16:19], v[168:171], v[196:199], v[16:19]
	v_mfma_f32_16x16x32_bf16 v[4:7], v[160:163], v[204:207], v[4:7]
	v_mfma_f32_16x16x32_bf16 v[0:3], v[168:171], v[204:207], v[0:3]
	v_mfma_f32_16x16x32_bf16 v[52:55], v[164:167], v[180:183], v[52:55]
	v_mfma_f32_16x16x32_bf16 v[48:51], v[172:175], v[180:183], v[48:51]
	v_mfma_f32_16x16x32_bf16 v[36:39], v[164:167], v[188:191], v[36:39]
	v_mfma_f32_16x16x32_bf16 v[32:35], v[172:175], v[188:191], v[32:35]
	v_mfma_f32_16x16x32_bf16 v[20:23], v[164:167], v[200:203], v[20:23]
	v_mfma_f32_16x16x32_bf16 v[16:19], v[172:175], v[200:203], v[16:19]
	v_mfma_f32_16x16x32_bf16 v[4:7], v[164:167], v[208:211], v[4:7]
	v_mfma_f32_16x16x32_bf16 v[0:3], v[172:175], v[208:211], v[0:3]
	s_setprio 0
	s_barrier
	s_add_i32 s12, 0, 0x18000
	v_add_u32_e32 v143, s12, v140
	s_add_i32 s13, 0, 0x1c000
	ds_read_b128 v[144:147], v143
	ds_read_b128 v[148:151], v143 offset:1024
	ds_read_b128 v[152:155], v143 offset:2048
	ds_read_b128 v[156:159], v143 offset:3072
	v_add_u32_e32 v143, s13, v140
	ds_read_b128 v[160:163], v143
	ds_read_b128 v[164:167], v143 offset:1024
	ds_read_b128 v[168:171], v143 offset:2048
	ds_read_b128 v[172:175], v143 offset:3072
	s_add_u32 s10, s66, s30
	s_addc_u32 s11, s67, s31
	s_mov_b32 m0, s84
	ds_read_b128 v[176:179], v142 offset:32768
	ds_read_b128 v[180:183], v142 offset:33792
	ds_read_b128 v[184:187], v142 offset:34816
	ds_read_b128 v[188:191], v142 offset:35840
	ds_read_b128 v[196:199], v142 offset:36864
	ds_read_b128 v[200:203], v142 offset:37888
	ds_read_b128 v[204:207], v142 offset:38912
	ds_read_b128 v[208:211], v142 offset:39936
	global_load_lds_dwordx4 v132, s[10:11]
	v_lshl_add_u64 v[224:225], s[10:11], 0, v[130:131]
	s_mov_b32 m0, s85
	s_nop 0
	global_load_lds_dwordx4 v[224:225], off
	s_waitcnt vmcnt(8)
	s_waitcnt lgkmcnt(0)
	s_barrier
	s_setprio 1
	s_waitcnt lgkmcnt(0)
	v_mfma_f32_16x16x32_bf16 v[120:123], v[144:147], v[176:179], v[120:123]
	v_mfma_f32_16x16x32_bf16 v[124:127], v[152:155], v[176:179], v[124:127]
	v_mfma_f32_16x16x32_bf16 v[108:111], v[144:147], v[184:187], v[108:111]
	v_mfma_f32_16x16x32_bf16 v[104:107], v[152:155], v[184:187], v[104:107]
	v_mfma_f32_16x16x32_bf16 v[92:95], v[144:147], v[196:199], v[92:95]
	v_mfma_f32_16x16x32_bf16 v[88:91], v[152:155], v[196:199], v[88:91]
	v_mfma_f32_16x16x32_bf16 v[76:79], v[144:147], v[204:207], v[76:79]
	v_mfma_f32_16x16x32_bf16 v[72:75], v[152:155], v[204:207], v[72:75]
	v_mfma_f32_16x16x32_bf16 v[120:123], v[148:151], v[180:183], v[120:123]
	v_mfma_f32_16x16x32_bf16 v[124:127], v[156:159], v[180:183], v[124:127]
	v_mfma_f32_16x16x32_bf16 v[108:111], v[148:151], v[188:191], v[108:111]
	v_mfma_f32_16x16x32_bf16 v[104:107], v[156:159], v[188:191], v[104:107]
	v_mfma_f32_16x16x32_bf16 v[92:95], v[148:151], v[200:203], v[92:95]
	v_mfma_f32_16x16x32_bf16 v[88:91], v[156:159], v[200:203], v[88:91]
	v_mfma_f32_16x16x32_bf16 v[76:79], v[148:151], v[208:211], v[76:79]
	v_mfma_f32_16x16x32_bf16 v[72:75], v[156:159], v[208:211], v[72:75]
	s_setprio 0
	s_setprio 1
	v_mfma_f32_16x16x32_bf16 v[116:119], v[160:163], v[176:179], v[116:119]
	v_mfma_f32_16x16x32_bf16 v[112:115], v[168:171], v[176:179], v[112:115]
	v_mfma_f32_16x16x32_bf16 v[100:103], v[160:163], v[184:187], v[100:103]
	v_mfma_f32_16x16x32_bf16 v[96:99], v[168:171], v[184:187], v[96:99]
	v_mfma_f32_16x16x32_bf16 v[84:87], v[160:163], v[196:199], v[84:87]
	v_mfma_f32_16x16x32_bf16 v[80:83], v[168:171], v[196:199], v[80:83]
	v_mfma_f32_16x16x32_bf16 v[68:71], v[160:163], v[204:207], v[68:71]
	v_mfma_f32_16x16x32_bf16 v[64:67], v[168:171], v[204:207], v[64:67]
	v_mfma_f32_16x16x32_bf16 v[116:119], v[164:167], v[180:183], v[116:119]
	v_mfma_f32_16x16x32_bf16 v[112:115], v[172:175], v[180:183], v[112:115]
	v_mfma_f32_16x16x32_bf16 v[100:103], v[164:167], v[188:191], v[100:103]
	v_mfma_f32_16x16x32_bf16 v[96:99], v[172:175], v[188:191], v[96:99]
	v_mfma_f32_16x16x32_bf16 v[84:87], v[164:167], v[200:203], v[84:87]
	v_mfma_f32_16x16x32_bf16 v[80:83], v[172:175], v[200:203], v[80:83]
	v_mfma_f32_16x16x32_bf16 v[68:71], v[164:167], v[208:211], v[68:71]
	v_mfma_f32_16x16x32_bf16 v[64:67], v[172:175], v[208:211], v[64:67]
	s_setprio 0
	s_barrier
; #define PG8_STAGE(bufoff, gbase, voff) do { _Pragma("unroll") for (int _i = 0; _i < 2; ++_i) \
;         __builtin_amdgcn_global_load_lds((const unsigned*)((const char*)(gbase) + (voff)[_i]), (PG8_LAS unsigned*)(lds + (bufoff) + ldsw + _i * 8192), 16, 0, 0); } while (0)
; #define PG8_LDA(dst, b, h) do { _Pragma("unroll") for (int m = 0; m < 4; ++m) _Pragma("unroll") for (int k = 0; k < 2; ++k) dst[m][k] = *(const PG8_LAS bf16x8*)(lds + PG8_SA(b, h) + aoff + m * 2048 + k * 1024); } while (0)
; #define PG8_MMA(ai, bj, At, Bt) do { __builtin_amdgcn_s_setprio(1); _Pragma("unroll") for (int m = 0; m < 4; ++m) _Pragma("unroll") for (int n = 0; n < 2; ++n) _Pragma("unroll") for (int k = 0; k < 2; ++k) \
;         acc[ai][bj][m][n] = __builtin_amdgcn_mfma_f32_16x16x32_bf16(Bt[n][k], At[m][k], acc[ai][bj][m][n], 0, 0, 0); __builtin_amdgcn_s_setprio(0); } while (0)
; #define PG8_WAIT_V(n) asm volatile("s_waitcnt vmcnt(" #n ")" ::: "memory")
; #define PG8_WAIT_L(n) asm volatile("s_waitcnt lgkmcnt(" #n ")" ::: "memory")
; #define PG8_BAR __builtin_amdgcn_s_barrier()
; #define PG8_SCHED __builtin_amdgcn_sched_barrier(0)
; template <class Epi, class Sched, bool ALIGN_EPI = false, bool SP2 = false>
; __device__ __forceinline__ void gemm_phase(PG8_LAS unsigned char* lds, const Gemm g, const Sched& S, const Epi& E, const int tid) {
;     ...
;             PG8_LDA(At, 1, 1); PG8_STAGE(PG8_SB(1, 0), b3, voffB); PG8_STAGE(PG8_SB(1, 1), b3 + hstep, voffB); PG8_STAGE(PG8_SA(1, 0), a3, voffA);
;             PG8_WAIT_V(8); PG8_WAIT_L(0); PG8_BAR; PG8_MMA(1, 0, At, B0); PG8_MMA(1, 1, At, B1); PG8_BAR; PG8_SCHED;
	s_add_i32 s10, s12, s4
	v_lshl_add_u64 v[212:213], v[212:213], 0, s[22:23]
	s_mov_b32 m0, s10
	ds_read_b128 v[176:179], v142 offset:49152
	ds_read_b128 v[180:183], v142 offset:50176
	ds_read_b128 v[184:187], v142 offset:51200
	ds_read_b128 v[188:191], v142 offset:52224
	ds_read_b128 v[196:199], v142 offset:53248
	ds_read_b128 v[200:203], v142 offset:54272
	ds_read_b128 v[204:207], v142 offset:55296
	ds_read_b128 v[208:211], v142 offset:56320
	global_load_lds_dwordx4 v[212:213], off
	v_lshl_add_u64 v[212:213], v[214:215], 0, s[22:23]
	s_add_i32 m0, s10, 0x2000
	s_add_i32 s10, s13, s4
	global_load_lds_dwordx4 v[212:213], off
	v_lshl_add_u64 v[212:213], v[216:217], 0, s[22:23]
	s_mov_b32 m0, s10
	s_nop 0
	global_load_lds_dwordx4 v[212:213], off
	v_lshl_add_u64 v[212:213], v[218:219], 0, s[22:23]
	s_add_i32 m0, s10, 0x2000
	s_nop 0
	global_load_lds_dwordx4 v[212:213], off
	v_lshl_add_u64 v[212:213], v[220:221], 0, s[22:23]
	s_mov_b32 m0, s88
	s_nop 0
	global_load_lds_dwordx4 v[212:213], off
	v_lshl_add_u64 v[212:213], v[222:223], 0, s[22:23]
	s_mov_b32 m0, s89
	s_nop 0
	global_load_lds_dwordx4 v[212:213], off
	s_waitcnt vmcnt(8)
	s_waitcnt lgkmcnt(0)
	s_barrier
	s_setprio 1
	s_waitcnt lgkmcnt(0)
	v_mfma_f32_16x16x32_bf16 v[60:63], v[144:147], v[176:179], v[60:63]
	v_mfma_f32_16x16x32_bf16 v[56:59], v[152:155], v[176:179], v[56:59]
	v_mfma_f32_16x16x32_bf16 v[44:47], v[144:147], v[184:187], v[44:47]
	v_mfma_f32_16x16x32_bf16 v[40:43], v[152:155], v[184:187], v[40:43]
	v_mfma_f32_16x16x32_bf16 v[28:31], v[144:147], v[196:199], v[28:31]
	v_mfma_f32_16x16x32_bf16 v[24:27], v[152:155], v[196:199], v[24:27]
	v_mfma_f32_16x16x32_bf16 v[12:15], v[144:147], v[204:207], v[12:15]
	v_mfma_f32_16x16x32_bf16 v[8:11], v[152:155], v[204:207], v[8:11]
	v_mfma_f32_16x16x32_bf16 v[60:63], v[148:151], v[180:183], v[60:63]
	v_mfma_f32_16x16x32_bf16 v[56:59], v[156:159], v[180:183], v[56:59]
	v_mfma_f32_16x16x32_bf16 v[44:47], v[148:151], v[188:191], v[44:47]
	v_mfma_f32_16x16x32_bf16 v[40:43], v[156:159], v[188:191], v[40:43]
	v_mfma_f32_16x16x32_bf16 v[28:31], v[148:151], v[200:203], v[28:31]
	v_mfma_f32_16x16x32_bf16 v[24:27], v[156:159], v[200:203], v[24:27]
	v_mfma_f32_16x16x32_bf16 v[12:15], v[148:151], v[208:211], v[12:15]
	v_mfma_f32_16x16x32_bf16 v[8:11], v[156:159], v[208:211], v[8:11]
	s_setprio 0
	s_setprio 1
	v_mfma_f32_16x16x32_bf16 v[52:55], v[160:163], v[176:179], v[52:55]
	v_mfma_f32_16x16x32_bf16 v[48:51], v[168:171], v[176:179], v[48:51]
	v_mfma_f32_16x16x32_bf16 v[36:39], v[160:163], v[184:187], v[36:39]
	v_mfma_f32_16x16x32_bf16 v[32:35], v[168:171], v[184:187], v[32:35]
	v_mfma_f32_16x16x32_bf16 v[20:23], v[160:163], v[196:199], v[20:23]
	v_mfma_f32_16x16x32_bf16 v[16:19], v[168:171], v[196:199], v[16:19]
	v_mfma_f32_16x16x32_bf16 v[4:7], v[160:163], v[204:207], v[4:7]
	v_mfma_f32_16x16x32_bf16 v[0:3], v[168:171], v[204:207], v[0:3]
	v_mfma_f32_16x16x32_bf16 v[52:55], v[164:167], v[180:183], v[52:55]
	v_mfma_f32_16x16x32_bf16 v[48:51], v[172:175], v[180:183], v[48:51]
	v_mfma_f32_16x16x32_bf16 v[36:39], v[164:167], v[188:191], v[36:39]
	v_mfma_f32_16x16x32_bf16 v[32:35], v[172:175], v[188:191], v[32:35]
	v_mfma_f32_16x16x32_bf16 v[20:23], v[164:167], v[200:203], v[20:23]
	v_mfma_f32_16x16x32_bf16 v[16:19], v[172:175], v[200:203], v[16:19]
	v_mfma_f32_16x16x32_bf16 v[4:7], v[164:167], v[208:211], v[4:7]
	v_mfma_f32_16x16x32_bf16 v[0:3], v[172:175], v[208:211], v[0:3]
	s_setprio 0
	s_barrier
	s_add_u32 s0, s0, 0x100
	s_addc_u32 s1, s1, 0
	s_add_u32 s8, s8, 0x100
	s_addc_u32 s9, s9, 0
	s_cmp_ge_i32 vcc_lo, s86
	s_mov_b32 s66, vcc_lo
	s_cbranch_scc0 .LBB0_144

; #define PG8_STAGE(bufoff, gbase, voff) do { _Pragma("unroll") for (int _i = 0; _i < 2; ++_i) \
;         __builtin_amdgcn_global_load_lds((const unsigned*)((const char*)(gbase) + (voff)[_i]), (PG8_LAS unsigned*)(lds + (bufoff) + ldsw + _i * 8192), 16, 0, 0); } while (0)
; #define PG8_WAIT_V(n) asm volatile("s_waitcnt vmcnt(" #n ")" ::: "memory")
; #define PG8_BAR __builtin_amdgcn_s_barrier()
; template <class Epi, class Sched, bool ALIGN_EPI = false, bool SP2 = false>
; __device__ __forceinline__ void gemm_phase(PG8_LAS unsigned char* lds, const Gemm g, const Sched& S, const Epi& E, const int tid) {
;     ...
;     if constexpr (SP2) {
;         PG8_STAGE(PG8_SB(0, 0), cB, voffB); PG8_STAGE(PG8_SB(0, 1), cB + hstep, voffB); PG8_STAGE(PG8_SA(0, 0), cA, voffA); PG8_STAGE(PG8_SA(0, 1), cA + hstep, voffA);
;         if (wr == 1) PG8_BAR;
;         PG8_WAIT_V(2); PG8_BAR;
;         PG8_STAGE(PG8_SB(1, 0), cB + kstep, voffB); PG8_STAGE(PG8_SA(1, 0), cA + kstep, voffA); PG8_STAGE(PG8_SB(1, 1), cB + hstep + kstep, voffB);
;         PG8_WAIT_V(6); PG8_BAR;
.LBB0_156:
	v_bfe_u32 v15, v138, 4, 2
	v_and_b32_e32 v14, 15, v138
	v_lshlrev_b32_e32 v17, 4, v15
	v_lshl_or_b32 v195, s38, 6, v14
	v_lshl_or_b32 v14, v14, 6, v17
	v_lshlrev_b32_e32 v17, 2, v138
	s_and_b32 s97, s9, 3
	s_lshl_b32 s9, s38, 13
	v_and_b32_e32 v17, 32, v17
	v_readlane_b32 s10, v255, 24
	v_bitop3_b32 v18, v14, s9, v17 bitop3:0xde
	s_lshl_b32 s9, s97, 12
	v_readlane_b32 s11, v255, 25
	s_and_b64 s[10:11], s[10:11], exec
	v_bitop3_b32 v224, v14, s9, v17 bitop3:0xde
	s_cselect_b32 s9, 0, 0x4000000
	s_add_u32 s9, s60, s9
	s_addc_u32 s10, s61, 0
	s_sub_i32 s11, s94, 25
	s_cmp_lt_u32 s11, 8
	s_cselect_b32 s57, s10, 0
	s_cselect_b32 s56, s9, 0
	s_cmp_lg_u64 s[56:57], 0
	s_cselect_b64 s[58:59], -1, 0
	s_add_i32 m0, s7, 0x18000
	v_lshl_add_u64 v[6:7], v[6:7], 0, s[22:23]
	s_waitcnt vmcnt(2)
	s_barrier
	global_load_lds_dwordx4 v[6:7], off
	v_lshl_add_u64 v[4:5], v[4:5], 0, s[22:23]
	s_add_i32 m0, s7, 0x1a000
	s_add_i32 s89, s7, 0x8000
	s_add_i32 s95, s7, 0xa000
	global_load_lds_dwordx4 v[4:5], off
	v_lshl_add_u64 v[0:1], v[0:1], 0, s[22:23]
	s_mov_b32 m0, s89
	s_add_u32 s10, s52, 0x40080
	global_load_lds_dwordx4 v[0:1], off
	v_lshl_add_u64 v[0:1], v[2:3], 0, s[22:23]
	s_mov_b32 m0, s95
	s_addc_u32 s11, s53, 0
	global_load_lds_dwordx4 v[0:1], off
	s_add_i32 m0, s7, 0x1c000
	s_nop 0
	global_load_lds_dwordx4 v192, s[10:11]
	v_lshl_add_u64 v[0:1], s[10:11], 0, v[200:201]
	s_add_i32 m0, s7, 0x1e000
	v_lshlrev_b32_e32 v16, 3, v15
	global_load_lds_dwordx4 v[0:1], off
	v_and_b32_e32 v1, 64, v245
	v_xor_b32_e32 v0, 16, v245
	v_add_u32_e32 v1, 64, v1
	v_cmp_lt_i32_e32 vcc, v0, v1
	s_waitcnt vmcnt(6)
	s_cmpk_lt_u32 s8, 0x100
	s_mov_b32 s88, 0
	v_cndmask_b32_e32 v0, v245, v0, vcc
	v_lshlrev_b32_e32 v226, 2, v0
	v_xor_b32_e32 v0, 32, v245
	v_cmp_lt_i32_e32 vcc, v0, v1
	v_and_b32_e32 v1, 1, v8
	v_lshl_or_b32 v225, s97, 5, v16
	v_cndmask_b32_e32 v0, v245, v0, vcc
	v_lshlrev_b32_e32 v227, 2, v0
	v_lshlrev_b32_e32 v0, 14, v8
	v_and_b32_e32 v0, 0xffff8000, v0
	v_lshl_add_u32 v0, v9, 11, v0
	v_lshl_or_b32 v0, v1, 6, v0
	v_lshl_add_u32 v202, v10, 1, v0
	v_lshlrev_b32_e32 v0, 14, v11
	v_and_b32_e32 v0, 0xffff8000, v0
	v_lshl_add_u32 v0, v12, 11, v0
	v_and_b32_e32 v1, 1, v11
	v_lshl_or_b32 v0, v1, 6, v0
	s_cselect_b64 s[60:61], -1, 0
	v_cmp_eq_u32_e64 s[38:39], 0, v15
	v_mov_b32_e32 v203, v193
	v_lshl_add_u32 v204, v13, 1, v0
	v_mov_b32_e32 v205, v193
	v_add_u32_e32 v228, 0, v18
	s_barrier
	s_branch .LBB0_159

; #define PG8_STAGE(bufoff, gbase, voff) do { _Pragma("unroll") for (int _i = 0; _i < 2; ++_i) \
;         __builtin_amdgcn_global_load_lds((const unsigned*)((const char*)(gbase) + (voff)[_i]), (PG8_LAS unsigned*)(lds + (bufoff) + ldsw + _i * 8192), 16, 0, 0); } while (0)
; #define PG8_LDA(dst, b, h) do { _Pragma("unroll") for (int m = 0; m < 4; ++m) _Pragma("unroll") for (int k = 0; k < 2; ++k) dst[m][k] = *(const PG8_LAS bf16x8*)(lds + PG8_SA(b, h) + aoff + m * 2048 + k * 1024); } while (0)
; #define PG8_LDB(dst, b, h) do { _Pragma("unroll") for (int n = 0; n < 2; ++n) _Pragma("unroll") for (int k = 0; k < 2; ++k) dst[n][k] = *(const PG8_LAS bf16x8*)(lds + PG8_SB(b, h) + boff + n * 2048 + k * 1024); } while (0)
; #define PG8_MMA(ai, bj, At, Bt) do { __builtin_amdgcn_s_setprio(1); _Pragma("unroll") for (int m = 0; m < 4; ++m) _Pragma("unroll") for (int n = 0; n < 2; ++n) _Pragma("unroll") for (int k = 0; k < 2; ++k) \
;         acc[ai][bj][m][n] = __builtin_amdgcn_mfma_f32_16x16x32_bf16(Bt[n][k], At[m][k], acc[ai][bj][m][n], 0, 0, 0); __builtin_amdgcn_s_setprio(0); } while (0)
; #define PG8_WAIT_V(n) asm volatile("s_waitcnt vmcnt(" #n ")" ::: "memory")
; #define PG8_WAIT_L(n) asm volatile("s_waitcnt lgkmcnt(" #n ")" ::: "memory")
; template <class Epi, class Sched, bool ALIGN_EPI = false, bool SP2 = false>
; __device__ __forceinline__ void gemm_phase(PG8_LAS unsigned char* lds, const Gemm g, const Sched& S, const Epi& E, const int tid) {
;     ...
;             const bool last = (t == nt - 2);
;             const char* a1 = cA + (size_t)(t + 1) * kstep;
;             const char* a2 = last ? nA : cA + (size_t)(t + 2) * kstep; const char* b2 = last ? nB : cB + (size_t)(t + 2) * kstep;
;             const char* a3 = a2 + kstep; const char* b3 = b2 + kstep;
;             if (last && has_next) S.a_ready(nxt);
;             if constexpr (SP2) {
;             PG8_LDB(B0, 0, 0); PG8_LDB(B1, 0, 1); PG8_SCHED; PG8_LDA(At, 0, 0); PG8_STAGE(PG8_SA(1, 1), a1 + hstep, voffA);
;             PG8_WAIT_V(8); PG8_WAIT_L(0); PG8_BAR; PG8_MMA(0, 0, At, B0); PG8_MMA(0, 1, At, B1); PG8_BAR; PG8_SCHED;
;             PG8_LDA(At, 0, 1); PG8_STAGE(PG8_SB(0, 0), b2, voffB); PG8_STAGE(PG8_SB(0, 1), b2 + hstep, voffB); PG8_STAGE(PG8_SA(0, 0), a2, voffA);
;             PG8_WAIT_V(8); PG8_WAIT_L(0); PG8_BAR; PG8_MMA(1, 0, At, B0); PG8_MMA(1, 1, At, B1); PG8_BAR; PG8_SCHED;
.LBB0_166:
	s_add_u32 s10, s0, 0xfffc0080
	s_addc_u32 s11, s1, -1
	s_add_i32 s12, 0, 0x10000
	s_cmp_eq_u32 s9, 12
	s_cselect_b32 s87, s31, s11
	s_cselect_b32 s86, s43, s10
	s_cselect_b32 s53, s65, s8
	s_cselect_b32 s52, s67, s82
	s_add_i32 s13, 0, 0x14000
	v_add_u32_e32 v124, s12, v224
	v_add_u32_e32 v152, s13, v224
	ds_read_b128 v[112:115], v124
	ds_read_b128 v[116:119], v124 offset:1024
	ds_read_b128 v[120:123], v124 offset:2048
	ds_read_b128 v[124:127], v124 offset:3072
	ds_read_b128 v[140:143], v152
	ds_read_b128 v[144:147], v152 offset:1024
	ds_read_b128 v[148:151], v152 offset:2048
	ds_read_b128 v[152:155], v152 offset:3072
	s_add_i32 m0, s7, 0xc000
	ds_read_b128 v[160:163], v228
	ds_read_b128 v[164:167], v228 offset:1024
	ds_read_b128 v[168:171], v228 offset:2048
	ds_read_b128 v[172:175], v228 offset:3072
	ds_read_b128 v[176:179], v228 offset:4096
	ds_read_b128 v[180:183], v228 offset:5120
	ds_read_b128 v[184:187], v228 offset:6144
	ds_read_b128 v[188:191], v228 offset:7168
	global_load_lds_dwordx4 v202, s[0:1]
	s_add_i32 m0, s7, 0xe000
	s_nop 0
	global_load_lds_dwordx4 v204, s[0:1]
	s_waitcnt vmcnt(8)
	s_waitcnt lgkmcnt(0)
	s_barrier
	s_setprio 1
	s_waitcnt lgkmcnt(0)
	v_mfma_f32_16x16x32_bf16 v[156:159], v[112:115], v[160:163], v[156:159]
	v_mfma_f32_16x16x32_bf16 v[136:139], v[120:123], v[160:163], v[136:139]
	v_mfma_f32_16x16x32_bf16 v[108:111], v[112:115], v[168:171], v[108:111]
	v_mfma_f32_16x16x32_bf16 v[104:107], v[120:123], v[168:171], v[104:107]
	v_mfma_f32_16x16x32_bf16 v[92:95], v[112:115], v[176:179], v[92:95]
	v_mfma_f32_16x16x32_bf16 v[88:91], v[120:123], v[176:179], v[88:91]
	v_mfma_f32_16x16x32_bf16 v[76:79], v[112:115], v[184:187], v[76:79]
	v_mfma_f32_16x16x32_bf16 v[72:75], v[120:123], v[184:187], v[72:75]
	v_mfma_f32_16x16x32_bf16 v[156:159], v[116:119], v[164:167], v[156:159]
	v_mfma_f32_16x16x32_bf16 v[136:139], v[124:127], v[164:167], v[136:139]
	v_mfma_f32_16x16x32_bf16 v[108:111], v[116:119], v[172:175], v[108:111]
	v_mfma_f32_16x16x32_bf16 v[104:107], v[124:127], v[172:175], v[104:107]
	v_mfma_f32_16x16x32_bf16 v[92:95], v[116:119], v[180:183], v[92:95]
	v_mfma_f32_16x16x32_bf16 v[88:91], v[124:127], v[180:183], v[88:91]
	v_mfma_f32_16x16x32_bf16 v[76:79], v[116:119], v[188:191], v[76:79]
	v_mfma_f32_16x16x32_bf16 v[72:75], v[124:127], v[188:191], v[72:75]
	s_setprio 0
	s_setprio 1
	v_mfma_f32_16x16x32_bf16 v[132:135], v[140:143], v[160:163], v[132:135]
	v_mfma_f32_16x16x32_bf16 v[128:131], v[148:151], v[160:163], v[128:131]
	v_mfma_f32_16x16x32_bf16 v[100:103], v[140:143], v[168:171], v[100:103]
	v_mfma_f32_16x16x32_bf16 v[96:99], v[148:151], v[168:171], v[96:99]
	v_mfma_f32_16x16x32_bf16 v[84:87], v[140:143], v[176:179], v[84:87]
	v_mfma_f32_16x16x32_bf16 v[80:83], v[148:151], v[176:179], v[80:83]
	v_mfma_f32_16x16x32_bf16 v[68:71], v[140:143], v[184:187], v[68:71]
	v_mfma_f32_16x16x32_bf16 v[64:67], v[148:151], v[184:187], v[64:67]
	v_mfma_f32_16x16x32_bf16 v[132:135], v[144:147], v[164:167], v[132:135]
	v_mfma_f32_16x16x32_bf16 v[128:131], v[152:155], v[164:167], v[128:131]
	v_mfma_f32_16x16x32_bf16 v[100:103], v[144:147], v[172:175], v[100:103]
	v_mfma_f32_16x16x32_bf16 v[96:99], v[152:155], v[172:175], v[96:99]
	v_mfma_f32_16x16x32_bf16 v[84:87], v[144:147], v[180:183], v[84:87]
	v_mfma_f32_16x16x32_bf16 v[80:83], v[152:155], v[180:183], v[80:83]
	v_mfma_f32_16x16x32_bf16 v[68:71], v[144:147], v[188:191], v[68:71]
	v_mfma_f32_16x16x32_bf16 v[64:67], v[152:155], v[188:191], v[64:67]
	s_setprio 0
	s_barrier
	s_add_i32 s10, s12, s4
	v_lshl_add_u64 v[206:207], s[52:53], 0, v[192:193]
	s_mov_b32 m0, s10
	ds_read_b128 v[160:163], v228 offset:16384
	ds_read_b128 v[164:167], v228 offset:17408
	ds_read_b128 v[168:171], v228 offset:18432
	ds_read_b128 v[172:175], v228 offset:19456
	ds_read_b128 v[176:179], v228 offset:20480
	ds_read_b128 v[180:183], v228 offset:21504
	ds_read_b128 v[184:187], v228 offset:22528
	ds_read_b128 v[188:191], v228 offset:23552
	global_load_lds_dwordx4 v[206:207], off
	s_add_i32 m0, s10, 0x2000
	s_add_u32 s10, s52, 0x40000
	v_lshl_add_u64 v[208:209], s[52:53], 0, v[200:201]
	s_addc_u32 s11, s53, 0
	s_add_i32 s12, s13, s4
	global_load_lds_dwordx4 v[208:209], off
	s_mov_b32 m0, s12
	v_lshl_add_u64 v[212:213], s[86:87], 0, v[198:199]
	global_load_lds_dwordx4 v192, s[10:11]
	s_add_i32 m0, s12, 0x2000
	s_nop 0
	global_load_lds_dwordx4 v200, s[10:11]
	v_lshl_add_u64 v[210:211], s[86:87], 0, v[196:197]
	s_mov_b32 m0, s7
	s_nop 0
	global_load_lds_dwordx4 v[210:211], off
	s_mov_b32 m0, s76
	s_nop 0
	global_load_lds_dwordx4 v[212:213], off
	s_waitcnt vmcnt(8)
	s_waitcnt lgkmcnt(0)
	s_barrier
; #define PG8_STAGE(bufoff, gbase, voff) do { _Pragma("unroll") for (int _i = 0; _i < 2; ++_i) \
;         __builtin_amdgcn_global_load_lds((const unsigned*)((const char*)(gbase) + (voff)[_i]), (PG8_LAS unsigned*)(lds + (bufoff) + ldsw + _i * 8192), 16, 0, 0); } while (0)
; #define PG8_LDA(dst, b, h) do { _Pragma("unroll") for (int m = 0; m < 4; ++m) _Pragma("unroll") for (int k = 0; k < 2; ++k) dst[m][k] = *(const PG8_LAS bf16x8*)(lds + PG8_SA(b, h) + aoff + m * 2048 + k * 1024); } while (0)
; #define PG8_LDB(dst, b, h) do { _Pragma("unroll") for (int n = 0; n < 2; ++n) _Pragma("unroll") for (int k = 0; k < 2; ++k) dst[n][k] = *(const PG8_LAS bf16x8*)(lds + PG8_SB(b, h) + boff + n * 2048 + k * 1024); } while (0)
; #define PG8_MMA(ai, bj, At, Bt) do { __builtin_amdgcn_s_setprio(1); _Pragma("unroll") for (int m = 0; m < 4; ++m) _Pragma("unroll") for (int n = 0; n < 2; ++n) _Pragma("unroll") for (int k = 0; k < 2; ++k) \
;         acc[ai][bj][m][n] = __builtin_amdgcn_mfma_f32_16x16x32_bf16(Bt[n][k], At[m][k], acc[ai][bj][m][n], 0, 0, 0); __builtin_amdgcn_s_setprio(0); } while (0)
; #define PG8_WAIT_V(n) asm volatile("s_waitcnt vmcnt(" #n ")" ::: "memory")
; #define PG8_WAIT_L(n) asm volatile("s_waitcnt lgkmcnt(" #n ")" ::: "memory")
; #define PG8_BAR __builtin_amdgcn_s_barrier()
; #define PG8_SCHED __builtin_amdgcn_sched_barrier(0)
; template <class Epi, class Sched, bool ALIGN_EPI = false, bool SP2 = false>
; __device__ __forceinline__ void gemm_phase(PG8_LAS unsigned char* lds, const Gemm g, const Sched& S, const Epi& E, const int tid) {
;     ...
;             PG8_WAIT_V(8); PG8_WAIT_L(0); PG8_BAR; PG8_MMA(1, 0, At, B0); PG8_MMA(1, 1, At, B1); PG8_BAR; PG8_SCHED;
;             PG8_LDB(B0, 1, 0); PG8_LDB(B1, 1, 1); PG8_SCHED; PG8_LDA(At, 1, 0); PG8_STAGE(PG8_SA(0, 1), a2 + hstep, voffA);
;             PG8_WAIT_V(8); PG8_WAIT_L(0); PG8_BAR; PG8_MMA(0, 0, At, B0); PG8_MMA(0, 1, At, B1); PG8_BAR; PG8_SCHED;
	s_setprio 1
	s_waitcnt lgkmcnt(0)
	v_mfma_f32_16x16x32_bf16 v[60:63], v[112:115], v[160:163], v[60:63]
	v_mfma_f32_16x16x32_bf16 v[56:59], v[120:123], v[160:163], v[56:59]
	v_mfma_f32_16x16x32_bf16 v[44:47], v[112:115], v[168:171], v[44:47]
	v_mfma_f32_16x16x32_bf16 v[40:43], v[120:123], v[168:171], v[40:43]
	v_mfma_f32_16x16x32_bf16 v[28:31], v[112:115], v[176:179], v[28:31]
	v_mfma_f32_16x16x32_bf16 v[24:27], v[120:123], v[176:179], v[24:27]
	v_mfma_f32_16x16x32_bf16 v[12:15], v[112:115], v[184:187], v[12:15]
	v_mfma_f32_16x16x32_bf16 v[8:11], v[120:123], v[184:187], v[8:11]
	v_mfma_f32_16x16x32_bf16 v[60:63], v[116:119], v[164:167], v[60:63]
	v_mfma_f32_16x16x32_bf16 v[56:59], v[124:127], v[164:167], v[56:59]
	v_mfma_f32_16x16x32_bf16 v[44:47], v[116:119], v[172:175], v[44:47]
	v_mfma_f32_16x16x32_bf16 v[40:43], v[124:127], v[172:175], v[40:43]
	v_mfma_f32_16x16x32_bf16 v[28:31], v[116:119], v[180:183], v[28:31]
	v_mfma_f32_16x16x32_bf16 v[24:27], v[124:127], v[180:183], v[24:27]
	v_mfma_f32_16x16x32_bf16 v[12:15], v[116:119], v[188:191], v[12:15]
	v_mfma_f32_16x16x32_bf16 v[8:11], v[124:127], v[188:191], v[8:11]
	s_setprio 0
	s_setprio 1
	v_mfma_f32_16x16x32_bf16 v[52:55], v[140:143], v[160:163], v[52:55]
	v_mfma_f32_16x16x32_bf16 v[48:51], v[148:151], v[160:163], v[48:51]
	v_mfma_f32_16x16x32_bf16 v[36:39], v[140:143], v[168:171], v[36:39]
	v_mfma_f32_16x16x32_bf16 v[32:35], v[148:151], v[168:171], v[32:35]
	v_mfma_f32_16x16x32_bf16 v[20:23], v[140:143], v[176:179], v[20:23]
	v_mfma_f32_16x16x32_bf16 v[16:19], v[148:151], v[176:179], v[16:19]
	v_mfma_f32_16x16x32_bf16 v[4:7], v[140:143], v[184:187], v[4:7]
	v_mfma_f32_16x16x32_bf16 v[0:3], v[148:151], v[184:187], v[0:3]
	v_mfma_f32_16x16x32_bf16 v[52:55], v[144:147], v[164:167], v[52:55]
	v_mfma_f32_16x16x32_bf16 v[48:51], v[152:155], v[164:167], v[48:51]
	v_mfma_f32_16x16x32_bf16 v[36:39], v[144:147], v[172:175], v[36:39]
	v_mfma_f32_16x16x32_bf16 v[32:35], v[152:155], v[172:175], v[32:35]
	v_mfma_f32_16x16x32_bf16 v[20:23], v[144:147], v[180:183], v[20:23]
	v_mfma_f32_16x16x32_bf16 v[16:19], v[152:155], v[180:183], v[16:19]
	v_mfma_f32_16x16x32_bf16 v[4:7], v[144:147], v[188:191], v[4:7]
	v_mfma_f32_16x16x32_bf16 v[0:3], v[152:155], v[188:191], v[0:3]
	s_setprio 0
	s_barrier
	s_add_i32 s12, 0, 0x18000
	s_add_i32 s13, 0, 0x1c000
	v_add_u32_e32 v124, s12, v224
	v_add_u32_e32 v152, s13, v224
	ds_read_b128 v[112:115], v124
	ds_read_b128 v[116:119], v124 offset:1024
	ds_read_b128 v[120:123], v124 offset:2048
	ds_read_b128 v[124:127], v124 offset:3072
	ds_read_b128 v[140:143], v152
	ds_read_b128 v[144:147], v152 offset:1024
	ds_read_b128 v[148:151], v152 offset:2048
	ds_read_b128 v[152:155], v152 offset:3072
	s_add_u32 s10, s86, 0x40000
	s_addc_u32 s11, s87, 0
	s_mov_b32 m0, s77
	ds_read_b128 v[160:163], v228 offset:32768
	ds_read_b128 v[164:167], v228 offset:33792
	ds_read_b128 v[168:171], v228 offset:34816
	ds_read_b128 v[172:175], v228 offset:35840
	ds_read_b128 v[176:179], v228 offset:36864
	ds_read_b128 v[180:183], v228 offset:37888
	ds_read_b128 v[184:187], v228 offset:38912
	ds_read_b128 v[188:191], v228 offset:39936
	global_load_lds_dwordx4 v196, s[10:11]
	v_lshl_add_u64 v[214:215], s[10:11], 0, v[198:199]
	s_mov_b32 m0, s96
	s_nop 0
	global_load_lds_dwordx4 v[214:215], off
	s_waitcnt vmcnt(8)
	s_waitcnt lgkmcnt(0)
	s_barrier
	s_setprio 1
	s_waitcnt lgkmcnt(0)
	v_mfma_f32_16x16x32_bf16 v[156:159], v[112:115], v[160:163], v[156:159]
	v_mfma_f32_16x16x32_bf16 v[136:139], v[120:123], v[160:163], v[136:139]
	v_mfma_f32_16x16x32_bf16 v[108:111], v[112:115], v[168:171], v[108:111]
	v_mfma_f32_16x16x32_bf16 v[104:107], v[120:123], v[168:171], v[104:107]
	v_mfma_f32_16x16x32_bf16 v[92:95], v[112:115], v[176:179], v[92:95]
	v_mfma_f32_16x16x32_bf16 v[88:91], v[120:123], v[176:179], v[88:91]
	v_mfma_f32_16x16x32_bf16 v[76:79], v[112:115], v[184:187], v[76:79]
	v_mfma_f32_16x16x32_bf16 v[72:75], v[120:123], v[184:187], v[72:75]
	v_mfma_f32_16x16x32_bf16 v[156:159], v[116:119], v[164:167], v[156:159]
	v_mfma_f32_16x16x32_bf16 v[136:139], v[124:127], v[164:167], v[136:139]
	v_mfma_f32_16x16x32_bf16 v[108:111], v[116:119], v[172:175], v[108:111]
	v_mfma_f32_16x16x32_bf16 v[104:107], v[124:127], v[172:175], v[104:107]
	v_mfma_f32_16x16x32_bf16 v[92:95], v[116:119], v[180:183], v[92:95]
	v_mfma_f32_16x16x32_bf16 v[88:91], v[124:127], v[180:183], v[88:91]
	v_mfma_f32_16x16x32_bf16 v[76:79], v[116:119], v[188:191], v[76:79]
	v_mfma_f32_16x16x32_bf16 v[72:75], v[124:127], v[188:191], v[72:75]
	s_setprio 0
	s_setprio 1
	v_mfma_f32_16x16x32_bf16 v[132:135], v[140:143], v[160:163], v[132:135]
	v_mfma_f32_16x16x32_bf16 v[128:131], v[148:151], v[160:163], v[128:131]
	v_mfma_f32_16x16x32_bf16 v[100:103], v[140:143], v[168:171], v[100:103]
	v_mfma_f32_16x16x32_bf16 v[96:99], v[148:151], v[168:171], v[96:99]
	v_mfma_f32_16x16x32_bf16 v[84:87], v[140:143], v[176:179], v[84:87]
	v_mfma_f32_16x16x32_bf16 v[80:83], v[148:151], v[176:179], v[80:83]
	v_mfma_f32_16x16x32_bf16 v[68:71], v[140:143], v[184:187], v[68:71]
	v_mfma_f32_16x16x32_bf16 v[64:67], v[148:151], v[184:187], v[64:67]
	v_mfma_f32_16x16x32_bf16 v[132:135], v[144:147], v[164:167], v[132:135]
	v_mfma_f32_16x16x32_bf16 v[128:131], v[152:155], v[164:167], v[128:131]
	v_mfma_f32_16x16x32_bf16 v[100:103], v[144:147], v[172:175], v[100:103]
	v_mfma_f32_16x16x32_bf16 v[96:99], v[152:155], v[172:175], v[96:99]
	v_mfma_f32_16x16x32_bf16 v[84:87], v[144:147], v[180:183], v[84:87]
	v_mfma_f32_16x16x32_bf16 v[80:83], v[152:155], v[180:183], v[80:83]
	v_mfma_f32_16x16x32_bf16 v[68:71], v[144:147], v[188:191], v[68:71]
	v_mfma_f32_16x16x32_bf16 v[64:67], v[152:155], v[188:191], v[64:67]
	s_setprio 0
	s_barrier
; #define PG8_STAGE(bufoff, gbase, voff) do { _Pragma("unroll") for (int _i = 0; _i < 2; ++_i) \
;         __builtin_amdgcn_global_load_lds((const unsigned*)((const char*)(gbase) + (voff)[_i]), (PG8_LAS unsigned*)(lds + (bufoff) + ldsw + _i * 8192), 16, 0, 0); } while (0)
; #define PG8_LDA(dst, b, h) do { _Pragma("unroll") for (int m = 0; m < 4; ++m) _Pragma("unroll") for (int k = 0; k < 2; ++k) dst[m][k] = *(const PG8_LAS bf16x8*)(lds + PG8_SA(b, h) + aoff + m * 2048 + k * 1024); } while (0)
; #define PG8_MMA(ai, bj, At, Bt) do { __builtin_amdgcn_s_setprio(1); _Pragma("unroll") for (int m = 0; m < 4; ++m) _Pragma("unroll") for (int n = 0; n < 2; ++n) _Pragma("unroll") for (int k = 0; k < 2; ++k) \
;         acc[ai][bj][m][n] = __builtin_amdgcn_mfma_f32_16x16x32_bf16(Bt[n][k], At[m][k], acc[ai][bj][m][n], 0, 0, 0); __builtin_amdgcn_s_setprio(0); } while (0)
; #define PG8_WAIT_V(n) asm volatile("s_waitcnt vmcnt(" #n ")" ::: "memory")
; #define PG8_WAIT_L(n) asm volatile("s_waitcnt lgkmcnt(" #n ")" ::: "memory")
; #define PG8_BAR __builtin_amdgcn_s_barrier()
; #define PG8_SCHED __builtin_amdgcn_sched_barrier(0)
; template <class Epi, class Sched, bool ALIGN_EPI = false, bool SP2 = false>
; __device__ __forceinline__ void gemm_phase(PG8_LAS unsigned char* lds, const Gemm g, const Sched& S, const Epi& E, const int tid) {
;     ...
;             PG8_LDA(At, 1, 1); PG8_STAGE(PG8_SB(1, 0), b3, voffB); PG8_STAGE(PG8_SB(1, 1), b3 + hstep, voffB); PG8_STAGE(PG8_SA(1, 0), a3, voffA);
;             PG8_WAIT_V(8); PG8_WAIT_L(0); PG8_BAR; PG8_MMA(1, 0, At, B0); PG8_MMA(1, 1, At, B1); PG8_BAR; PG8_SCHED;
	s_add_i32 s10, s12, s4
	v_lshl_add_u64 v[206:207], v[206:207], 0, s[22:23]
	s_mov_b32 m0, s10
	ds_read_b128 v[160:163], v228 offset:49152
	ds_read_b128 v[164:167], v228 offset:50176
	ds_read_b128 v[168:171], v228 offset:51200
	ds_read_b128 v[172:175], v228 offset:52224
	ds_read_b128 v[176:179], v228 offset:53248
	ds_read_b128 v[180:183], v228 offset:54272
	ds_read_b128 v[184:187], v228 offset:55296
	ds_read_b128 v[188:191], v228 offset:56320
	global_load_lds_dwordx4 v[206:207], off
	s_add_i32 m0, s10, 0x2000
	s_add_u32 s10, s52, 0x40080
	v_lshl_add_u64 v[206:207], v[208:209], 0, s[22:23]
	s_addc_u32 s11, s53, 0
	s_add_i32 s12, s13, s4
	global_load_lds_dwordx4 v[206:207], off
	s_mov_b32 m0, s12
	s_nop 0
	global_load_lds_dwordx4 v192, s[10:11]
	s_add_i32 m0, s12, 0x2000
	s_nop 0
	global_load_lds_dwordx4 v200, s[10:11]
	v_lshl_add_u64 v[206:207], v[210:211], 0, s[22:23]
	s_mov_b32 m0, s89
	s_nop 0
	global_load_lds_dwordx4 v[206:207], off
	v_lshl_add_u64 v[206:207], v[212:213], 0, s[22:23]
	s_mov_b32 m0, s95
	s_nop 0
	global_load_lds_dwordx4 v[206:207], off
	s_waitcnt vmcnt(8)
	s_waitcnt lgkmcnt(0)
	s_barrier
	s_setprio 1
	s_waitcnt lgkmcnt(0)
	v_mfma_f32_16x16x32_bf16 v[60:63], v[112:115], v[160:163], v[60:63]
	v_mfma_f32_16x16x32_bf16 v[56:59], v[120:123], v[160:163], v[56:59]
	v_mfma_f32_16x16x32_bf16 v[44:47], v[112:115], v[168:171], v[44:47]
	v_mfma_f32_16x16x32_bf16 v[40:43], v[120:123], v[168:171], v[40:43]
	v_mfma_f32_16x16x32_bf16 v[28:31], v[112:115], v[176:179], v[28:31]
	v_mfma_f32_16x16x32_bf16 v[24:27], v[120:123], v[176:179], v[24:27]
	v_mfma_f32_16x16x32_bf16 v[12:15], v[112:115], v[184:187], v[12:15]
	v_mfma_f32_16x16x32_bf16 v[8:11], v[120:123], v[184:187], v[8:11]
	v_mfma_f32_16x16x32_bf16 v[60:63], v[116:119], v[164:167], v[60:63]
	v_mfma_f32_16x16x32_bf16 v[56:59], v[124:127], v[164:167], v[56:59]
	v_mfma_f32_16x16x32_bf16 v[44:47], v[116:119], v[172:175], v[44:47]
	v_mfma_f32_16x16x32_bf16 v[40:43], v[124:127], v[172:175], v[40:43]
	v_mfma_f32_16x16x32_bf16 v[28:31], v[116:119], v[180:183], v[28:31]
	v_mfma_f32_16x16x32_bf16 v[24:27], v[124:127], v[180:183], v[24:27]
	v_mfma_f32_16x16x32_bf16 v[12:15], v[116:119], v[188:191], v[12:15]
	v_mfma_f32_16x16x32_bf16 v[8:11], v[124:127], v[188:191], v[8:11]
	s_setprio 0
	s_setprio 1
	v_mfma_f32_16x16x32_bf16 v[52:55], v[140:143], v[160:163], v[52:55]
	v_mfma_f32_16x16x32_bf16 v[48:51], v[148:151], v[160:163], v[48:51]
	v_mfma_f32_16x16x32_bf16 v[36:39], v[140:143], v[168:171], v[36:39]
	v_mfma_f32_16x16x32_bf16 v[32:35], v[148:151], v[168:171], v[32:35]
	v_mfma_f32_16x16x32_bf16 v[20:23], v[140:143], v[176:179], v[20:23]
	v_mfma_f32_16x16x32_bf16 v[16:19], v[148:151], v[176:179], v[16:19]
	v_mfma_f32_16x16x32_bf16 v[4:7], v[140:143], v[184:187], v[4:7]
	v_mfma_f32_16x16x32_bf16 v[0:3], v[148:151], v[184:187], v[0:3]
	v_mfma_f32_16x16x32_bf16 v[52:55], v[144:147], v[164:167], v[52:55]
	v_mfma_f32_16x16x32_bf16 v[48:51], v[152:155], v[164:167], v[48:51]
	v_mfma_f32_16x16x32_bf16 v[36:39], v[144:147], v[172:175], v[36:39]
	v_mfma_f32_16x16x32_bf16 v[32:35], v[152:155], v[172:175], v[32:35]
	v_mfma_f32_16x16x32_bf16 v[20:23], v[144:147], v[180:183], v[20:23]
	v_mfma_f32_16x16x32_bf16 v[16:19], v[152:155], v[180:183], v[16:19]
	v_mfma_f32_16x16x32_bf16 v[4:7], v[144:147], v[188:191], v[4:7]
	v_mfma_f32_16x16x32_bf16 v[0:3], v[152:155], v[188:191], v[0:3]
	s_setprio 0
	s_barrier
	s_add_i32 s9, s9, 2
	s_add_u32 s0, s0, 0x100
	s_addc_u32 s1, s1, 0
	s_add_u32 s82, s82, 0x100
	s_addc_u32 s8, s8, 0
	s_cmp_gt_u32 s9, 13
	s_cbranch_scc0 .LBB0_166
	s_and_b64 vcc, exec, s[60:61]
	s_cbranch_vccz .LBB0_169
	s_barrier

; #define PG8_STAGE(bufoff, gbase, voff) do { _Pragma("unroll") for (int _i = 0; _i < 2; ++_i) \
;         __builtin_amdgcn_global_load_lds((const unsigned*)((const char*)(gbase) + (voff)[_i]), (PG8_LAS unsigned*)(lds + (bufoff) + ldsw + _i * 8192), 16, 0, 0); } while (0)
; #define PG8_WAIT_V(n) asm volatile("s_waitcnt vmcnt(" #n ")" ::: "memory")
; #define PG8_BAR __builtin_amdgcn_s_barrier()
; template <class Epi, class Sched, bool ALIGN_EPI = false, bool SP2 = false>
; __device__ __forceinline__ void gemm_phase(PG8_LAS unsigned char* lds, const Gemm g, const Sched& S, const Epi& E, const int tid) {
;     ...
;         PG8_WAIT_V(2); PG8_BAR;
;         PG8_STAGE(PG8_SB(1, 0), cB + kstep, voffB); PG8_STAGE(PG8_SA(1, 0), cA + kstep, voffA); PG8_STAGE(PG8_SB(1, 1), cB + hstep + kstep, voffB);
;         PG8_WAIT_V(6); PG8_BAR;
.LBB0_226:
	v_bfe_u32 v7, v6, 4, 2
	v_and_b32_e32 v16, 15, v6
	v_lshlrev_b32_e32 v17, 3, v7
	v_lshlrev_b32_e32 v7, 4, v7
	v_lshlrev_b32_e32 v6, 2, v6
	s_and_b32 s12, s39, 3
	v_lshl_or_b32 v195, s9, 6, v16
	v_lshl_or_b32 v7, v16, 6, v7
	s_lshl_b32 s9, s9, 13
	v_and_b32_e32 v6, 32, v6
	v_lshl_add_u64 v[8:9], s[60:61], 0, v[192:193]
	v_mov_b32_e32 v189, v193
	v_bitop3_b32 v16, v7, s9, v6 bitop3:0xde
	s_lshl_b32 s9, s12, 12
	v_lshl_add_u64 v[10:11], s[60:61], 0, v[188:189]
	v_mov_b32_e32 v197, v193
	v_bitop3_b32 v218, v7, s9, v6 bitop3:0xde
	s_add_i32 m0, s7, 0x18000
	v_lshl_add_u64 v[6:7], v[8:9], 0, s[22:23]
	v_lshl_add_u64 v[12:13], s[58:59], 0, v[196:197]
	v_mov_b32_e32 v191, v193
	s_waitcnt vmcnt(2)
	s_barrier
	global_load_lds_dwordx4 v[6:7], off
	v_lshl_add_u64 v[6:7], v[10:11], 0, s[22:23]
	s_add_i32 m0, s7, 0x1a000
	s_add_i32 s77, s7, 0x8000
	s_add_i32 s82, s7, 0xa000
	v_lshl_add_u64 v[14:15], s[58:59], 0, v[190:191]
	global_load_lds_dwordx4 v[6:7], off
	v_lshl_add_u64 v[6:7], v[12:13], 0, s[22:23]
	s_mov_b32 m0, s77
	s_add_u32 s10, s60, 0x100080
	global_load_lds_dwordx4 v[6:7], off
	v_lshl_add_u64 v[6:7], v[14:15], 0, s[22:23]
	s_mov_b32 m0, s82
	s_addc_u32 s11, s61, 0
	global_load_lds_dwordx4 v[6:7], off
	s_add_i32 m0, s7, 0x1c000
	s_nop 0
	global_load_lds_dwordx4 v192, s[10:11]
	v_lshl_add_u64 v[6:7], s[10:11], 0, v[188:189]
	s_add_i32 m0, s7, 0x1e000
	s_cmpk_lt_u32 s8, 0x100
	global_load_lds_dwordx4 v[6:7], off
	v_lshlrev_b32_e32 v6, 16, v4
	v_and_b32_e32 v6, 0xfffe0000, v6
	v_lshl_add_u32 v3, v3, 13, v6
	v_and_b32_e32 v4, 1, v4
	v_lshl_or_b32 v3, v4, 6, v3
	v_lshl_add_u32 v198, v5, 1, v3
	v_lshlrev_b32_e32 v3, 16, v0
	v_and_b32_e32 v3, 0xfffe0000, v3
	s_waitcnt vmcnt(6)
	v_lshl_add_u32 v1, v1, 13, v3
	v_and_b32_e32 v0, 1, v0
	v_lshl_or_b32 v0, v0, 6, v1
	s_sext_i32_i16 s1, s38
	v_lshl_or_b32 v219, s12, 5, v17
	s_cselect_b64 s[40:41], -1, 0
	v_mov_b32_e32 v199, v193
	v_lshl_add_u32 v200, v2, 1, v0
	v_mov_b32_e32 v201, v193
	s_mov_b32 s84, 0
	v_add_u32_e32 v220, 0, v16
	s_barrier
	s_branch .LBB0_229

; #define PG8_STAGE(bufoff, gbase, voff) do { _Pragma("unroll") for (int _i = 0; _i < 2; ++_i) \
;         __builtin_amdgcn_global_load_lds((const unsigned*)((const char*)(gbase) + (voff)[_i]), (PG8_LAS unsigned*)(lds + (bufoff) + ldsw + _i * 8192), 16, 0, 0); } while (0)
; #define PG8_LDA(dst, b, h) do { _Pragma("unroll") for (int m = 0; m < 4; ++m) _Pragma("unroll") for (int k = 0; k < 2; ++k) dst[m][k] = *(const PG8_LAS bf16x8*)(lds + PG8_SA(b, h) + aoff + m * 2048 + k * 1024); } while (0)
; #define PG8_LDB(dst, b, h) do { _Pragma("unroll") for (int n = 0; n < 2; ++n) _Pragma("unroll") for (int k = 0; k < 2; ++k) dst[n][k] = *(const PG8_LAS bf16x8*)(lds + PG8_SB(b, h) + boff + n * 2048 + k * 1024); } while (0)
; #define PG8_MMA(ai, bj, At, Bt) do { __builtin_amdgcn_s_setprio(1); _Pragma("unroll") for (int m = 0; m < 4; ++m) _Pragma("unroll") for (int n = 0; n < 2; ++n) _Pragma("unroll") for (int k = 0; k < 2; ++k) \
;         acc[ai][bj][m][n] = __builtin_amdgcn_mfma_f32_16x16x32_bf16(Bt[n][k], At[m][k], acc[ai][bj][m][n], 0, 0, 0); __builtin_amdgcn_s_setprio(0); } while (0)
; #define PG8_WAIT_V(n) asm volatile("s_waitcnt vmcnt(" #n ")" ::: "memory")
; #define PG8_WAIT_L(n) asm volatile("s_waitcnt lgkmcnt(" #n ")" ::: "memory")
; template <class Epi, class Sched, bool ALIGN_EPI = false, bool SP2 = false>
; __device__ __forceinline__ void gemm_phase(PG8_LAS unsigned char* lds, const Gemm g, const Sched& S, const Epi& E, const int tid) {
;     ...
;             const bool last = (t == nt - 2);
;             const char* a1 = cA + (size_t)(t + 1) * kstep;
;             const char* a2 = last ? nA : cA + (size_t)(t + 2) * kstep; const char* b2 = last ? nB : cB + (size_t)(t + 2) * kstep;
;             const char* a3 = a2 + kstep; const char* b3 = b2 + kstep;
;             if (last && has_next) S.a_ready(nxt);
;             if constexpr (SP2) {
;             PG8_LDB(B0, 0, 0); PG8_LDB(B1, 0, 1); PG8_SCHED; PG8_LDA(At, 0, 0); PG8_STAGE(PG8_SA(1, 1), a1 + hstep, voffA);
;             PG8_WAIT_V(8); PG8_WAIT_L(0); PG8_BAR; PG8_MMA(0, 0, At, B0); PG8_MMA(0, 1, At, B1); PG8_BAR; PG8_SCHED;
;             PG8_LDA(At, 0, 1); PG8_STAGE(PG8_SB(0, 0), b2, voffB); PG8_STAGE(PG8_SB(0, 1), b2 + hstep, voffB); PG8_STAGE(PG8_SA(0, 0), a2, voffA);
;             PG8_WAIT_V(8); PG8_WAIT_L(0); PG8_BAR; PG8_MMA(1, 0, At, B0); PG8_MMA(1, 1, At, B1); PG8_BAR; PG8_SCHED;
.LBB0_236:
	s_add_u32 s10, s58, 0xfff00080
	s_addc_u32 s11, s59, -1
	s_add_i32 s12, 0, 0x10000
	s_cmp_eq_u32 s9, 60
	s_cselect_b32 s65, s53, s11
	s_cselect_b32 s64, s85, s10
	s_cselect_b32 s61, s43, s8
	s_cselect_b32 s60, s86, s87
	s_add_i32 s13, 0, 0x14000
	v_add_u32_e32 v140, s12, v218
	v_add_u32_e32 v156, s13, v218
	ds_read_b128 v[128:131], v140
	ds_read_b128 v[132:135], v140 offset:1024
	ds_read_b128 v[136:139], v140 offset:2048
	ds_read_b128 v[140:143], v140 offset:3072
	ds_read_b128 v[144:147], v156
	ds_read_b128 v[148:151], v156 offset:1024
	ds_read_b128 v[152:155], v156 offset:2048
	ds_read_b128 v[156:159], v156 offset:3072
	s_add_i32 m0, s7, 0xc000
	ds_read_b128 v[160:163], v220
	ds_read_b128 v[164:167], v220 offset:1024
	ds_read_b128 v[168:171], v220 offset:2048
	ds_read_b128 v[172:175], v220 offset:3072
	ds_read_b128 v[176:179], v220 offset:4096
	ds_read_b128 v[180:183], v220 offset:5120
	ds_read_b128 v[184:187], v220 offset:6144
	ds_read_b128 v[202:205], v220 offset:7168
	global_load_lds_dwordx4 v198, s[58:59]
	s_add_i32 m0, s7, 0xe000
	s_nop 0
	global_load_lds_dwordx4 v200, s[58:59]
	s_waitcnt vmcnt(8)
	s_waitcnt lgkmcnt(0)
	s_barrier
	s_setprio 1
	s_waitcnt lgkmcnt(0)
	v_mfma_f32_16x16x32_bf16 v[124:127], v[128:131], v[160:163], v[124:127]
	v_mfma_f32_16x16x32_bf16 v[120:123], v[136:139], v[160:163], v[120:123]
	v_mfma_f32_16x16x32_bf16 v[108:111], v[128:131], v[168:171], v[108:111]
	v_mfma_f32_16x16x32_bf16 v[104:107], v[136:139], v[168:171], v[104:107]
	v_mfma_f32_16x16x32_bf16 v[96:99], v[128:131], v[176:179], v[96:99]
	v_mfma_f32_16x16x32_bf16 v[88:91], v[136:139], v[176:179], v[88:91]
	v_mfma_f32_16x16x32_bf16 v[80:83], v[128:131], v[184:187], v[80:83]
	v_mfma_f32_16x16x32_bf16 v[72:75], v[136:139], v[184:187], v[72:75]
	v_mfma_f32_16x16x32_bf16 v[124:127], v[132:135], v[164:167], v[124:127]
	v_mfma_f32_16x16x32_bf16 v[120:123], v[140:143], v[164:167], v[120:123]
	v_mfma_f32_16x16x32_bf16 v[108:111], v[132:135], v[172:175], v[108:111]
	v_mfma_f32_16x16x32_bf16 v[104:107], v[140:143], v[172:175], v[104:107]
	v_mfma_f32_16x16x32_bf16 v[96:99], v[132:135], v[180:183], v[96:99]
	v_mfma_f32_16x16x32_bf16 v[88:91], v[140:143], v[180:183], v[88:91]
	v_mfma_f32_16x16x32_bf16 v[80:83], v[132:135], v[202:205], v[80:83]
	v_mfma_f32_16x16x32_bf16 v[72:75], v[140:143], v[202:205], v[72:75]
	s_setprio 0
	s_setprio 1
	v_mfma_f32_16x16x32_bf16 v[116:119], v[144:147], v[160:163], v[116:119]
	v_mfma_f32_16x16x32_bf16 v[112:115], v[152:155], v[160:163], v[112:115]
	v_mfma_f32_16x16x32_bf16 v[100:103], v[144:147], v[168:171], v[100:103]
	v_mfma_f32_16x16x32_bf16 v[92:95], v[152:155], v[168:171], v[92:95]
	v_mfma_f32_16x16x32_bf16 v[84:87], v[144:147], v[176:179], v[84:87]
	v_mfma_f32_16x16x32_bf16 v[76:79], v[152:155], v[176:179], v[76:79]
	v_mfma_f32_16x16x32_bf16 v[68:71], v[144:147], v[184:187], v[68:71]
	v_mfma_f32_16x16x32_bf16 v[64:67], v[152:155], v[184:187], v[64:67]
	v_mfma_f32_16x16x32_bf16 v[116:119], v[148:151], v[164:167], v[116:119]
	v_mfma_f32_16x16x32_bf16 v[112:115], v[156:159], v[164:167], v[112:115]
	v_mfma_f32_16x16x32_bf16 v[100:103], v[148:151], v[172:175], v[100:103]
	v_mfma_f32_16x16x32_bf16 v[92:95], v[156:159], v[172:175], v[92:95]
	v_mfma_f32_16x16x32_bf16 v[84:87], v[148:151], v[180:183], v[84:87]
	v_mfma_f32_16x16x32_bf16 v[76:79], v[156:159], v[180:183], v[76:79]
	v_mfma_f32_16x16x32_bf16 v[68:71], v[148:151], v[202:205], v[68:71]
	v_mfma_f32_16x16x32_bf16 v[64:67], v[156:159], v[202:205], v[64:67]
	s_setprio 0
	s_barrier
	s_add_i32 s10, s12, s4
	v_lshl_add_u64 v[206:207], s[60:61], 0, v[192:193]
	s_mov_b32 m0, s10
	ds_read_b128 v[160:163], v220 offset:16384
	ds_read_b128 v[164:167], v220 offset:17408
	ds_read_b128 v[168:171], v220 offset:18432
	ds_read_b128 v[172:175], v220 offset:19456
	ds_read_b128 v[176:179], v220 offset:20480
	ds_read_b128 v[180:183], v220 offset:21504
	ds_read_b128 v[184:187], v220 offset:22528
	ds_read_b128 v[202:205], v220 offset:23552
	global_load_lds_dwordx4 v[206:207], off
	s_add_i32 m0, s10, 0x2000
	s_add_u32 s10, s60, 0x100000
	v_lshl_add_u64 v[208:209], s[60:61], 0, v[188:189]
	s_addc_u32 s11, s61, 0
	s_add_i32 s12, s13, s4
	global_load_lds_dwordx4 v[208:209], off
	s_mov_b32 m0, s12
	v_lshl_add_u64 v[212:213], s[64:65], 0, v[190:191]
	global_load_lds_dwordx4 v192, s[10:11]
	s_add_i32 m0, s12, 0x2000
	s_nop 0
	global_load_lds_dwordx4 v188, s[10:11]
	v_lshl_add_u64 v[210:211], s[64:65], 0, v[196:197]
	s_mov_b32 m0, s7
	s_nop 0
	global_load_lds_dwordx4 v[210:211], off
	s_mov_b32 m0, s66
	s_nop 0
	global_load_lds_dwordx4 v[212:213], off
	s_waitcnt vmcnt(8)
	s_waitcnt lgkmcnt(0)
	s_barrier
; #define PG8_STAGE(bufoff, gbase, voff) do { _Pragma("unroll") for (int _i = 0; _i < 2; ++_i) \
;         __builtin_amdgcn_global_load_lds((const unsigned*)((const char*)(gbase) + (voff)[_i]), (PG8_LAS unsigned*)(lds + (bufoff) + ldsw + _i * 8192), 16, 0, 0); } while (0)
; #define PG8_LDA(dst, b, h) do { _Pragma("unroll") for (int m = 0; m < 4; ++m) _Pragma("unroll") for (int k = 0; k < 2; ++k) dst[m][k] = *(const PG8_LAS bf16x8*)(lds + PG8_SA(b, h) + aoff + m * 2048 + k * 1024); } while (0)
; #define PG8_LDB(dst, b, h) do { _Pragma("unroll") for (int n = 0; n < 2; ++n) _Pragma("unroll") for (int k = 0; k < 2; ++k) dst[n][k] = *(const PG8_LAS bf16x8*)(lds + PG8_SB(b, h) + boff + n * 2048 + k * 1024); } while (0)
; #define PG8_MMA(ai, bj, At, Bt) do { __builtin_amdgcn_s_setprio(1); _Pragma("unroll") for (int m = 0; m < 4; ++m) _Pragma("unroll") for (int n = 0; n < 2; ++n) _Pragma("unroll") for (int k = 0; k < 2; ++k) \
;         acc[ai][bj][m][n] = __builtin_amdgcn_mfma_f32_16x16x32_bf16(Bt[n][k], At[m][k], acc[ai][bj][m][n], 0, 0, 0); __builtin_amdgcn_s_setprio(0); } while (0)
; #define PG8_WAIT_V(n) asm volatile("s_waitcnt vmcnt(" #n ")" ::: "memory")
; #define PG8_WAIT_L(n) asm volatile("s_waitcnt lgkmcnt(" #n ")" ::: "memory")
; #define PG8_BAR __builtin_amdgcn_s_barrier()
; #define PG8_SCHED __builtin_amdgcn_sched_barrier(0)
; template <class Epi, class Sched, bool ALIGN_EPI = false, bool SP2 = false>
; __device__ __forceinline__ void gemm_phase(PG8_LAS unsigned char* lds, const Gemm g, const Sched& S, const Epi& E, const int tid) {
;     ...
;             PG8_WAIT_V(8); PG8_WAIT_L(0); PG8_BAR; PG8_MMA(1, 0, At, B0); PG8_MMA(1, 1, At, B1); PG8_BAR; PG8_SCHED;
;             PG8_LDB(B0, 1, 0); PG8_LDB(B1, 1, 1); PG8_SCHED; PG8_LDA(At, 1, 0); PG8_STAGE(PG8_SA(0, 1), a2 + hstep, voffA);
;             PG8_WAIT_V(8); PG8_WAIT_L(0); PG8_BAR; PG8_MMA(0, 0, At, B0); PG8_MMA(0, 1, At, B1); PG8_BAR; PG8_SCHED;
	s_setprio 1
	s_waitcnt lgkmcnt(0)
	v_mfma_f32_16x16x32_bf16 v[60:63], v[128:131], v[160:163], v[60:63]
	v_mfma_f32_16x16x32_bf16 v[56:59], v[136:139], v[160:163], v[56:59]
	v_mfma_f32_16x16x32_bf16 v[48:51], v[128:131], v[168:171], v[48:51]
	v_mfma_f32_16x16x32_bf16 v[40:43], v[136:139], v[168:171], v[40:43]
	v_mfma_f32_16x16x32_bf16 v[32:35], v[128:131], v[176:179], v[32:35]
	v_mfma_f32_16x16x32_bf16 v[24:27], v[136:139], v[176:179], v[24:27]
	v_mfma_f32_16x16x32_bf16 v[16:19], v[128:131], v[184:187], v[16:19]
	v_mfma_f32_16x16x32_bf16 v[8:11], v[136:139], v[184:187], v[8:11]
	v_mfma_f32_16x16x32_bf16 v[60:63], v[132:135], v[164:167], v[60:63]
	v_mfma_f32_16x16x32_bf16 v[56:59], v[140:143], v[164:167], v[56:59]
	v_mfma_f32_16x16x32_bf16 v[48:51], v[132:135], v[172:175], v[48:51]
	v_mfma_f32_16x16x32_bf16 v[40:43], v[140:143], v[172:175], v[40:43]
	v_mfma_f32_16x16x32_bf16 v[32:35], v[132:135], v[180:183], v[32:35]
	v_mfma_f32_16x16x32_bf16 v[24:27], v[140:143], v[180:183], v[24:27]
	v_mfma_f32_16x16x32_bf16 v[16:19], v[132:135], v[202:205], v[16:19]
	v_mfma_f32_16x16x32_bf16 v[8:11], v[140:143], v[202:205], v[8:11]
	s_setprio 0
	s_setprio 1
	v_mfma_f32_16x16x32_bf16 v[52:55], v[144:147], v[160:163], v[52:55]
	v_mfma_f32_16x16x32_bf16 v[44:47], v[152:155], v[160:163], v[44:47]
	v_mfma_f32_16x16x32_bf16 v[36:39], v[144:147], v[168:171], v[36:39]
	v_mfma_f32_16x16x32_bf16 v[28:31], v[152:155], v[168:171], v[28:31]
	v_mfma_f32_16x16x32_bf16 v[20:23], v[144:147], v[176:179], v[20:23]
	v_mfma_f32_16x16x32_bf16 v[12:15], v[152:155], v[176:179], v[12:15]
	v_mfma_f32_16x16x32_bf16 v[4:7], v[144:147], v[184:187], v[4:7]
	v_mfma_f32_16x16x32_bf16 v[0:3], v[152:155], v[184:187], v[0:3]
	v_mfma_f32_16x16x32_bf16 v[52:55], v[148:151], v[164:167], v[52:55]
	v_mfma_f32_16x16x32_bf16 v[44:47], v[156:159], v[164:167], v[44:47]
	v_mfma_f32_16x16x32_bf16 v[36:39], v[148:151], v[172:175], v[36:39]
	v_mfma_f32_16x16x32_bf16 v[28:31], v[156:159], v[172:175], v[28:31]
	v_mfma_f32_16x16x32_bf16 v[20:23], v[148:151], v[180:183], v[20:23]
	v_mfma_f32_16x16x32_bf16 v[12:15], v[156:159], v[180:183], v[12:15]
	v_mfma_f32_16x16x32_bf16 v[4:7], v[148:151], v[202:205], v[4:7]
	v_mfma_f32_16x16x32_bf16 v[0:3], v[156:159], v[202:205], v[0:3]
	s_setprio 0
	s_barrier
	s_add_i32 s12, 0, 0x18000
	s_add_i32 s13, 0, 0x1c000
	v_add_u32_e32 v140, s12, v218
	v_add_u32_e32 v156, s13, v218
	ds_read_b128 v[128:131], v140
	ds_read_b128 v[132:135], v140 offset:1024
	ds_read_b128 v[136:139], v140 offset:2048
	ds_read_b128 v[140:143], v140 offset:3072
	ds_read_b128 v[144:147], v156
	ds_read_b128 v[148:151], v156 offset:1024
	ds_read_b128 v[152:155], v156 offset:2048
	ds_read_b128 v[156:159], v156 offset:3072
	s_add_u32 s10, s64, 0x100000
	s_addc_u32 s11, s65, 0
	s_mov_b32 m0, s67
	ds_read_b128 v[160:163], v220 offset:32768
	ds_read_b128 v[164:167], v220 offset:33792
	ds_read_b128 v[168:171], v220 offset:34816
	ds_read_b128 v[172:175], v220 offset:35840
	ds_read_b128 v[176:179], v220 offset:36864
	ds_read_b128 v[180:183], v220 offset:37888
	ds_read_b128 v[184:187], v220 offset:38912
	ds_read_b128 v[202:205], v220 offset:39936
	global_load_lds_dwordx4 v196, s[10:11]
	v_lshl_add_u64 v[214:215], s[10:11], 0, v[190:191]
	s_mov_b32 m0, s76
	s_nop 0
	global_load_lds_dwordx4 v[214:215], off
	s_waitcnt vmcnt(8)
	s_waitcnt lgkmcnt(0)
	s_barrier
	s_setprio 1
	s_waitcnt lgkmcnt(0)
	v_mfma_f32_16x16x32_bf16 v[124:127], v[128:131], v[160:163], v[124:127]
	v_mfma_f32_16x16x32_bf16 v[120:123], v[136:139], v[160:163], v[120:123]
	v_mfma_f32_16x16x32_bf16 v[108:111], v[128:131], v[168:171], v[108:111]
	v_mfma_f32_16x16x32_bf16 v[104:107], v[136:139], v[168:171], v[104:107]
	v_mfma_f32_16x16x32_bf16 v[96:99], v[128:131], v[176:179], v[96:99]
	v_mfma_f32_16x16x32_bf16 v[88:91], v[136:139], v[176:179], v[88:91]
	v_mfma_f32_16x16x32_bf16 v[80:83], v[128:131], v[184:187], v[80:83]
	v_mfma_f32_16x16x32_bf16 v[72:75], v[136:139], v[184:187], v[72:75]
	v_mfma_f32_16x16x32_bf16 v[124:127], v[132:135], v[164:167], v[124:127]
	v_mfma_f32_16x16x32_bf16 v[120:123], v[140:143], v[164:167], v[120:123]
	v_mfma_f32_16x16x32_bf16 v[108:111], v[132:135], v[172:175], v[108:111]
	v_mfma_f32_16x16x32_bf16 v[104:107], v[140:143], v[172:175], v[104:107]
	v_mfma_f32_16x16x32_bf16 v[96:99], v[132:135], v[180:183], v[96:99]
	v_mfma_f32_16x16x32_bf16 v[88:91], v[140:143], v[180:183], v[88:91]
	v_mfma_f32_16x16x32_bf16 v[80:83], v[132:135], v[202:205], v[80:83]
	v_mfma_f32_16x16x32_bf16 v[72:75], v[140:143], v[202:205], v[72:75]
	s_setprio 0
	s_setprio 1
	v_mfma_f32_16x16x32_bf16 v[116:119], v[144:147], v[160:163], v[116:119]
	v_mfma_f32_16x16x32_bf16 v[112:115], v[152:155], v[160:163], v[112:115]
	v_mfma_f32_16x16x32_bf16 v[100:103], v[144:147], v[168:171], v[100:103]
	v_mfma_f32_16x16x32_bf16 v[92:95], v[152:155], v[168:171], v[92:95]
	v_mfma_f32_16x16x32_bf16 v[84:87], v[144:147], v[176:179], v[84:87]
	v_mfma_f32_16x16x32_bf16 v[76:79], v[152:155], v[176:179], v[76:79]
	v_mfma_f32_16x16x32_bf16 v[68:71], v[144:147], v[184:187], v[68:71]
	v_mfma_f32_16x16x32_bf16 v[64:67], v[152:155], v[184:187], v[64:67]
	v_mfma_f32_16x16x32_bf16 v[116:119], v[148:151], v[164:167], v[116:119]
	v_mfma_f32_16x16x32_bf16 v[112:115], v[156:159], v[164:167], v[112:115]
	v_mfma_f32_16x16x32_bf16 v[100:103], v[148:151], v[172:175], v[100:103]
	v_mfma_f32_16x16x32_bf16 v[92:95], v[156:159], v[172:175], v[92:95]
	v_mfma_f32_16x16x32_bf16 v[84:87], v[148:151], v[180:183], v[84:87]
	v_mfma_f32_16x16x32_bf16 v[76:79], v[156:159], v[180:183], v[76:79]
	v_mfma_f32_16x16x32_bf16 v[68:71], v[148:151], v[202:205], v[68:71]
	v_mfma_f32_16x16x32_bf16 v[64:67], v[156:159], v[202:205], v[64:67]
	s_setprio 0
	s_barrier
; #define PG8_STAGE(bufoff, gbase, voff) do { _Pragma("unroll") for (int _i = 0; _i < 2; ++_i) \
;         __builtin_amdgcn_global_load_lds((const unsigned*)((const char*)(gbase) + (voff)[_i]), (PG8_LAS unsigned*)(lds + (bufoff) + ldsw + _i * 8192), 16, 0, 0); } while (0)
; #define PG8_LDA(dst, b, h) do { _Pragma("unroll") for (int m = 0; m < 4; ++m) _Pragma("unroll") for (int k = 0; k < 2; ++k) dst[m][k] = *(const PG8_LAS bf16x8*)(lds + PG8_SA(b, h) + aoff + m * 2048 + k * 1024); } while (0)
; #define PG8_MMA(ai, bj, At, Bt) do { __builtin_amdgcn_s_setprio(1); _Pragma("unroll") for (int m = 0; m < 4; ++m) _Pragma("unroll") for (int n = 0; n < 2; ++n) _Pragma("unroll") for (int k = 0; k < 2; ++k) \
;         acc[ai][bj][m][n] = __builtin_amdgcn_mfma_f32_16x16x32_bf16(Bt[n][k], At[m][k], acc[ai][bj][m][n], 0, 0, 0); __builtin_amdgcn_s_setprio(0); } while (0)
; #define PG8_WAIT_V(n) asm volatile("s_waitcnt vmcnt(" #n ")" ::: "memory")
; #define PG8_WAIT_L(n) asm volatile("s_waitcnt lgkmcnt(" #n ")" ::: "memory")
; #define PG8_BAR __builtin_amdgcn_s_barrier()
; #define PG8_SCHED __builtin_amdgcn_sched_barrier(0)
; template <class Epi, class Sched, bool ALIGN_EPI = false, bool SP2 = false>
; __device__ __forceinline__ void gemm_phase(PG8_LAS unsigned char* lds, const Gemm g, const Sched& S, const Epi& E, const int tid) {
;     ...
;             PG8_LDA(At, 1, 1); PG8_STAGE(PG8_SB(1, 0), b3, voffB); PG8_STAGE(PG8_SB(1, 1), b3 + hstep, voffB); PG8_STAGE(PG8_SA(1, 0), a3, voffA);
;             PG8_WAIT_V(8); PG8_WAIT_L(0); PG8_BAR; PG8_MMA(1, 0, At, B0); PG8_MMA(1, 1, At, B1); PG8_BAR; PG8_SCHED;
	s_add_i32 s10, s12, s4
	v_lshl_add_u64 v[206:207], v[206:207], 0, s[22:23]
	s_mov_b32 m0, s10
	ds_read_b128 v[160:163], v220 offset:49152
	ds_read_b128 v[164:167], v220 offset:50176
	ds_read_b128 v[168:171], v220 offset:51200
	ds_read_b128 v[172:175], v220 offset:52224
	ds_read_b128 v[176:179], v220 offset:53248
	ds_read_b128 v[180:183], v220 offset:54272
	ds_read_b128 v[184:187], v220 offset:55296
	ds_read_b128 v[202:205], v220 offset:56320
	global_load_lds_dwordx4 v[206:207], off
	s_add_i32 m0, s10, 0x2000
	s_add_u32 s10, s60, 0x100080
	v_lshl_add_u64 v[206:207], v[208:209], 0, s[22:23]
	s_addc_u32 s11, s61, 0
	s_add_i32 s12, s13, s4
	global_load_lds_dwordx4 v[206:207], off
	s_mov_b32 m0, s12
	s_nop 0
	global_load_lds_dwordx4 v192, s[10:11]
	s_add_i32 m0, s12, 0x2000
	s_nop 0
	global_load_lds_dwordx4 v188, s[10:11]
	v_lshl_add_u64 v[206:207], v[210:211], 0, s[22:23]
	s_mov_b32 m0, s77
	s_nop 0
	global_load_lds_dwordx4 v[206:207], off
	v_lshl_add_u64 v[206:207], v[212:213], 0, s[22:23]
	s_mov_b32 m0, s82
	s_nop 0
	global_load_lds_dwordx4 v[206:207], off
	s_waitcnt vmcnt(8)
	s_waitcnt lgkmcnt(0)
	s_barrier
	s_setprio 1
	s_waitcnt lgkmcnt(0)
	v_mfma_f32_16x16x32_bf16 v[60:63], v[128:131], v[160:163], v[60:63]
	v_mfma_f32_16x16x32_bf16 v[56:59], v[136:139], v[160:163], v[56:59]
	v_mfma_f32_16x16x32_bf16 v[48:51], v[128:131], v[168:171], v[48:51]
	v_mfma_f32_16x16x32_bf16 v[40:43], v[136:139], v[168:171], v[40:43]
	v_mfma_f32_16x16x32_bf16 v[32:35], v[128:131], v[176:179], v[32:35]
	v_mfma_f32_16x16x32_bf16 v[24:27], v[136:139], v[176:179], v[24:27]
	v_mfma_f32_16x16x32_bf16 v[16:19], v[128:131], v[184:187], v[16:19]
	v_mfma_f32_16x16x32_bf16 v[8:11], v[136:139], v[184:187], v[8:11]
	v_mfma_f32_16x16x32_bf16 v[60:63], v[132:135], v[164:167], v[60:63]
	v_mfma_f32_16x16x32_bf16 v[56:59], v[140:143], v[164:167], v[56:59]
	v_mfma_f32_16x16x32_bf16 v[48:51], v[132:135], v[172:175], v[48:51]
	v_mfma_f32_16x16x32_bf16 v[40:43], v[140:143], v[172:175], v[40:43]
	v_mfma_f32_16x16x32_bf16 v[32:35], v[132:135], v[180:183], v[32:35]
	v_mfma_f32_16x16x32_bf16 v[24:27], v[140:143], v[180:183], v[24:27]
	v_mfma_f32_16x16x32_bf16 v[16:19], v[132:135], v[202:205], v[16:19]
	v_mfma_f32_16x16x32_bf16 v[8:11], v[140:143], v[202:205], v[8:11]
	s_setprio 0
	s_setprio 1
	v_mfma_f32_16x16x32_bf16 v[52:55], v[144:147], v[160:163], v[52:55]
	v_mfma_f32_16x16x32_bf16 v[44:47], v[152:155], v[160:163], v[44:47]
	v_mfma_f32_16x16x32_bf16 v[36:39], v[144:147], v[168:171], v[36:39]
	v_mfma_f32_16x16x32_bf16 v[28:31], v[152:155], v[168:171], v[28:31]
	v_mfma_f32_16x16x32_bf16 v[20:23], v[144:147], v[176:179], v[20:23]
	v_mfma_f32_16x16x32_bf16 v[12:15], v[152:155], v[176:179], v[12:15]
	v_mfma_f32_16x16x32_bf16 v[4:7], v[144:147], v[184:187], v[4:7]
	v_mfma_f32_16x16x32_bf16 v[0:3], v[152:155], v[184:187], v[0:3]
	v_mfma_f32_16x16x32_bf16 v[52:55], v[148:151], v[164:167], v[52:55]
	v_mfma_f32_16x16x32_bf16 v[44:47], v[156:159], v[164:167], v[44:47]
	v_mfma_f32_16x16x32_bf16 v[36:39], v[148:151], v[172:175], v[36:39]
	v_mfma_f32_16x16x32_bf16 v[28:31], v[156:159], v[172:175], v[28:31]
	v_mfma_f32_16x16x32_bf16 v[20:23], v[148:151], v[180:183], v[20:23]
	v_mfma_f32_16x16x32_bf16 v[12:15], v[156:159], v[180:183], v[12:15]
	v_mfma_f32_16x16x32_bf16 v[4:7], v[148:151], v[202:205], v[4:7]
	v_mfma_f32_16x16x32_bf16 v[0:3], v[156:159], v[202:205], v[0:3]
	s_setprio 0
	s_barrier
	s_add_i32 s9, s9, 2
	s_add_u32 s58, s58, 0x100
	s_addc_u32 s59, s59, 0
	s_add_u32 s87, s87, 0x100
	s_addc_u32 s8, s8, 0
	s_cmp_gt_u32 s9, 61
	s_cbranch_scc0 .LBB0_236
	s_and_b64 vcc, exec, s[40:41]
	s_cbranch_vccz .LBB0_239
	s_barrier

; #define PG8_STAGE(bufoff, gbase, voff) do { _Pragma("unroll") for (int _i = 0; _i < 2; ++_i) \
;         __builtin_amdgcn_global_load_lds((const unsigned*)((const char*)(gbase) + (voff)[_i]), (PG8_LAS unsigned*)(lds + (bufoff) + ldsw + _i * 8192), 16, 0, 0); } while (0)
; #define PG8_WAIT_V(n) asm volatile("s_waitcnt vmcnt(" #n ")" ::: "memory")
; #define PG8_BAR __builtin_amdgcn_s_barrier()
; template <class Epi, class Sched, bool ALIGN_EPI = false, bool SP2 = false>
; __device__ __forceinline__ void gemm_phase(PG8_LAS unsigned char* lds, const Gemm g, const Sched& S, const Epi& E, const int tid) {
;     ...
;         PG8_WAIT_V(2); PG8_BAR;
;         PG8_STAGE(PG8_SB(1, 0), cB + kstep, voffB); PG8_STAGE(PG8_SA(1, 0), cA + kstep, voffA); PG8_STAGE(PG8_SB(1, 1), cB + hstep + kstep, voffB);
;         PG8_WAIT_V(6); PG8_BAR;
.LBB0_260:
	v_and_b32_e32 v15, 15, v8
	v_lshrrev_b32_e32 v8, 1, v8
	v_and_b32_e32 v8, 24, v8
	v_lshlrev_b32_e32 v16, 1, v8
	s_waitcnt vmcnt(0)
	v_lshl_or_b32 v143, s9, 6, v15
	v_lshl_or_b32 v16, v15, 6, v16
	v_lshlrev_b32_e32 v15, 2, v15
	s_lshl_b32 s1, s9, 13
	v_and_b32_e32 v17, 32, v15
	v_bitop3_b32 v18, v16, s1, v17 bitop3:0xde
	s_lshl_b32 s1, s30, 5
	s_and_b32 s1, s1, 0x60
	s_add_i32 m0, s77, 0x18000
	v_lshl_add_u64 v[6:7], v[6:7], 0, s[22:23]
	s_lshl_b32 s10, s1, 7
	s_waitcnt vmcnt(2)
	s_barrier
	global_load_lds_dwordx4 v[6:7], off
	v_lshl_add_u64 v[4:5], v[4:5], 0, s[22:23]
	s_add_i32 m0, s77, 0x1a000
	s_add_i32 s89, s77, 0x8000
	s_add_i32 s92, s77, 0xa000
	v_bitop3_b32 v144, s10, v16, v17 bitop3:0xf6
	global_load_lds_dwordx4 v[4:5], off
	v_lshl_add_u64 v[0:1], v[0:1], 0, s[22:23]
	s_mov_b32 m0, s89
	s_add_u32 s10, s66, 0x40080
	global_load_lds_dwordx4 v[0:1], off
	v_lshl_add_u64 v[0:1], v[2:3], 0, s[22:23]
	s_mov_b32 m0, s92
	s_addc_u32 s11, s67, 0
	global_load_lds_dwordx4 v[0:1], off
	s_add_i32 m0, s77, 0x1c000
	s_nop 0
	global_load_lds_dwordx4 v192, s[10:11]
	v_lshl_add_u64 v[0:1], s[10:11], 0, v[132:133]
	s_add_i32 m0, s77, 0x1e000
	s_cmpk_lt_u32 s8, 0x100
	global_load_lds_dwordx4 v[0:1], off
	v_lshlrev_b32_e32 v0, 14, v9
	v_and_b32_e32 v0, 0xffff8000, v0
	v_lshl_add_u32 v0, v10, 11, v0
	v_and_b32_e32 v1, 1, v9
	v_lshl_or_b32 v0, v1, 6, v0
	v_lshl_add_u32 v134, v11, 1, v0
	v_lshlrev_b32_e32 v0, 14, v12
	s_cselect_b64 s[54:55], -1, 0
	s_lshl_b32 s8, s9, 8
	v_and_b32_e32 v0, 0xffff8000, v0
	s_waitcnt vmcnt(6)
	s_add_i32 s8, s8, 0
	v_lshl_add_u32 v0, v13, 11, v0
	v_and_b32_e32 v1, 1, v12
	s_add_i32 s8, s8, 0x20000
	v_lshl_or_b32 v0, v1, 6, v0
	v_add_u32_e32 v145, s8, v15
	v_or_b32_e32 v146, s1, v8
	v_mov_b32_e32 v135, v193
	v_lshl_add_u32 v136, v14, 1, v0
	v_mov_b32_e32 v137, v193
	s_mov_b32 s41, 0
	v_add_u32_e32 v147, 0, v18
	s_barrier
	s_branch .LBB0_263

; #define PG8_STAGE(bufoff, gbase, voff) do { _Pragma("unroll") for (int _i = 0; _i < 2; ++_i) \
;         __builtin_amdgcn_global_load_lds((const unsigned*)((const char*)(gbase) + (voff)[_i]), (PG8_LAS unsigned*)(lds + (bufoff) + ldsw + _i * 8192), 16, 0, 0); } while (0)
; #define PG8_LDA(dst, b, h) do { _Pragma("unroll") for (int m = 0; m < 4; ++m) _Pragma("unroll") for (int k = 0; k < 2; ++k) dst[m][k] = *(const PG8_LAS bf16x8*)(lds + PG8_SA(b, h) + aoff + m * 2048 + k * 1024); } while (0)
; #define PG8_LDB(dst, b, h) do { _Pragma("unroll") for (int n = 0; n < 2; ++n) _Pragma("unroll") for (int k = 0; k < 2; ++k) dst[n][k] = *(const PG8_LAS bf16x8*)(lds + PG8_SB(b, h) + boff + n * 2048 + k * 1024); } while (0)
; #define PG8_MMA(ai, bj, At, Bt) do { __builtin_amdgcn_s_setprio(1); _Pragma("unroll") for (int m = 0; m < 4; ++m) _Pragma("unroll") for (int n = 0; n < 2; ++n) _Pragma("unroll") for (int k = 0; k < 2; ++k) \
;         acc[ai][bj][m][n] = __builtin_amdgcn_mfma_f32_16x16x32_bf16(Bt[n][k], At[m][k], acc[ai][bj][m][n], 0, 0, 0); __builtin_amdgcn_s_setprio(0); } while (0)
; #define PG8_WAIT_V(n) asm volatile("s_waitcnt vmcnt(" #n ")" ::: "memory")
; #define PG8_WAIT_L(n) asm volatile("s_waitcnt lgkmcnt(" #n ")" ::: "memory")
; template <class Epi, class Sched, bool ALIGN_EPI = false, bool SP2 = false>
; __device__ __forceinline__ void gemm_phase(PG8_LAS unsigned char* lds, const Gemm g, const Sched& S, const Epi& E, const int tid) {
;     ...
;             const bool last = (t == nt - 2);
;             const char* a1 = cA + (size_t)(t + 1) * kstep;
;             const char* a2 = last ? nA : cA + (size_t)(t + 2) * kstep; const char* b2 = last ? nB : cB + (size_t)(t + 2) * kstep;
;             const char* a3 = a2 + kstep; const char* b3 = b2 + kstep;
;             if (last && has_next) S.a_ready(nxt);
;             if constexpr (SP2) {
;             PG8_LDB(B0, 0, 0); PG8_LDB(B1, 0, 1); PG8_SCHED; PG8_LDA(At, 0, 0); PG8_STAGE(PG8_SA(1, 1), a1 + hstep, voffA);
;             PG8_WAIT_V(8); PG8_WAIT_L(0); PG8_BAR; PG8_MMA(0, 0, At, B0); PG8_MMA(0, 1, At, B1); PG8_BAR; PG8_SCHED;
;             PG8_LDA(At, 0, 1); PG8_STAGE(PG8_SB(0, 0), b2, voffB); PG8_STAGE(PG8_SB(0, 1), b2 + hstep, voffB); PG8_STAGE(PG8_SA(0, 0), a2, voffA);
;             PG8_WAIT_V(8); PG8_WAIT_L(0); PG8_BAR; PG8_MMA(1, 0, At, B0); PG8_MMA(1, 1, At, B1); PG8_BAR; PG8_SCHED;
.LBB0_270:
	s_add_u32 s10, s64, 0xfffc0080
	s_addc_u32 s11, s65, -1
	s_add_i32 s12, 0, 0x10000
	s_cmp_eq_u32 s9, 12
	s_cselect_b32 s85, s1, s11
	s_cselect_b32 s84, s57, s10
	v_add_u32_e32 v142, s12, v144
	s_cselect_b32 s67, s31, s8
	s_cselect_b32 s66, s95, s96
	s_add_i32 s13, 0, 0x14000
	ds_read_b128 v[138:141], v142
	ds_read_b128 v[148:151], v142 offset:1024
	ds_read_b128 v[152:155], v142 offset:2048
	ds_read_b128 v[156:159], v142 offset:3072
	v_add_u32_e32 v142, s13, v144
	ds_read_b128 v[160:163], v142
	ds_read_b128 v[164:167], v142 offset:1024
	ds_read_b128 v[168:171], v142 offset:2048
	ds_read_b128 v[172:175], v142 offset:3072
	s_add_i32 m0, s77, 0xc000
	ds_read_b128 v[176:179], v147
	ds_read_b128 v[180:183], v147 offset:1024
	ds_read_b128 v[184:187], v147 offset:2048
	ds_read_b128 v[188:191], v147 offset:3072
	ds_read_b128 v[196:199], v147 offset:4096
	ds_read_b128 v[200:203], v147 offset:5120
	ds_read_b128 v[204:207], v147 offset:6144
	ds_read_b128 v[208:211], v147 offset:7168
	global_load_lds_dwordx4 v134, s[64:65]
	s_add_i32 m0, s77, 0xe000
	s_nop 0
	global_load_lds_dwordx4 v136, s[64:65]
	s_waitcnt vmcnt(8)
	s_waitcnt lgkmcnt(0)
	s_barrier
	s_setprio 1
	s_waitcnt lgkmcnt(0)
	v_mfma_f32_16x16x32_bf16 v[124:127], v[138:141], v[176:179], v[124:127]
	v_mfma_f32_16x16x32_bf16 v[120:123], v[152:155], v[176:179], v[120:123]
	v_mfma_f32_16x16x32_bf16 v[108:111], v[138:141], v[184:187], v[108:111]
	v_mfma_f32_16x16x32_bf16 v[104:107], v[152:155], v[184:187], v[104:107]
	v_mfma_f32_16x16x32_bf16 v[92:95], v[138:141], v[196:199], v[92:95]
	v_mfma_f32_16x16x32_bf16 v[88:91], v[152:155], v[196:199], v[88:91]
	v_mfma_f32_16x16x32_bf16 v[76:79], v[138:141], v[204:207], v[76:79]
	v_mfma_f32_16x16x32_bf16 v[72:75], v[152:155], v[204:207], v[72:75]
	v_mfma_f32_16x16x32_bf16 v[124:127], v[148:151], v[180:183], v[124:127]
	v_mfma_f32_16x16x32_bf16 v[120:123], v[156:159], v[180:183], v[120:123]
	v_mfma_f32_16x16x32_bf16 v[108:111], v[148:151], v[188:191], v[108:111]
	v_mfma_f32_16x16x32_bf16 v[104:107], v[156:159], v[188:191], v[104:107]
	v_mfma_f32_16x16x32_bf16 v[92:95], v[148:151], v[200:203], v[92:95]
	v_mfma_f32_16x16x32_bf16 v[88:91], v[156:159], v[200:203], v[88:91]
	v_mfma_f32_16x16x32_bf16 v[76:79], v[148:151], v[208:211], v[76:79]
	v_mfma_f32_16x16x32_bf16 v[72:75], v[156:159], v[208:211], v[72:75]
	s_setprio 0
	s_setprio 1
	v_mfma_f32_16x16x32_bf16 v[116:119], v[160:163], v[176:179], v[116:119]
	v_mfma_f32_16x16x32_bf16 v[112:115], v[168:171], v[176:179], v[112:115]
	v_mfma_f32_16x16x32_bf16 v[100:103], v[160:163], v[184:187], v[100:103]
	v_mfma_f32_16x16x32_bf16 v[96:99], v[168:171], v[184:187], v[96:99]
	v_mfma_f32_16x16x32_bf16 v[84:87], v[160:163], v[196:199], v[84:87]
	v_mfma_f32_16x16x32_bf16 v[80:83], v[168:171], v[196:199], v[80:83]
	v_mfma_f32_16x16x32_bf16 v[68:71], v[160:163], v[204:207], v[68:71]
	v_mfma_f32_16x16x32_bf16 v[64:67], v[168:171], v[204:207], v[64:67]
	v_mfma_f32_16x16x32_bf16 v[116:119], v[164:167], v[180:183], v[116:119]
	v_mfma_f32_16x16x32_bf16 v[112:115], v[172:175], v[180:183], v[112:115]
	v_mfma_f32_16x16x32_bf16 v[100:103], v[164:167], v[188:191], v[100:103]
	v_mfma_f32_16x16x32_bf16 v[96:99], v[172:175], v[188:191], v[96:99]
	v_mfma_f32_16x16x32_bf16 v[84:87], v[164:167], v[200:203], v[84:87]
	v_mfma_f32_16x16x32_bf16 v[80:83], v[172:175], v[200:203], v[80:83]
	v_mfma_f32_16x16x32_bf16 v[68:71], v[164:167], v[208:211], v[68:71]
	v_mfma_f32_16x16x32_bf16 v[64:67], v[172:175], v[208:211], v[64:67]
	s_setprio 0
	s_barrier
	s_add_i32 s10, s12, s6
	v_lshl_add_u64 v[212:213], s[66:67], 0, v[192:193]
	s_mov_b32 m0, s10
	ds_read_b128 v[176:179], v147 offset:16384
	ds_read_b128 v[180:183], v147 offset:17408
	ds_read_b128 v[184:187], v147 offset:18432
	ds_read_b128 v[188:191], v147 offset:19456
	ds_read_b128 v[196:199], v147 offset:20480
	ds_read_b128 v[200:203], v147 offset:21504
	ds_read_b128 v[204:207], v147 offset:22528
	ds_read_b128 v[208:211], v147 offset:23552
	global_load_lds_dwordx4 v[212:213], off
	s_add_i32 m0, s10, 0x2000
	s_add_u32 s10, s66, 0x40000
	v_lshl_add_u64 v[214:215], s[66:67], 0, v[132:133]
	s_addc_u32 s11, s67, 0
	s_add_i32 s12, s13, s6
	global_load_lds_dwordx4 v[214:215], off
	s_mov_b32 m0, s12
	v_lshl_add_u64 v[218:219], s[84:85], 0, v[130:131]
	global_load_lds_dwordx4 v192, s[10:11]
	s_add_i32 m0, s12, 0x2000
	s_nop 0
	global_load_lds_dwordx4 v132, s[10:11]
	v_lshl_add_u64 v[216:217], s[84:85], 0, v[128:129]
	s_mov_b32 m0, s77
	s_nop 0
	global_load_lds_dwordx4 v[216:217], off
	s_mov_b32 m0, s86
	s_nop 0
	global_load_lds_dwordx4 v[218:219], off
	s_waitcnt vmcnt(8)
	s_waitcnt lgkmcnt(0)
	s_barrier
; #define PG8_STAGE(bufoff, gbase, voff) do { _Pragma("unroll") for (int _i = 0; _i < 2; ++_i) \
;         __builtin_amdgcn_global_load_lds((const unsigned*)((const char*)(gbase) + (voff)[_i]), (PG8_LAS unsigned*)(lds + (bufoff) + ldsw + _i * 8192), 16, 0, 0); } while (0)
; #define PG8_LDA(dst, b, h) do { _Pragma("unroll") for (int m = 0; m < 4; ++m) _Pragma("unroll") for (int k = 0; k < 2; ++k) dst[m][k] = *(const PG8_LAS bf16x8*)(lds + PG8_SA(b, h) + aoff + m * 2048 + k * 1024); } while (0)
; #define PG8_LDB(dst, b, h) do { _Pragma("unroll") for (int n = 0; n < 2; ++n) _Pragma("unroll") for (int k = 0; k < 2; ++k) dst[n][k] = *(const PG8_LAS bf16x8*)(lds + PG8_SB(b, h) + boff + n * 2048 + k * 1024); } while (0)
; #define PG8_MMA(ai, bj, At, Bt) do { __builtin_amdgcn_s_setprio(1); _Pragma("unroll") for (int m = 0; m < 4; ++m) _Pragma("unroll") for (int n = 0; n < 2; ++n) _Pragma("unroll") for (int k = 0; k < 2; ++k) \
;         acc[ai][bj][m][n] = __builtin_amdgcn_mfma_f32_16x16x32_bf16(Bt[n][k], At[m][k], acc[ai][bj][m][n], 0, 0, 0); __builtin_amdgcn_s_setprio(0); } while (0)
; #define PG8_WAIT_V(n) asm volatile("s_waitcnt vmcnt(" #n ")" ::: "memory")
; #define PG8_WAIT_L(n) asm volatile("s_waitcnt lgkmcnt(" #n ")" ::: "memory")
; #define PG8_BAR __builtin_amdgcn_s_barrier()
; #define PG8_SCHED __builtin_amdgcn_sched_barrier(0)
; template <class Epi, class Sched, bool ALIGN_EPI = false, bool SP2 = false>
; __device__ __forceinline__ void gemm_phase(PG8_LAS unsigned char* lds, const Gemm g, const Sched& S, const Epi& E, const int tid) {
;     ...
;             PG8_WAIT_V(8); PG8_WAIT_L(0); PG8_BAR; PG8_MMA(1, 0, At, B0); PG8_MMA(1, 1, At, B1); PG8_BAR; PG8_SCHED;
;             PG8_LDB(B0, 1, 0); PG8_LDB(B1, 1, 1); PG8_SCHED; PG8_LDA(At, 1, 0); PG8_STAGE(PG8_SA(0, 1), a2 + hstep, voffA);
;             PG8_WAIT_V(8); PG8_WAIT_L(0); PG8_BAR; PG8_MMA(0, 0, At, B0); PG8_MMA(0, 1, At, B1); PG8_BAR; PG8_SCHED;
	s_setprio 1
	s_waitcnt lgkmcnt(0)
	v_mfma_f32_16x16x32_bf16 v[60:63], v[138:141], v[176:179], v[60:63]
	v_mfma_f32_16x16x32_bf16 v[56:59], v[152:155], v[176:179], v[56:59]
	v_mfma_f32_16x16x32_bf16 v[44:47], v[138:141], v[184:187], v[44:47]
	v_mfma_f32_16x16x32_bf16 v[40:43], v[152:155], v[184:187], v[40:43]
	v_mfma_f32_16x16x32_bf16 v[28:31], v[138:141], v[196:199], v[28:31]
	v_mfma_f32_16x16x32_bf16 v[24:27], v[152:155], v[196:199], v[24:27]
	v_mfma_f32_16x16x32_bf16 v[12:15], v[138:141], v[204:207], v[12:15]
	v_mfma_f32_16x16x32_bf16 v[8:11], v[152:155], v[204:207], v[8:11]
	v_mfma_f32_16x16x32_bf16 v[60:63], v[148:151], v[180:183], v[60:63]
	v_mfma_f32_16x16x32_bf16 v[56:59], v[156:159], v[180:183], v[56:59]
	v_mfma_f32_16x16x32_bf16 v[44:47], v[148:151], v[188:191], v[44:47]
	v_mfma_f32_16x16x32_bf16 v[40:43], v[156:159], v[188:191], v[40:43]
	v_mfma_f32_16x16x32_bf16 v[28:31], v[148:151], v[200:203], v[28:31]
	v_mfma_f32_16x16x32_bf16 v[24:27], v[156:159], v[200:203], v[24:27]
	v_mfma_f32_16x16x32_bf16 v[12:15], v[148:151], v[208:211], v[12:15]
	v_mfma_f32_16x16x32_bf16 v[8:11], v[156:159], v[208:211], v[8:11]
	s_setprio 0
	s_setprio 1
	v_mfma_f32_16x16x32_bf16 v[52:55], v[160:163], v[176:179], v[52:55]
	v_mfma_f32_16x16x32_bf16 v[48:51], v[168:171], v[176:179], v[48:51]
	v_mfma_f32_16x16x32_bf16 v[36:39], v[160:163], v[184:187], v[36:39]
	v_mfma_f32_16x16x32_bf16 v[32:35], v[168:171], v[184:187], v[32:35]
	v_mfma_f32_16x16x32_bf16 v[20:23], v[160:163], v[196:199], v[20:23]
	v_mfma_f32_16x16x32_bf16 v[16:19], v[168:171], v[196:199], v[16:19]
	v_mfma_f32_16x16x32_bf16 v[4:7], v[160:163], v[204:207], v[4:7]
	v_mfma_f32_16x16x32_bf16 v[0:3], v[168:171], v[204:207], v[0:3]
	v_mfma_f32_16x16x32_bf16 v[52:55], v[164:167], v[180:183], v[52:55]
	v_mfma_f32_16x16x32_bf16 v[48:51], v[172:175], v[180:183], v[48:51]
	v_mfma_f32_16x16x32_bf16 v[36:39], v[164:167], v[188:191], v[36:39]
	v_mfma_f32_16x16x32_bf16 v[32:35], v[172:175], v[188:191], v[32:35]
	v_mfma_f32_16x16x32_bf16 v[20:23], v[164:167], v[200:203], v[20:23]
	v_mfma_f32_16x16x32_bf16 v[16:19], v[172:175], v[200:203], v[16:19]
	v_mfma_f32_16x16x32_bf16 v[4:7], v[164:167], v[208:211], v[4:7]
	v_mfma_f32_16x16x32_bf16 v[0:3], v[172:175], v[208:211], v[0:3]
	s_setprio 0
	s_barrier
	s_add_i32 s12, 0, 0x18000
	v_add_u32_e32 v142, s12, v144
	s_add_i32 s13, 0, 0x1c000
	ds_read_b128 v[138:141], v142
	ds_read_b128 v[148:151], v142 offset:1024
	ds_read_b128 v[152:155], v142 offset:2048
	ds_read_b128 v[156:159], v142 offset:3072
	v_add_u32_e32 v142, s13, v144
	ds_read_b128 v[160:163], v142
	ds_read_b128 v[164:167], v142 offset:1024
	ds_read_b128 v[168:171], v142 offset:2048
	ds_read_b128 v[172:175], v142 offset:3072
	s_add_u32 s10, s84, 0x40000
	s_addc_u32 s11, s85, 0
	s_mov_b32 m0, s87
	ds_read_b128 v[176:179], v147 offset:32768
	ds_read_b128 v[180:183], v147 offset:33792
	ds_read_b128 v[184:187], v147 offset:34816
	ds_read_b128 v[188:191], v147 offset:35840
	ds_read_b128 v[196:199], v147 offset:36864
	ds_read_b128 v[200:203], v147 offset:37888
	ds_read_b128 v[204:207], v147 offset:38912
	ds_read_b128 v[208:211], v147 offset:39936
	global_load_lds_dwordx4 v128, s[10:11]
	v_lshl_add_u64 v[220:221], s[10:11], 0, v[130:131]
	s_mov_b32 m0, s88
	s_nop 0
	global_load_lds_dwordx4 v[220:221], off
	s_waitcnt vmcnt(8)
	s_waitcnt lgkmcnt(0)
	s_barrier
	s_setprio 1
	s_waitcnt lgkmcnt(0)
	v_mfma_f32_16x16x32_bf16 v[124:127], v[138:141], v[176:179], v[124:127]
	v_mfma_f32_16x16x32_bf16 v[120:123], v[152:155], v[176:179], v[120:123]
	v_mfma_f32_16x16x32_bf16 v[108:111], v[138:141], v[184:187], v[108:111]
	v_mfma_f32_16x16x32_bf16 v[104:107], v[152:155], v[184:187], v[104:107]
	v_mfma_f32_16x16x32_bf16 v[92:95], v[138:141], v[196:199], v[92:95]
	v_mfma_f32_16x16x32_bf16 v[88:91], v[152:155], v[196:199], v[88:91]
	v_mfma_f32_16x16x32_bf16 v[76:79], v[138:141], v[204:207], v[76:79]
	v_mfma_f32_16x16x32_bf16 v[72:75], v[152:155], v[204:207], v[72:75]
	v_mfma_f32_16x16x32_bf16 v[124:127], v[148:151], v[180:183], v[124:127]
	v_mfma_f32_16x16x32_bf16 v[120:123], v[156:159], v[180:183], v[120:123]
	v_mfma_f32_16x16x32_bf16 v[108:111], v[148:151], v[188:191], v[108:111]
	v_mfma_f32_16x16x32_bf16 v[104:107], v[156:159], v[188:191], v[104:107]
	v_mfma_f32_16x16x32_bf16 v[92:95], v[148:151], v[200:203], v[92:95]
	v_mfma_f32_16x16x32_bf16 v[88:91], v[156:159], v[200:203], v[88:91]
	v_mfma_f32_16x16x32_bf16 v[76:79], v[148:151], v[208:211], v[76:79]
	v_mfma_f32_16x16x32_bf16 v[72:75], v[156:159], v[208:211], v[72:75]
	s_setprio 0
	s_setprio 1
	v_mfma_f32_16x16x32_bf16 v[116:119], v[160:163], v[176:179], v[116:119]
	v_mfma_f32_16x16x32_bf16 v[112:115], v[168:171], v[176:179], v[112:115]
	v_mfma_f32_16x16x32_bf16 v[100:103], v[160:163], v[184:187], v[100:103]
	v_mfma_f32_16x16x32_bf16 v[96:99], v[168:171], v[184:187], v[96:99]
	v_mfma_f32_16x16x32_bf16 v[84:87], v[160:163], v[196:199], v[84:87]
	v_mfma_f32_16x16x32_bf16 v[80:83], v[168:171], v[196:199], v[80:83]
	v_mfma_f32_16x16x32_bf16 v[68:71], v[160:163], v[204:207], v[68:71]
	v_mfma_f32_16x16x32_bf16 v[64:67], v[168:171], v[204:207], v[64:67]
	v_mfma_f32_16x16x32_bf16 v[116:119], v[164:167], v[180:183], v[116:119]
	v_mfma_f32_16x16x32_bf16 v[112:115], v[172:175], v[180:183], v[112:115]
	v_mfma_f32_16x16x32_bf16 v[100:103], v[164:167], v[188:191], v[100:103]
	v_mfma_f32_16x16x32_bf16 v[96:99], v[172:175], v[188:191], v[96:99]
	v_mfma_f32_16x16x32_bf16 v[84:87], v[164:167], v[200:203], v[84:87]
	v_mfma_f32_16x16x32_bf16 v[80:83], v[172:175], v[200:203], v[80:83]
	v_mfma_f32_16x16x32_bf16 v[68:71], v[164:167], v[208:211], v[68:71]
	v_mfma_f32_16x16x32_bf16 v[64:67], v[172:175], v[208:211], v[64:67]
	s_setprio 0
	s_barrier
; #define PG8_STAGE(bufoff, gbase, voff) do { _Pragma("unroll") for (int _i = 0; _i < 2; ++_i) \
;         __builtin_amdgcn_global_load_lds((const unsigned*)((const char*)(gbase) + (voff)[_i]), (PG8_LAS unsigned*)(lds + (bufoff) + ldsw + _i * 8192), 16, 0, 0); } while (0)
; #define PG8_LDA(dst, b, h) do { _Pragma("unroll") for (int m = 0; m < 4; ++m) _Pragma("unroll") for (int k = 0; k < 2; ++k) dst[m][k] = *(const PG8_LAS bf16x8*)(lds + PG8_SA(b, h) + aoff + m * 2048 + k * 1024); } while (0)
; #define PG8_MMA(ai, bj, At, Bt) do { __builtin_amdgcn_s_setprio(1); _Pragma("unroll") for (int m = 0; m < 4; ++m) _Pragma("unroll") for (int n = 0; n < 2; ++n) _Pragma("unroll") for (int k = 0; k < 2; ++k) \
;         acc[ai][bj][m][n] = __builtin_amdgcn_mfma_f32_16x16x32_bf16(Bt[n][k], At[m][k], acc[ai][bj][m][n], 0, 0, 0); __builtin_amdgcn_s_setprio(0); } while (0)
; #define PG8_WAIT_V(n) asm volatile("s_waitcnt vmcnt(" #n ")" ::: "memory")
; #define PG8_WAIT_L(n) asm volatile("s_waitcnt lgkmcnt(" #n ")" ::: "memory")
; #define PG8_BAR __builtin_amdgcn_s_barrier()
; #define PG8_SCHED __builtin_amdgcn_sched_barrier(0)
; template <class Epi, class Sched, bool ALIGN_EPI = false, bool SP2 = false>
; __device__ __forceinline__ void gemm_phase(PG8_LAS unsigned char* lds, const Gemm g, const Sched& S, const Epi& E, const int tid) {
;     ...
;             PG8_LDA(At, 1, 1); PG8_STAGE(PG8_SB(1, 0), b3, voffB); PG8_STAGE(PG8_SB(1, 1), b3 + hstep, voffB); PG8_STAGE(PG8_SA(1, 0), a3, voffA);
;             PG8_WAIT_V(8); PG8_WAIT_L(0); PG8_BAR; PG8_MMA(1, 0, At, B0); PG8_MMA(1, 1, At, B1); PG8_BAR; PG8_SCHED;
	s_add_i32 s10, s12, s6
	v_lshl_add_u64 v[212:213], v[212:213], 0, s[22:23]
	s_mov_b32 m0, s10
	ds_read_b128 v[176:179], v147 offset:49152
	ds_read_b128 v[180:183], v147 offset:50176
	ds_read_b128 v[184:187], v147 offset:51200
	ds_read_b128 v[188:191], v147 offset:52224
	ds_read_b128 v[196:199], v147 offset:53248
	ds_read_b128 v[200:203], v147 offset:54272
	ds_read_b128 v[204:207], v147 offset:55296
	ds_read_b128 v[208:211], v147 offset:56320
	global_load_lds_dwordx4 v[212:213], off
	s_add_i32 m0, s10, 0x2000
	s_add_u32 s10, s66, 0x40080
	v_lshl_add_u64 v[212:213], v[214:215], 0, s[22:23]
	s_addc_u32 s11, s67, 0
	s_add_i32 s12, s13, s6
	global_load_lds_dwordx4 v[212:213], off
	s_mov_b32 m0, s12
	s_nop 0
	global_load_lds_dwordx4 v192, s[10:11]
	s_add_i32 m0, s12, 0x2000
	s_nop 0
	global_load_lds_dwordx4 v132, s[10:11]
	v_lshl_add_u64 v[212:213], v[216:217], 0, s[22:23]
	s_mov_b32 m0, s89
	s_nop 0
	global_load_lds_dwordx4 v[212:213], off
	v_lshl_add_u64 v[212:213], v[218:219], 0, s[22:23]
	s_mov_b32 m0, s92
	s_nop 0
	global_load_lds_dwordx4 v[212:213], off
	s_waitcnt vmcnt(8)
	s_waitcnt lgkmcnt(0)
	s_barrier
	s_setprio 1
	s_waitcnt lgkmcnt(0)
	v_mfma_f32_16x16x32_bf16 v[60:63], v[138:141], v[176:179], v[60:63]
	v_mfma_f32_16x16x32_bf16 v[56:59], v[152:155], v[176:179], v[56:59]
	v_mfma_f32_16x16x32_bf16 v[44:47], v[138:141], v[184:187], v[44:47]
	v_mfma_f32_16x16x32_bf16 v[40:43], v[152:155], v[184:187], v[40:43]
	v_mfma_f32_16x16x32_bf16 v[28:31], v[138:141], v[196:199], v[28:31]
	v_mfma_f32_16x16x32_bf16 v[24:27], v[152:155], v[196:199], v[24:27]
	v_mfma_f32_16x16x32_bf16 v[12:15], v[138:141], v[204:207], v[12:15]
	v_mfma_f32_16x16x32_bf16 v[8:11], v[152:155], v[204:207], v[8:11]
	v_mfma_f32_16x16x32_bf16 v[60:63], v[148:151], v[180:183], v[60:63]
	v_mfma_f32_16x16x32_bf16 v[56:59], v[156:159], v[180:183], v[56:59]
	v_mfma_f32_16x16x32_bf16 v[44:47], v[148:151], v[188:191], v[44:47]
	v_mfma_f32_16x16x32_bf16 v[40:43], v[156:159], v[188:191], v[40:43]
	v_mfma_f32_16x16x32_bf16 v[28:31], v[148:151], v[200:203], v[28:31]
	v_mfma_f32_16x16x32_bf16 v[24:27], v[156:159], v[200:203], v[24:27]
	v_mfma_f32_16x16x32_bf16 v[12:15], v[148:151], v[208:211], v[12:15]
	v_mfma_f32_16x16x32_bf16 v[8:11], v[156:159], v[208:211], v[8:11]
	s_setprio 0
	s_setprio 1
	v_mfma_f32_16x16x32_bf16 v[52:55], v[160:163], v[176:179], v[52:55]
	v_mfma_f32_16x16x32_bf16 v[48:51], v[168:171], v[176:179], v[48:51]
	v_mfma_f32_16x16x32_bf16 v[36:39], v[160:163], v[184:187], v[36:39]
	v_mfma_f32_16x16x32_bf16 v[32:35], v[168:171], v[184:187], v[32:35]
	v_mfma_f32_16x16x32_bf16 v[20:23], v[160:163], v[196:199], v[20:23]
	v_mfma_f32_16x16x32_bf16 v[16:19], v[168:171], v[196:199], v[16:19]
	v_mfma_f32_16x16x32_bf16 v[4:7], v[160:163], v[204:207], v[4:7]
	v_mfma_f32_16x16x32_bf16 v[0:3], v[168:171], v[204:207], v[0:3]
	v_mfma_f32_16x16x32_bf16 v[52:55], v[164:167], v[180:183], v[52:55]
	v_mfma_f32_16x16x32_bf16 v[48:51], v[172:175], v[180:183], v[48:51]
	v_mfma_f32_16x16x32_bf16 v[36:39], v[164:167], v[188:191], v[36:39]
	v_mfma_f32_16x16x32_bf16 v[32:35], v[172:175], v[188:191], v[32:35]
	v_mfma_f32_16x16x32_bf16 v[20:23], v[164:167], v[200:203], v[20:23]
	v_mfma_f32_16x16x32_bf16 v[16:19], v[172:175], v[200:203], v[16:19]
	v_mfma_f32_16x16x32_bf16 v[4:7], v[164:167], v[208:211], v[4:7]
	v_mfma_f32_16x16x32_bf16 v[0:3], v[172:175], v[208:211], v[0:3]
	s_setprio 0
	s_barrier
	s_add_i32 s9, s9, 2
	s_add_u32 s64, s64, 0x100
	s_addc_u32 s65, s65, 0
	s_add_u32 s96, s96, 0x100
	s_addc_u32 s8, s8, 0
	s_cmp_gt_u32 s9, 13
	s_cbranch_scc0 .LBB0_270
	s_and_b64 vcc, exec, s[54:55]
	s_cbranch_vccz .LBB0_273
	s_barrier

; #define PG8_STAGE(bufoff, gbase, voff) do { _Pragma("unroll") for (int _i = 0; _i < 2; ++_i) \
;         __builtin_amdgcn_global_load_lds((const unsigned*)((const char*)(gbase) + (voff)[_i]), (PG8_LAS unsigned*)(lds + (bufoff) + ldsw + _i * 8192), 16, 0, 0); } while (0)
; #define PG8_WAIT_V(n) asm volatile("s_waitcnt vmcnt(" #n ")" ::: "memory")
; #define PG8_BAR __builtin_amdgcn_s_barrier()
; template <class Epi, class Sched, bool ALIGN_EPI = false, bool SP2 = false>
; __device__ __forceinline__ void gemm_phase(PG8_LAS unsigned char* lds, const Gemm g, const Sched& S, const Epi& E, const int tid) {
;     ...
;         PG8_WAIT_V(2); PG8_BAR;
;         PG8_STAGE(PG8_SB(1, 0), cB + kstep, voffB); PG8_STAGE(PG8_SA(1, 0), cA + kstep, voffA); PG8_STAGE(PG8_SB(1, 1), cB + hstep + kstep, voffB);
;         PG8_WAIT_V(6); PG8_BAR;
.LBB0_316:
	v_bfe_u32 v15, v14, 4, 2
	v_and_b32_e32 v16, 15, v14
	v_lshlrev_b32_e32 v18, 4, v15
	v_lshlrev_b32_e32 v14, 2, v14
	s_and_b32 s96, s1, 3
	v_lshl_or_b32 v195, s8, 6, v16
	v_lshl_or_b32 v16, v16, 6, v18
	s_lshl_b32 s1, s8, 13
	v_and_b32_e32 v14, 32, v14
	v_bitop3_b32 v18, v16, s1, v14 bitop3:0xde
	s_lshl_b32 s1, s96, 12
	v_readlane_b32 s8, v255, 24
	v_bitop3_b32 v248, v16, s1, v14 bitop3:0xde
	s_add_i32 s1, s94, 6
	v_readlane_b32 s9, v255, 25
	s_and_b64 s[8:9], s[8:9], exec
	s_load_dwordx8 s[8:15], s[44:45], 0x0
	v_lshl_add_u64 v[6:7], v[6:7], 0, s[22:23]
	s_waitcnt vmcnt(2)
	s_barrier
	v_lshl_add_u64 v[4:5], v[4:5], 0, s[22:23]
	s_waitcnt lgkmcnt(0)
	s_cselect_b32 s8, s8, s10
	s_cselect_b32 s9, s9, s11
	s_cmp_lt_u32 s1, 15
	s_cselect_b32 s55, s9, 0
	s_cselect_b32 s54, s8, 0
	s_cmp_lg_u64 s[54:55], 0
	s_cselect_b64 s[56:57], -1, 0
	s_add_i32 m0, s7, 0x18000
	s_add_i32 s92, s7, 0x8000
	global_load_lds_dwordx4 v[6:7], off
	s_add_i32 m0, s7, 0x1a000
	s_add_i32 s93, s7, 0xa000
	global_load_lds_dwordx4 v[4:5], off
	v_lshl_add_u64 v[0:1], v[0:1], 0, s[22:23]
	s_mov_b32 m0, s92
	s_add_u32 s8, s84, 0x40080
	global_load_lds_dwordx4 v[0:1], off
	v_lshl_add_u64 v[0:1], v[2:3], 0, s[22:23]
	s_mov_b32 m0, s93
	s_addc_u32 s9, s85, 0
	global_load_lds_dwordx4 v[0:1], off
	s_add_i32 m0, s7, 0x1c000
	s_nop 0
	global_load_lds_dwordx4 v192, s[8:9]
	v_lshl_add_u64 v[0:1], s[8:9], 0, v[200:201]
	s_add_i32 m0, s7, 0x1e000
	v_lshlrev_b32_e32 v17, 3, v15
	global_load_lds_dwordx4 v[0:1], off
	v_and_b32_e32 v1, 64, v245
	v_xor_b32_e32 v0, 16, v245
	v_add_u32_e32 v1, 64, v1
	v_cmp_lt_i32_e32 vcc, v0, v1
	s_waitcnt vmcnt(6)
	s_cmpk_lt_u32 s0, 0x100
	s_mov_b32 s97, 0
	v_cndmask_b32_e32 v0, v245, v0, vcc
	v_lshlrev_b32_e32 v250, 2, v0
	v_xor_b32_e32 v0, 32, v245
	v_cmp_lt_i32_e32 vcc, v0, v1
	v_and_b32_e32 v1, 1, v8
	v_lshl_or_b32 v249, s96, 5, v17
	v_cndmask_b32_e32 v0, v245, v0, vcc
	v_lshlrev_b32_e32 v251, 2, v0
	v_lshlrev_b32_e32 v0, 14, v8
	v_and_b32_e32 v0, 0xffff8000, v0
	v_lshl_add_u32 v0, v9, 11, v0
	v_lshl_or_b32 v0, v1, 6, v0
	v_lshl_add_u32 v202, v10, 1, v0
	v_lshlrev_b32_e32 v0, 14, v11
	v_and_b32_e32 v0, 0xffff8000, v0
	v_lshl_add_u32 v0, v12, 11, v0
	v_and_b32_e32 v1, 1, v11
	v_lshl_or_b32 v0, v1, 6, v0
	s_cselect_b64 s[58:59], -1, 0
	v_cmp_eq_u32_e64 s[38:39], 0, v15
	v_mov_b32_e32 v203, v193
	v_lshl_add_u32 v204, v13, 1, v0
	v_mov_b32_e32 v205, v193
	v_add_u32_e32 v252, 0, v18
	s_mov_b32 s14, s20
	s_mov_b32 s15, s21
	s_barrier
	s_branch .LBB0_319

; #define PG8_STAGE(bufoff, gbase, voff) do { _Pragma("unroll") for (int _i = 0; _i < 2; ++_i) \
;         __builtin_amdgcn_global_load_lds((const unsigned*)((const char*)(gbase) + (voff)[_i]), (PG8_LAS unsigned*)(lds + (bufoff) + ldsw + _i * 8192), 16, 0, 0); } while (0)
; #define PG8_LDA(dst, b, h) do { _Pragma("unroll") for (int m = 0; m < 4; ++m) _Pragma("unroll") for (int k = 0; k < 2; ++k) dst[m][k] = *(const PG8_LAS bf16x8*)(lds + PG8_SA(b, h) + aoff + m * 2048 + k * 1024); } while (0)
; #define PG8_LDB(dst, b, h) do { _Pragma("unroll") for (int n = 0; n < 2; ++n) _Pragma("unroll") for (int k = 0; k < 2; ++k) dst[n][k] = *(const PG8_LAS bf16x8*)(lds + PG8_SB(b, h) + boff + n * 2048 + k * 1024); } while (0)
; #define PG8_MMA(ai, bj, At, Bt) do { __builtin_amdgcn_s_setprio(1); _Pragma("unroll") for (int m = 0; m < 4; ++m) _Pragma("unroll") for (int n = 0; n < 2; ++n) _Pragma("unroll") for (int k = 0; k < 2; ++k) \
;         acc[ai][bj][m][n] = __builtin_amdgcn_mfma_f32_16x16x32_bf16(Bt[n][k], At[m][k], acc[ai][bj][m][n], 0, 0, 0); __builtin_amdgcn_s_setprio(0); } while (0)
; #define PG8_WAIT_V(n) asm volatile("s_waitcnt vmcnt(" #n ")" ::: "memory")
; #define PG8_WAIT_L(n) asm volatile("s_waitcnt lgkmcnt(" #n ")" ::: "memory")
; template <class Epi, class Sched, bool ALIGN_EPI = false, bool SP2 = false>
; __device__ __forceinline__ void gemm_phase(PG8_LAS unsigned char* lds, const Gemm g, const Sched& S, const Epi& E, const int tid) {
;     ...
;             const bool last = (t == nt - 2);
;             const char* a1 = cA + (size_t)(t + 1) * kstep;
;             const char* a2 = last ? nA : cA + (size_t)(t + 2) * kstep; const char* b2 = last ? nB : cB + (size_t)(t + 2) * kstep;
;             const char* a3 = a2 + kstep; const char* b3 = b2 + kstep;
;             if (last && has_next) S.a_ready(nxt);
;             if constexpr (SP2) {
;             PG8_LDB(B0, 0, 0); PG8_LDB(B1, 0, 1); PG8_SCHED; PG8_LDA(At, 0, 0); PG8_STAGE(PG8_SA(1, 1), a1 + hstep, voffA);
;             PG8_WAIT_V(8); PG8_WAIT_L(0); PG8_BAR; PG8_MMA(0, 0, At, B0); PG8_MMA(0, 1, At, B1); PG8_BAR; PG8_SCHED;
;             PG8_LDA(At, 0, 1); PG8_STAGE(PG8_SB(0, 0), b2, voffB); PG8_STAGE(PG8_SB(0, 1), b2 + hstep, voffB); PG8_STAGE(PG8_SA(0, 0), a2, voffA);
;             PG8_WAIT_V(8); PG8_WAIT_L(0); PG8_BAR; PG8_MMA(1, 0, At, B0); PG8_MMA(1, 1, At, B1); PG8_BAR; PG8_SCHED;
.LBB0_326:
	s_add_u32 s10, vcc_lo, 0xfffc0080
	s_addc_u32 s11, vcc_hi, -1
	s_add_i32 s12, 0, 0x10000
	s_cmp_eq_u32 s9, 12
	s_cselect_b32 s85, s1, s11
	s_cselect_b32 s84, s31, s10
	s_cselect_b32 s67, s61, s8
	s_cselect_b32 s66, s65, s82
	s_add_i32 s13, 0, 0x14000
	v_add_u32_e32 v140, s12, v248
	v_add_u32_e32 v156, s13, v248
	ds_read_b128 v[128:131], v140
	ds_read_b128 v[132:135], v140 offset:1024
	ds_read_b128 v[136:139], v140 offset:2048
	ds_read_b128 v[140:143], v140 offset:3072
	ds_read_b128 v[144:147], v156
	ds_read_b128 v[148:151], v156 offset:1024
	ds_read_b128 v[152:155], v156 offset:2048
	ds_read_b128 v[156:159], v156 offset:3072
	v_lshl_add_u64 v[206:207], vcc, 0, v[202:203]
	s_add_i32 m0, s7, 0xc000
	ds_read_b128 v[160:163], v252
	ds_read_b128 v[164:167], v252 offset:1024
	ds_read_b128 v[168:171], v252 offset:2048
	ds_read_b128 v[172:175], v252 offset:3072
	ds_read_b128 v[176:179], v252 offset:4096
	ds_read_b128 v[180:183], v252 offset:5120
	ds_read_b128 v[184:187], v252 offset:6144
	ds_read_b128 v[188:191], v252 offset:7168
	global_load_lds_dwordx4 v[206:207], off
	v_lshl_add_u64 v[206:207], vcc, 0, v[204:205]
	s_add_i32 m0, s7, 0xe000
	s_nop 0
	global_load_lds_dwordx4 v[206:207], off
	s_waitcnt vmcnt(8)
	s_waitcnt lgkmcnt(0)
	s_barrier
	s_setprio 1
	s_waitcnt lgkmcnt(0)
	v_mfma_f32_16x16x32_bf16 v[124:127], v[128:131], v[160:163], v[124:127]
	v_mfma_f32_16x16x32_bf16 v[120:123], v[136:139], v[160:163], v[120:123]
	v_mfma_f32_16x16x32_bf16 v[108:111], v[128:131], v[168:171], v[108:111]
	v_mfma_f32_16x16x32_bf16 v[104:107], v[136:139], v[168:171], v[104:107]
	v_mfma_f32_16x16x32_bf16 v[92:95], v[128:131], v[176:179], v[92:95]
	v_mfma_f32_16x16x32_bf16 v[88:91], v[136:139], v[176:179], v[88:91]
	v_mfma_f32_16x16x32_bf16 v[76:79], v[128:131], v[184:187], v[76:79]
	v_mfma_f32_16x16x32_bf16 v[72:75], v[136:139], v[184:187], v[72:75]
	v_mfma_f32_16x16x32_bf16 v[124:127], v[132:135], v[164:167], v[124:127]
	v_mfma_f32_16x16x32_bf16 v[120:123], v[140:143], v[164:167], v[120:123]
	v_mfma_f32_16x16x32_bf16 v[108:111], v[132:135], v[172:175], v[108:111]
	v_mfma_f32_16x16x32_bf16 v[104:107], v[140:143], v[172:175], v[104:107]
	v_mfma_f32_16x16x32_bf16 v[92:95], v[132:135], v[180:183], v[92:95]
	v_mfma_f32_16x16x32_bf16 v[88:91], v[140:143], v[180:183], v[88:91]
	v_mfma_f32_16x16x32_bf16 v[76:79], v[132:135], v[188:191], v[76:79]
	v_mfma_f32_16x16x32_bf16 v[72:75], v[140:143], v[188:191], v[72:75]
	s_setprio 0
	s_setprio 1
	v_mfma_f32_16x16x32_bf16 v[116:119], v[144:147], v[160:163], v[116:119]
	v_mfma_f32_16x16x32_bf16 v[112:115], v[152:155], v[160:163], v[112:115]
	v_mfma_f32_16x16x32_bf16 v[100:103], v[144:147], v[168:171], v[100:103]
	v_mfma_f32_16x16x32_bf16 v[96:99], v[152:155], v[168:171], v[96:99]
	v_mfma_f32_16x16x32_bf16 v[84:87], v[144:147], v[176:179], v[84:87]
	v_mfma_f32_16x16x32_bf16 v[80:83], v[152:155], v[176:179], v[80:83]
	v_mfma_f32_16x16x32_bf16 v[68:71], v[144:147], v[184:187], v[68:71]
	v_mfma_f32_16x16x32_bf16 v[64:67], v[152:155], v[184:187], v[64:67]
	v_mfma_f32_16x16x32_bf16 v[116:119], v[148:151], v[164:167], v[116:119]
	v_mfma_f32_16x16x32_bf16 v[112:115], v[156:159], v[164:167], v[112:115]
	v_mfma_f32_16x16x32_bf16 v[100:103], v[148:151], v[172:175], v[100:103]
	v_mfma_f32_16x16x32_bf16 v[96:99], v[156:159], v[172:175], v[96:99]
	v_mfma_f32_16x16x32_bf16 v[84:87], v[148:151], v[180:183], v[84:87]
	v_mfma_f32_16x16x32_bf16 v[80:83], v[156:159], v[180:183], v[80:83]
	v_mfma_f32_16x16x32_bf16 v[68:71], v[148:151], v[188:191], v[68:71]
	v_mfma_f32_16x16x32_bf16 v[64:67], v[156:159], v[188:191], v[64:67]
	s_setprio 0
	s_barrier
	s_add_i32 s10, s12, s4
	v_lshl_add_u64 v[206:207], s[66:67], 0, v[192:193]
	s_mov_b32 m0, s10
	ds_read_b128 v[160:163], v252 offset:16384
	ds_read_b128 v[164:167], v252 offset:17408
	ds_read_b128 v[168:171], v252 offset:18432
	ds_read_b128 v[172:175], v252 offset:19456
	ds_read_b128 v[176:179], v252 offset:20480
	ds_read_b128 v[180:183], v252 offset:21504
	ds_read_b128 v[184:187], v252 offset:22528
	ds_read_b128 v[188:191], v252 offset:23552
	global_load_lds_dwordx4 v[206:207], off
	s_add_i32 m0, s10, 0x2000
	s_add_u32 s10, s66, 0x40000
	v_lshl_add_u64 v[208:209], s[66:67], 0, v[200:201]
	s_addc_u32 s11, s67, 0
	s_add_i32 s12, s13, s4
	global_load_lds_dwordx4 v[208:209], off
	s_mov_b32 m0, s12
	v_lshl_add_u64 v[212:213], s[84:85], 0, v[198:199]
	global_load_lds_dwordx4 v192, s[10:11]
	s_add_i32 m0, s12, 0x2000
	s_nop 0
	global_load_lds_dwordx4 v200, s[10:11]
	v_lshl_add_u64 v[210:211], s[84:85], 0, v[196:197]
	s_mov_b32 m0, s7
	s_nop 0
	global_load_lds_dwordx4 v[210:211], off
	s_mov_b32 m0, s76
	s_nop 0
	global_load_lds_dwordx4 v[212:213], off
	s_waitcnt vmcnt(8)
	s_waitcnt lgkmcnt(0)
	s_barrier
; #define PG8_STAGE(bufoff, gbase, voff) do { _Pragma("unroll") for (int _i = 0; _i < 2; ++_i) \
;         __builtin_amdgcn_global_load_lds((const unsigned*)((const char*)(gbase) + (voff)[_i]), (PG8_LAS unsigned*)(lds + (bufoff) + ldsw + _i * 8192), 16, 0, 0); } while (0)
; #define PG8_LDA(dst, b, h) do { _Pragma("unroll") for (int m = 0; m < 4; ++m) _Pragma("unroll") for (int k = 0; k < 2; ++k) dst[m][k] = *(const PG8_LAS bf16x8*)(lds + PG8_SA(b, h) + aoff + m * 2048 + k * 1024); } while (0)
; #define PG8_LDB(dst, b, h) do { _Pragma("unroll") for (int n = 0; n < 2; ++n) _Pragma("unroll") for (int k = 0; k < 2; ++k) dst[n][k] = *(const PG8_LAS bf16x8*)(lds + PG8_SB(b, h) + boff + n * 2048 + k * 1024); } while (0)
; #define PG8_MMA(ai, bj, At, Bt) do { __builtin_amdgcn_s_setprio(1); _Pragma("unroll") for (int m = 0; m < 4; ++m) _Pragma("unroll") for (int n = 0; n < 2; ++n) _Pragma("unroll") for (int k = 0; k < 2; ++k) \
;         acc[ai][bj][m][n] = __builtin_amdgcn_mfma_f32_16x16x32_bf16(Bt[n][k], At[m][k], acc[ai][bj][m][n], 0, 0, 0); __builtin_amdgcn_s_setprio(0); } while (0)
; #define PG8_WAIT_V(n) asm volatile("s_waitcnt vmcnt(" #n ")" ::: "memory")
; #define PG8_WAIT_L(n) asm volatile("s_waitcnt lgkmcnt(" #n ")" ::: "memory")
; #define PG8_BAR __builtin_amdgcn_s_barrier()
; #define PG8_SCHED __builtin_amdgcn_sched_barrier(0)
; template <class Epi, class Sched, bool ALIGN_EPI = false, bool SP2 = false>
; __device__ __forceinline__ void gemm_phase(PG8_LAS unsigned char* lds, const Gemm g, const Sched& S, const Epi& E, const int tid) {
;     ...
;             PG8_WAIT_V(8); PG8_WAIT_L(0); PG8_BAR; PG8_MMA(1, 0, At, B0); PG8_MMA(1, 1, At, B1); PG8_BAR; PG8_SCHED;
;             PG8_LDB(B0, 1, 0); PG8_LDB(B1, 1, 1); PG8_SCHED; PG8_LDA(At, 1, 0); PG8_STAGE(PG8_SA(0, 1), a2 + hstep, voffA);
;             PG8_WAIT_V(8); PG8_WAIT_L(0); PG8_BAR; PG8_MMA(0, 0, At, B0); PG8_MMA(0, 1, At, B1); PG8_BAR; PG8_SCHED;
	s_setprio 1
	s_waitcnt lgkmcnt(0)
	v_mfma_f32_16x16x32_bf16 v[60:63], v[128:131], v[160:163], v[60:63]
	v_mfma_f32_16x16x32_bf16 v[56:59], v[136:139], v[160:163], v[56:59]
	v_mfma_f32_16x16x32_bf16 v[44:47], v[128:131], v[168:171], v[44:47]
	v_mfma_f32_16x16x32_bf16 v[40:43], v[136:139], v[168:171], v[40:43]
	v_mfma_f32_16x16x32_bf16 v[28:31], v[128:131], v[176:179], v[28:31]
	v_mfma_f32_16x16x32_bf16 v[24:27], v[136:139], v[176:179], v[24:27]
	v_mfma_f32_16x16x32_bf16 v[12:15], v[128:131], v[184:187], v[12:15]
	v_mfma_f32_16x16x32_bf16 v[8:11], v[136:139], v[184:187], v[8:11]
	v_mfma_f32_16x16x32_bf16 v[60:63], v[132:135], v[164:167], v[60:63]
	v_mfma_f32_16x16x32_bf16 v[56:59], v[140:143], v[164:167], v[56:59]
	v_mfma_f32_16x16x32_bf16 v[44:47], v[132:135], v[172:175], v[44:47]
	v_mfma_f32_16x16x32_bf16 v[40:43], v[140:143], v[172:175], v[40:43]
	v_mfma_f32_16x16x32_bf16 v[28:31], v[132:135], v[180:183], v[28:31]
	v_mfma_f32_16x16x32_bf16 v[24:27], v[140:143], v[180:183], v[24:27]
	v_mfma_f32_16x16x32_bf16 v[12:15], v[132:135], v[188:191], v[12:15]
	v_mfma_f32_16x16x32_bf16 v[8:11], v[140:143], v[188:191], v[8:11]
	s_setprio 0
	s_setprio 1
	v_mfma_f32_16x16x32_bf16 v[52:55], v[144:147], v[160:163], v[52:55]
	v_mfma_f32_16x16x32_bf16 v[48:51], v[152:155], v[160:163], v[48:51]
	v_mfma_f32_16x16x32_bf16 v[36:39], v[144:147], v[168:171], v[36:39]
	v_mfma_f32_16x16x32_bf16 v[32:35], v[152:155], v[168:171], v[32:35]
	v_mfma_f32_16x16x32_bf16 v[20:23], v[144:147], v[176:179], v[20:23]
	v_mfma_f32_16x16x32_bf16 v[16:19], v[152:155], v[176:179], v[16:19]
	v_mfma_f32_16x16x32_bf16 v[4:7], v[144:147], v[184:187], v[4:7]
	v_mfma_f32_16x16x32_bf16 v[0:3], v[152:155], v[184:187], v[0:3]
	v_mfma_f32_16x16x32_bf16 v[52:55], v[148:151], v[164:167], v[52:55]
	v_mfma_f32_16x16x32_bf16 v[48:51], v[156:159], v[164:167], v[48:51]
	v_mfma_f32_16x16x32_bf16 v[36:39], v[148:151], v[172:175], v[36:39]
	v_mfma_f32_16x16x32_bf16 v[32:35], v[156:159], v[172:175], v[32:35]
	v_mfma_f32_16x16x32_bf16 v[20:23], v[148:151], v[180:183], v[20:23]
	v_mfma_f32_16x16x32_bf16 v[16:19], v[156:159], v[180:183], v[16:19]
	v_mfma_f32_16x16x32_bf16 v[4:7], v[148:151], v[188:191], v[4:7]
	v_mfma_f32_16x16x32_bf16 v[0:3], v[156:159], v[188:191], v[0:3]
	s_setprio 0
	s_barrier
	s_add_i32 s12, 0, 0x18000
	s_add_i32 s13, 0, 0x1c000
	v_add_u32_e32 v140, s12, v248
	v_add_u32_e32 v156, s13, v248
	ds_read_b128 v[128:131], v140
	ds_read_b128 v[132:135], v140 offset:1024
	ds_read_b128 v[136:139], v140 offset:2048
	ds_read_b128 v[140:143], v140 offset:3072
	ds_read_b128 v[144:147], v156
	ds_read_b128 v[148:151], v156 offset:1024
	ds_read_b128 v[152:155], v156 offset:2048
	ds_read_b128 v[156:159], v156 offset:3072
	s_add_u32 s10, s84, 0x40000
	s_addc_u32 s11, s85, 0
	s_mov_b32 m0, s77
	ds_read_b128 v[160:163], v252 offset:32768
	ds_read_b128 v[164:167], v252 offset:33792
	ds_read_b128 v[168:171], v252 offset:34816
	ds_read_b128 v[172:175], v252 offset:35840
	ds_read_b128 v[176:179], v252 offset:36864
	ds_read_b128 v[180:183], v252 offset:37888
	ds_read_b128 v[184:187], v252 offset:38912
	ds_read_b128 v[188:191], v252 offset:39936
	global_load_lds_dwordx4 v196, s[10:11]
	v_lshl_add_u64 v[214:215], s[10:11], 0, v[198:199]
	s_mov_b32 m0, s95
	s_nop 0
	global_load_lds_dwordx4 v[214:215], off
	s_waitcnt vmcnt(8)
	s_waitcnt lgkmcnt(0)
	s_barrier
	s_setprio 1
	s_waitcnt lgkmcnt(0)
	v_mfma_f32_16x16x32_bf16 v[124:127], v[128:131], v[160:163], v[124:127]
	v_mfma_f32_16x16x32_bf16 v[120:123], v[136:139], v[160:163], v[120:123]
	v_mfma_f32_16x16x32_bf16 v[108:111], v[128:131], v[168:171], v[108:111]
	v_mfma_f32_16x16x32_bf16 v[104:107], v[136:139], v[168:171], v[104:107]
	v_mfma_f32_16x16x32_bf16 v[92:95], v[128:131], v[176:179], v[92:95]
	v_mfma_f32_16x16x32_bf16 v[88:91], v[136:139], v[176:179], v[88:91]
	v_mfma_f32_16x16x32_bf16 v[76:79], v[128:131], v[184:187], v[76:79]
	v_mfma_f32_16x16x32_bf16 v[72:75], v[136:139], v[184:187], v[72:75]
	v_mfma_f32_16x16x32_bf16 v[124:127], v[132:135], v[164:167], v[124:127]
	v_mfma_f32_16x16x32_bf16 v[120:123], v[140:143], v[164:167], v[120:123]
	v_mfma_f32_16x16x32_bf16 v[108:111], v[132:135], v[172:175], v[108:111]
	v_mfma_f32_16x16x32_bf16 v[104:107], v[140:143], v[172:175], v[104:107]
	v_mfma_f32_16x16x32_bf16 v[92:95], v[132:135], v[180:183], v[92:95]
	v_mfma_f32_16x16x32_bf16 v[88:91], v[140:143], v[180:183], v[88:91]
	v_mfma_f32_16x16x32_bf16 v[76:79], v[132:135], v[188:191], v[76:79]
	v_mfma_f32_16x16x32_bf16 v[72:75], v[140:143], v[188:191], v[72:75]
	s_setprio 0
	s_setprio 1
	v_mfma_f32_16x16x32_bf16 v[116:119], v[144:147], v[160:163], v[116:119]
	v_mfma_f32_16x16x32_bf16 v[112:115], v[152:155], v[160:163], v[112:115]
	v_mfma_f32_16x16x32_bf16 v[100:103], v[144:147], v[168:171], v[100:103]
	v_mfma_f32_16x16x32_bf16 v[96:99], v[152:155], v[168:171], v[96:99]
	v_mfma_f32_16x16x32_bf16 v[84:87], v[144:147], v[176:179], v[84:87]
	v_mfma_f32_16x16x32_bf16 v[80:83], v[152:155], v[176:179], v[80:83]
	v_mfma_f32_16x16x32_bf16 v[68:71], v[144:147], v[184:187], v[68:71]
	v_mfma_f32_16x16x32_bf16 v[64:67], v[152:155], v[184:187], v[64:67]
	v_mfma_f32_16x16x32_bf16 v[116:119], v[148:151], v[164:167], v[116:119]
	v_mfma_f32_16x16x32_bf16 v[112:115], v[156:159], v[164:167], v[112:115]
	v_mfma_f32_16x16x32_bf16 v[100:103], v[148:151], v[172:175], v[100:103]
	v_mfma_f32_16x16x32_bf16 v[96:99], v[156:159], v[172:175], v[96:99]
	v_mfma_f32_16x16x32_bf16 v[84:87], v[148:151], v[180:183], v[84:87]
	v_mfma_f32_16x16x32_bf16 v[80:83], v[156:159], v[180:183], v[80:83]
	v_mfma_f32_16x16x32_bf16 v[68:71], v[148:151], v[188:191], v[68:71]
	v_mfma_f32_16x16x32_bf16 v[64:67], v[156:159], v[188:191], v[64:67]
	s_setprio 0
	s_barrier
; #define PG8_STAGE(bufoff, gbase, voff) do { _Pragma("unroll") for (int _i = 0; _i < 2; ++_i) \
;         __builtin_amdgcn_global_load_lds((const unsigned*)((const char*)(gbase) + (voff)[_i]), (PG8_LAS unsigned*)(lds + (bufoff) + ldsw + _i * 8192), 16, 0, 0); } while (0)
; #define PG8_LDA(dst, b, h) do { _Pragma("unroll") for (int m = 0; m < 4; ++m) _Pragma("unroll") for (int k = 0; k < 2; ++k) dst[m][k] = *(const PG8_LAS bf16x8*)(lds + PG8_SA(b, h) + aoff + m * 2048 + k * 1024); } while (0)
; #define PG8_MMA(ai, bj, At, Bt) do { __builtin_amdgcn_s_setprio(1); _Pragma("unroll") for (int m = 0; m < 4; ++m) _Pragma("unroll") for (int n = 0; n < 2; ++n) _Pragma("unroll") for (int k = 0; k < 2; ++k) \
;         acc[ai][bj][m][n] = __builtin_amdgcn_mfma_f32_16x16x32_bf16(Bt[n][k], At[m][k], acc[ai][bj][m][n], 0, 0, 0); __builtin_amdgcn_s_setprio(0); } while (0)
; #define PG8_WAIT_V(n) asm volatile("s_waitcnt vmcnt(" #n ")" ::: "memory")
; #define PG8_WAIT_L(n) asm volatile("s_waitcnt lgkmcnt(" #n ")" ::: "memory")
; #define PG8_BAR __builtin_amdgcn_s_barrier()
; #define PG8_SCHED __builtin_amdgcn_sched_barrier(0)
; template <class Epi, class Sched, bool ALIGN_EPI = false, bool SP2 = false>
; __device__ __forceinline__ void gemm_phase(PG8_LAS unsigned char* lds, const Gemm g, const Sched& S, const Epi& E, const int tid) {
;     ...
;             PG8_LDA(At, 1, 1); PG8_STAGE(PG8_SB(1, 0), b3, voffB); PG8_STAGE(PG8_SB(1, 1), b3 + hstep, voffB); PG8_STAGE(PG8_SA(1, 0), a3, voffA);
;             PG8_WAIT_V(8); PG8_WAIT_L(0); PG8_BAR; PG8_MMA(1, 0, At, B0); PG8_MMA(1, 1, At, B1); PG8_BAR; PG8_SCHED;
	s_add_i32 s10, s12, s4
	v_lshl_add_u64 v[206:207], v[206:207], 0, s[22:23]
	s_mov_b32 m0, s10
	ds_read_b128 v[160:163], v252 offset:49152
	ds_read_b128 v[164:167], v252 offset:50176
	ds_read_b128 v[168:171], v252 offset:51200
	ds_read_b128 v[172:175], v252 offset:52224
	ds_read_b128 v[176:179], v252 offset:53248
	ds_read_b128 v[180:183], v252 offset:54272
	ds_read_b128 v[184:187], v252 offset:55296
	ds_read_b128 v[188:191], v252 offset:56320
	global_load_lds_dwordx4 v[206:207], off
	s_add_i32 m0, s10, 0x2000
	s_add_u32 s10, s66, 0x40080
	v_lshl_add_u64 v[206:207], v[208:209], 0, s[22:23]
	s_addc_u32 s11, s67, 0
	s_add_i32 s12, s13, s4
	global_load_lds_dwordx4 v[206:207], off
	s_mov_b32 m0, s12
	s_nop 0
	global_load_lds_dwordx4 v192, s[10:11]
	s_add_i32 m0, s12, 0x2000
	s_nop 0
	global_load_lds_dwordx4 v200, s[10:11]
	v_lshl_add_u64 v[206:207], v[210:211], 0, s[22:23]
	s_mov_b32 m0, s92
	s_nop 0
	global_load_lds_dwordx4 v[206:207], off
	v_lshl_add_u64 v[206:207], v[212:213], 0, s[22:23]
	s_mov_b32 m0, s93
	s_nop 0
	global_load_lds_dwordx4 v[206:207], off
	s_waitcnt vmcnt(8)
	s_waitcnt lgkmcnt(0)
	s_barrier
	s_setprio 1
	s_waitcnt lgkmcnt(0)
	v_mfma_f32_16x16x32_bf16 v[60:63], v[128:131], v[160:163], v[60:63]
	v_mfma_f32_16x16x32_bf16 v[56:59], v[136:139], v[160:163], v[56:59]
	v_mfma_f32_16x16x32_bf16 v[44:47], v[128:131], v[168:171], v[44:47]
	v_mfma_f32_16x16x32_bf16 v[40:43], v[136:139], v[168:171], v[40:43]
	v_mfma_f32_16x16x32_bf16 v[28:31], v[128:131], v[176:179], v[28:31]
	v_mfma_f32_16x16x32_bf16 v[24:27], v[136:139], v[176:179], v[24:27]
	v_mfma_f32_16x16x32_bf16 v[12:15], v[128:131], v[184:187], v[12:15]
	v_mfma_f32_16x16x32_bf16 v[8:11], v[136:139], v[184:187], v[8:11]
	v_mfma_f32_16x16x32_bf16 v[60:63], v[132:135], v[164:167], v[60:63]
	v_mfma_f32_16x16x32_bf16 v[56:59], v[140:143], v[164:167], v[56:59]
	v_mfma_f32_16x16x32_bf16 v[44:47], v[132:135], v[172:175], v[44:47]
	v_mfma_f32_16x16x32_bf16 v[40:43], v[140:143], v[172:175], v[40:43]
	v_mfma_f32_16x16x32_bf16 v[28:31], v[132:135], v[180:183], v[28:31]
	v_mfma_f32_16x16x32_bf16 v[24:27], v[140:143], v[180:183], v[24:27]
	v_mfma_f32_16x16x32_bf16 v[12:15], v[132:135], v[188:191], v[12:15]
	v_mfma_f32_16x16x32_bf16 v[8:11], v[140:143], v[188:191], v[8:11]
	s_setprio 0
	s_setprio 1
	v_mfma_f32_16x16x32_bf16 v[52:55], v[144:147], v[160:163], v[52:55]
	v_mfma_f32_16x16x32_bf16 v[48:51], v[152:155], v[160:163], v[48:51]
	v_mfma_f32_16x16x32_bf16 v[36:39], v[144:147], v[168:171], v[36:39]
	v_mfma_f32_16x16x32_bf16 v[32:35], v[152:155], v[168:171], v[32:35]
	v_mfma_f32_16x16x32_bf16 v[20:23], v[144:147], v[176:179], v[20:23]
	v_mfma_f32_16x16x32_bf16 v[16:19], v[152:155], v[176:179], v[16:19]
	v_mfma_f32_16x16x32_bf16 v[4:7], v[144:147], v[184:187], v[4:7]
	v_mfma_f32_16x16x32_bf16 v[0:3], v[152:155], v[184:187], v[0:3]
	v_mfma_f32_16x16x32_bf16 v[52:55], v[148:151], v[164:167], v[52:55]
	v_mfma_f32_16x16x32_bf16 v[48:51], v[156:159], v[164:167], v[48:51]
	v_mfma_f32_16x16x32_bf16 v[36:39], v[148:151], v[172:175], v[36:39]
	v_mfma_f32_16x16x32_bf16 v[32:35], v[156:159], v[172:175], v[32:35]
	v_mfma_f32_16x16x32_bf16 v[20:23], v[148:151], v[180:183], v[20:23]
	v_mfma_f32_16x16x32_bf16 v[16:19], v[156:159], v[180:183], v[16:19]
	v_mfma_f32_16x16x32_bf16 v[4:7], v[148:151], v[188:191], v[4:7]
	v_mfma_f32_16x16x32_bf16 v[0:3], v[156:159], v[188:191], v[0:3]
	s_setprio 0
	s_barrier
	s_add_i32 s9, s9, 2
	s_add_u32 vcc_lo, vcc_lo, 0x100
	s_addc_u32 vcc_hi, vcc_hi, 0
	s_add_u32 s82, s82, 0x100
	s_addc_u32 s8, s8, 0
	s_cmp_gt_u32 s9, 13
	s_cbranch_scc0 .LBB0_326
	s_and_b64 vcc, exec, s[58:59]
	s_cbranch_vccz .LBB0_329
	s_barrier

; #define PG8_STAGE(bufoff, gbase, voff) do { _Pragma("unroll") for (int _i = 0; _i < 2; ++_i) \
;         __builtin_amdgcn_global_load_lds((const unsigned*)((const char*)(gbase) + (voff)[_i]), (PG8_LAS unsigned*)(lds + (bufoff) + ldsw + _i * 8192), 16, 0, 0); } while (0)
; #define PG8_WAIT_V(n) asm volatile("s_waitcnt vmcnt(" #n ")" ::: "memory")
; #define PG8_BAR __builtin_amdgcn_s_barrier()
; template <class Epi, class Sched, bool ALIGN_EPI = false, bool SP2 = false>
; __device__ __forceinline__ void gemm_phase(PG8_LAS unsigned char* lds, const Gemm g, const Sched& S, const Epi& E, const int tid) {
;     ...
;         PG8_WAIT_V(2); PG8_BAR;
;         PG8_STAGE(PG8_SB(1, 0), cB + kstep, voffB); PG8_STAGE(PG8_SA(1, 0), cA + kstep, voffA); PG8_STAGE(PG8_SB(1, 1), cB + hstep + kstep, voffB);
;         PG8_WAIT_V(6); PG8_BAR;
;     DI void operator()(const f32x4 (&acc)[2][2][4][2], const Unit& u, int wr, int wc, int fr, int fq) const {
;     ...
;         if (isnorm) { const float* wp = type == 0 ? qnw : knw;
; #pragma unroll
;             for (int bj = 0; bj < 2; ++bj)
; #pragma unroll
;                 for (int n = 0; n < 2; ++n)
; #pragma unroll
;                     for (int j = 0; j < 4; ++j) w[bj][n][j] = wp[pi_diff(32 * bj + 8 * fq + 4 * n + j)]; }
.LBB0_453:
	v_bfe_u32 v17, v8, 4, 2
	v_and_b32_e32 v15, 15, v8
	v_lshlrev_b32_e32 v8, 4, v17
	v_lshl_or_b32 v164, s8, 6, v15
	v_lshl_or_b32 v8, v15, 6, v8
	v_lshlrev_b32_e32 v15, 2, v15
	s_and_b32 s10, s4, 3
	s_lshl_b32 s4, s8, 13
	v_and_b32_e32 v16, 32, v15
	v_bitop3_b32 v21, v8, s4, v16 bitop3:0xde
	s_lshl_b32 s4, s10, 12
	s_add_u32 s58, s62, 0x24410000
	s_addc_u32 s59, s63, 0
	s_add_i32 m0, s96, 0x18000
	v_lshl_add_u64 v[4:5], v[4:5], 0, s[22:23]
	v_bitop3_b32 v165, s4, v8, v16 bitop3:0xf6
	s_add_i32 s4, s50, -1
	s_waitcnt vmcnt(2)
	s_barrier
	global_load_lds_dwordx4 v[4:5], off
	v_lshl_add_u64 v[2:3], v[2:3], 0, s[22:23]
	s_add_i32 m0, s96, 0x1a000
	s_add_i32 s5, s96, 0x8000
	s_add_i32 s6, s96, 0xa000
	global_load_lds_dwordx4 v[2:3], off
	v_lshl_add_u64 v[0:1], v[0:1], 0, s[22:23]
	s_mov_b32 m0, s5
	s_add_u32 s38, s42, 0x40080
	global_load_lds_dwordx4 v[0:1], off
	v_lshl_add_u64 v[0:1], v[6:7], 0, s[22:23]
	s_mov_b32 m0, s6
	s_addc_u32 s39, s43, 0
	global_load_lds_dwordx4 v[0:1], off
	s_add_i32 m0, s96, 0x1c000
	s_nop 0
	global_load_lds_dwordx4 v130, s[38:39]
	v_lshl_add_u64 v[0:1], s[38:39], 0, v[134:135]
	s_add_i32 m0, s96, 0x1e000
	v_lshlrev_b32_e32 v19, 3, v17
	global_load_lds_dwordx4 v[0:1], off
	v_or_b32_e32 v22, 32, v19
	v_add_u32_e32 v1, 8, v19
	v_cmp_eq_u32_e64 s[38:39], 0, v17
	v_cmp_gt_u32_e32 vcc, 40, v22
	v_add_u32_e32 v3, 9, v19
	v_cndmask_b32_e64 v0, v1, 0, s[38:39]
	v_cndmask_b32_e32 v22, v22, v1, vcc
	v_or_b32_e32 v1, 33, v19
	v_cmp_gt_u32_e32 vcc, 40, v1
	v_add_u32_e32 v5, 10, v19
	v_add_u32_e32 v7, 11, v19
	v_cndmask_b32_e32 v24, v1, v3, vcc
	v_or_b32_e32 v1, 34, v19
	v_cmp_gt_u32_e32 vcc, 40, v1
	v_add_u32_e32 v23, 12, v19
	v_add_u32_e32 v25, 13, v19
	v_cndmask_b32_e32 v26, v1, v5, vcc
	v_or_b32_e32 v1, 35, v19
	v_cmp_gt_u32_e32 vcc, 40, v1
	v_add_u32_e32 v27, 14, v19
	v_cndmask_b32_e64 v2, v3, 1, s[38:39]
	v_cndmask_b32_e32 v28, v1, v7, vcc
	v_or_b32_e32 v1, 36, v19
	v_cmp_gt_u32_e32 vcc, 40, v1
	v_and_b32_e32 v3, 64, v245
	v_add_u32_e32 v3, 64, v3
	v_cndmask_b32_e32 v30, v1, v23, vcc
	v_or_b32_e32 v1, 37, v19
	v_cmp_gt_u32_e32 vcc, 40, v1
	s_cmpk_lt_u32 s7, 0x100
	s_cselect_b64 s[66:67], -1, 0
	v_cndmask_b32_e32 v32, v1, v25, vcc
	v_or_b32_e32 v1, 38, v19
	v_cmp_gt_u32_e32 vcc, 40, v1
	s_lshl_b32 s7, s8, 8
	s_waitcnt vmcnt(6)
	v_add_u32_e32 v20, 15, v19
	v_cndmask_b32_e32 v34, v1, v27, vcc
	v_or_b32_e32 v1, 39, v19
	v_cndmask_b32_e64 v36, v1, 15, s[38:39]
	v_xor_b32_e32 v1, 16, v245
	v_cmp_lt_i32_e32 vcc, v1, v3
	s_add_i32 s7, s7, 0
	v_lshlrev_b32_e32 v192, 5, v17
	v_cndmask_b32_e32 v1, v245, v1, vcc
	v_lshlrev_b32_e32 v167, 2, v1
	v_xor_b32_e32 v1, 32, v245
	v_cmp_lt_i32_e32 vcc, v1, v3
	v_and_b32_e32 v3, 1, v9
	v_cndmask_b32_e64 v4, v5, 2, s[38:39]
	v_cndmask_b32_e32 v1, v245, v1, vcc
	v_lshlrev_b32_e32 v168, 2, v1
	v_lshlrev_b32_e32 v1, 14, v9
	v_and_b32_e32 v1, 0xffff8000, v1
	v_lshl_add_u32 v1, v10, 11, v1
	v_lshl_or_b32 v1, v3, 6, v1
	v_lshl_add_u32 v138, v11, 1, v1
	v_lshlrev_b32_e32 v1, 14, v12
	v_and_b32_e32 v1, 0xffff8000, v1
	v_lshl_add_u32 v1, v13, 11, v1
	v_and_b32_e32 v3, 1, v12
	v_cndmask_b32_e64 v6, v7, 3, s[38:39]
	v_cndmask_b32_e64 v8, v23, 4, s[38:39]
	v_cndmask_b32_e64 v16, v25, 5, s[38:39]
	v_cndmask_b32_e64 v18, v27, 6, s[38:39]
	v_cndmask_b32_e64 v20, v20, 7, s[38:39]
	s_add_i32 s7, s7, 0x20000
	v_lshl_add_u64 v[38:39], s[62:63], 0, v[192:193]
	s_mov_b64 s[8:9], 0x24210000
	v_lshl_or_b32 v1, v3, 6, v1
	s_mov_b32 s31, 0
	v_add_u32_e32 v166, s7, v15
	v_lshl_add_u64 v[136:137], v[38:39], 0, s[8:9]
	v_lshl_or_b32 v169, s10, 6, v19
	v_mov_b32_e32 v139, v193
	v_lshl_add_u32 v140, v14, 1, v1
	v_mov_b32_e32 v141, v193
	v_add_u32_e32 v170, 0, v21
	v_lshlrev_b32_e32 v171, 2, v0
	v_lshlrev_b32_e32 v172, 2, v2
	v_lshlrev_b32_e32 v173, 2, v4
	v_lshlrev_b32_e32 v174, 2, v6
	v_lshlrev_b32_e32 v175, 2, v8
	v_lshlrev_b32_e32 v176, 2, v16
	v_lshlrev_b32_e32 v177, 2, v18
	v_lshlrev_b32_e32 v178, 2, v20
	v_lshlrev_b32_e32 v179, 2, v22
	v_lshlrev_b32_e32 v180, 2, v24
	v_lshlrev_b32_e32 v181, 2, v26
	v_lshlrev_b32_e32 v182, 2, v28
	v_lshlrev_b32_e32 v183, 2, v30
	v_lshlrev_b32_e32 v184, 2, v32
	v_lshlrev_b32_e32 v185, 2, v34
	v_lshlrev_b32_e32 v186, 2, v36
	s_mov_b64 s[20:21], s[88:89]
	s_barrier
	s_branch .LBB0_456

; #define PG8_STAGE(bufoff, gbase, voff) do { _Pragma("unroll") for (int _i = 0; _i < 2; ++_i) \
;         __builtin_amdgcn_global_load_lds((const unsigned*)((const char*)(gbase) + (voff)[_i]), (PG8_LAS unsigned*)(lds + (bufoff) + ldsw + _i * 8192), 16, 0, 0); } while (0)
; #define PG8_LDA(dst, b, h) do { _Pragma("unroll") for (int m = 0; m < 4; ++m) _Pragma("unroll") for (int k = 0; k < 2; ++k) dst[m][k] = *(const PG8_LAS bf16x8*)(lds + PG8_SA(b, h) + aoff + m * 2048 + k * 1024); } while (0)
; #define PG8_LDB(dst, b, h) do { _Pragma("unroll") for (int n = 0; n < 2; ++n) _Pragma("unroll") for (int k = 0; k < 2; ++k) dst[n][k] = *(const PG8_LAS bf16x8*)(lds + PG8_SB(b, h) + boff + n * 2048 + k * 1024); } while (0)
; #define PG8_MMA(ai, bj, At, Bt) do { __builtin_amdgcn_s_setprio(1); _Pragma("unroll") for (int m = 0; m < 4; ++m) _Pragma("unroll") for (int n = 0; n < 2; ++n) _Pragma("unroll") for (int k = 0; k < 2; ++k) \
;         acc[ai][bj][m][n] = __builtin_amdgcn_mfma_f32_16x16x32_bf16(Bt[n][k], At[m][k], acc[ai][bj][m][n], 0, 0, 0); __builtin_amdgcn_s_setprio(0); } while (0)
; #define PG8_WAIT_V(n) asm volatile("s_waitcnt vmcnt(" #n ")" ::: "memory")
; #define PG8_WAIT_L(n) asm volatile("s_waitcnt lgkmcnt(" #n ")" ::: "memory")
; template <class Epi, class Sched, bool ALIGN_EPI = false, bool SP2 = false>
; __device__ __forceinline__ void gemm_phase(PG8_LAS unsigned char* lds, const Gemm g, const Sched& S, const Epi& E, const int tid) {
;     ...
;             const bool last = (t == nt - 2);
;             const char* a1 = cA + (size_t)(t + 1) * kstep;
;             const char* a2 = last ? nA : cA + (size_t)(t + 2) * kstep; const char* b2 = last ? nB : cB + (size_t)(t + 2) * kstep;
;             const char* a3 = a2 + kstep; const char* b3 = b2 + kstep;
;             if (last && has_next) S.a_ready(nxt);
;             if constexpr (SP2) {
;             PG8_LDB(B0, 0, 0); PG8_LDB(B1, 0, 1); PG8_SCHED; PG8_LDA(At, 0, 0); PG8_STAGE(PG8_SA(1, 1), a1 + hstep, voffA);
;             PG8_WAIT_V(8); PG8_WAIT_L(0); PG8_BAR; PG8_MMA(0, 0, At, B0); PG8_MMA(0, 1, At, B1); PG8_BAR; PG8_SCHED;
;             PG8_LDA(At, 0, 1); PG8_STAGE(PG8_SB(0, 0), b2, voffB); PG8_STAGE(PG8_SB(0, 1), b2 + hstep, voffB); PG8_STAGE(PG8_SA(0, 0), a2, voffA);
;             PG8_WAIT_V(8); PG8_WAIT_L(0); PG8_BAR; PG8_MMA(1, 0, At, B0); PG8_MMA(1, 1, At, B1); PG8_BAR; PG8_SCHED;
.LBB0_459:
	s_add_u32 s9, s0, 0xfffc0080
	s_addc_u32 s10, s1, -1
	s_add_i32 s11, 0, 0x10000
	s_cmp_eq_u32 s8, 12
	s_cselect_b32 s87, s45, s10
	s_cselect_b32 s86, s50, s9
	s_cselect_b32 s43, s51, s57
	s_cselect_b32 s42, s53, s56
	s_add_i32 s9, 0, 0x14000
	s_waitcnt vmcnt(0)
	v_add_u32_e32 v154, s11, v165
	v_add_u32_e32 v162, s9, v165
	ds_read_b128 v[142:145], v154
	ds_read_b128 v[146:149], v154 offset:1024
	ds_read_b128 v[150:153], v154 offset:2048
	ds_read_b128 v[154:157], v154 offset:3072
	ds_read_b128 v[158:161], v162
	ds_read_b128 v[188:191], v162 offset:1024
	ds_read_b128 v[196:199], v162 offset:2048
	ds_read_b128 v[200:203], v162 offset:3072
	s_add_i32 m0, s96, 0xc000
	ds_read_b128 v[204:207], v170
	ds_read_b128 v[208:211], v170 offset:1024
	ds_read_b128 v[212:215], v170 offset:2048
	ds_read_b128 v[216:219], v170 offset:3072
	ds_read_b128 v[220:223], v170 offset:4096
	ds_read_b128 v[224:227], v170 offset:5120
	ds_read_b128 v[228:231], v170 offset:6144
	ds_read_b128 v[232:235], v170 offset:7168
	global_load_lds_dwordx4 v138, s[0:1]
	s_add_i32 m0, s96, 0xe000
	s_nop 0
	global_load_lds_dwordx4 v140, s[0:1]
	s_waitcnt vmcnt(8)
	s_waitcnt lgkmcnt(0)
	s_barrier
	s_setprio 1
	s_waitcnt lgkmcnt(0)
	v_mfma_f32_16x16x32_bf16 v[124:127], v[142:145], v[204:207], v[124:127]
	v_mfma_f32_16x16x32_bf16 v[120:123], v[150:153], v[204:207], v[120:123]
	v_mfma_f32_16x16x32_bf16 v[108:111], v[142:145], v[212:215], v[108:111]
	v_mfma_f32_16x16x32_bf16 v[104:107], v[150:153], v[212:215], v[104:107]
	v_mfma_f32_16x16x32_bf16 v[92:95], v[142:145], v[220:223], v[92:95]
	v_mfma_f32_16x16x32_bf16 v[88:91], v[150:153], v[220:223], v[88:91]
	v_mfma_f32_16x16x32_bf16 v[76:79], v[142:145], v[228:231], v[76:79]
	v_mfma_f32_16x16x32_bf16 v[72:75], v[150:153], v[228:231], v[72:75]
	v_mfma_f32_16x16x32_bf16 v[124:127], v[146:149], v[208:211], v[124:127]
	v_mfma_f32_16x16x32_bf16 v[120:123], v[154:157], v[208:211], v[120:123]
	v_mfma_f32_16x16x32_bf16 v[108:111], v[146:149], v[216:219], v[108:111]
	v_mfma_f32_16x16x32_bf16 v[104:107], v[154:157], v[216:219], v[104:107]
	v_mfma_f32_16x16x32_bf16 v[92:95], v[146:149], v[224:227], v[92:95]
	v_mfma_f32_16x16x32_bf16 v[88:91], v[154:157], v[224:227], v[88:91]
	v_mfma_f32_16x16x32_bf16 v[76:79], v[146:149], v[232:235], v[76:79]
	v_mfma_f32_16x16x32_bf16 v[72:75], v[154:157], v[232:235], v[72:75]
	s_setprio 0
	s_setprio 1
	v_mfma_f32_16x16x32_bf16 v[116:119], v[158:161], v[204:207], v[116:119]
	v_mfma_f32_16x16x32_bf16 v[112:115], v[196:199], v[204:207], v[112:115]
	v_mfma_f32_16x16x32_bf16 v[100:103], v[158:161], v[212:215], v[100:103]
	v_mfma_f32_16x16x32_bf16 v[96:99], v[196:199], v[212:215], v[96:99]
	v_mfma_f32_16x16x32_bf16 v[84:87], v[158:161], v[220:223], v[84:87]
	v_mfma_f32_16x16x32_bf16 v[80:83], v[196:199], v[220:223], v[80:83]
	v_mfma_f32_16x16x32_bf16 v[68:71], v[158:161], v[228:231], v[68:71]
	v_mfma_f32_16x16x32_bf16 v[64:67], v[196:199], v[228:231], v[64:67]
	v_mfma_f32_16x16x32_bf16 v[116:119], v[188:191], v[208:211], v[116:119]
	v_mfma_f32_16x16x32_bf16 v[112:115], v[200:203], v[208:211], v[112:115]
	v_mfma_f32_16x16x32_bf16 v[100:103], v[188:191], v[216:219], v[100:103]
	v_mfma_f32_16x16x32_bf16 v[96:99], v[200:203], v[216:219], v[96:99]
	v_mfma_f32_16x16x32_bf16 v[84:87], v[188:191], v[224:227], v[84:87]
	v_mfma_f32_16x16x32_bf16 v[80:83], v[200:203], v[224:227], v[80:83]
	v_mfma_f32_16x16x32_bf16 v[68:71], v[188:191], v[232:235], v[68:71]
	v_mfma_f32_16x16x32_bf16 v[64:67], v[200:203], v[232:235], v[64:67]
	s_setprio 0
	s_barrier
	s_add_i32 s10, s11, s95
	v_lshl_add_u64 v[162:163], s[42:43], 0, v[130:131]
	s_mov_b32 m0, s10
	ds_read_b128 v[204:207], v170 offset:16384
	ds_read_b128 v[208:211], v170 offset:17408
	ds_read_b128 v[212:215], v170 offset:18432
	ds_read_b128 v[216:219], v170 offset:19456
	ds_read_b128 v[220:223], v170 offset:20480
	ds_read_b128 v[224:227], v170 offset:21504
	ds_read_b128 v[228:231], v170 offset:22528
	ds_read_b128 v[232:235], v170 offset:23552
	global_load_lds_dwordx4 v[162:163], off
	s_add_i32 m0, s10, 0x2000
	s_add_u32 s88, s42, 0x40000
	v_lshl_add_u64 v[236:237], s[42:43], 0, v[134:135]
	s_addc_u32 s89, s43, 0
	s_add_i32 s9, s9, s95
	global_load_lds_dwordx4 v[236:237], off
	s_mov_b32 m0, s9
	v_lshl_add_u64 v[240:241], s[86:87], 0, v[132:133]
	global_load_lds_dwordx4 v130, s[88:89]
	s_add_i32 m0, s9, 0x2000
	s_nop 0
	global_load_lds_dwordx4 v134, s[88:89]
	v_lshl_add_u64 v[238:239], s[86:87], 0, v[128:129]
	s_mov_b32 m0, s96
	s_nop 0
	global_load_lds_dwordx4 v[238:239], off
	s_mov_b32 m0, s97
	s_nop 0
	global_load_lds_dwordx4 v[240:241], off
	s_waitcnt vmcnt(8)
	s_waitcnt lgkmcnt(0)
	s_barrier
; #define PG8_STAGE(bufoff, gbase, voff) do { _Pragma("unroll") for (int _i = 0; _i < 2; ++_i) \
;         __builtin_amdgcn_global_load_lds((const unsigned*)((const char*)(gbase) + (voff)[_i]), (PG8_LAS unsigned*)(lds + (bufoff) + ldsw + _i * 8192), 16, 0, 0); } while (0)
; #define PG8_LDA(dst, b, h) do { _Pragma("unroll") for (int m = 0; m < 4; ++m) _Pragma("unroll") for (int k = 0; k < 2; ++k) dst[m][k] = *(const PG8_LAS bf16x8*)(lds + PG8_SA(b, h) + aoff + m * 2048 + k * 1024); } while (0)
; #define PG8_LDB(dst, b, h) do { _Pragma("unroll") for (int n = 0; n < 2; ++n) _Pragma("unroll") for (int k = 0; k < 2; ++k) dst[n][k] = *(const PG8_LAS bf16x8*)(lds + PG8_SB(b, h) + boff + n * 2048 + k * 1024); } while (0)
; #define PG8_MMA(ai, bj, At, Bt) do { __builtin_amdgcn_s_setprio(1); _Pragma("unroll") for (int m = 0; m < 4; ++m) _Pragma("unroll") for (int n = 0; n < 2; ++n) _Pragma("unroll") for (int k = 0; k < 2; ++k) \
;         acc[ai][bj][m][n] = __builtin_amdgcn_mfma_f32_16x16x32_bf16(Bt[n][k], At[m][k], acc[ai][bj][m][n], 0, 0, 0); __builtin_amdgcn_s_setprio(0); } while (0)
; #define PG8_WAIT_V(n) asm volatile("s_waitcnt vmcnt(" #n ")" ::: "memory")
; #define PG8_WAIT_L(n) asm volatile("s_waitcnt lgkmcnt(" #n ")" ::: "memory")
; #define PG8_BAR __builtin_amdgcn_s_barrier()
; #define PG8_SCHED __builtin_amdgcn_sched_barrier(0)
; template <class Epi, class Sched, bool ALIGN_EPI = false, bool SP2 = false>
; __device__ __forceinline__ void gemm_phase(PG8_LAS unsigned char* lds, const Gemm g, const Sched& S, const Epi& E, const int tid) {
;     ...
;             PG8_WAIT_V(8); PG8_WAIT_L(0); PG8_BAR; PG8_MMA(1, 0, At, B0); PG8_MMA(1, 1, At, B1); PG8_BAR; PG8_SCHED;
;             PG8_LDB(B0, 1, 0); PG8_LDB(B1, 1, 1); PG8_SCHED; PG8_LDA(At, 1, 0); PG8_STAGE(PG8_SA(0, 1), a2 + hstep, voffA);
;             PG8_WAIT_V(8); PG8_WAIT_L(0); PG8_BAR; PG8_MMA(0, 0, At, B0); PG8_MMA(0, 1, At, B1); PG8_BAR; PG8_SCHED;
	s_setprio 1
	s_waitcnt lgkmcnt(0)
	v_mfma_f32_16x16x32_bf16 v[60:63], v[142:145], v[204:207], v[60:63]
	v_mfma_f32_16x16x32_bf16 v[56:59], v[150:153], v[204:207], v[56:59]
	v_mfma_f32_16x16x32_bf16 v[44:47], v[142:145], v[212:215], v[44:47]
	v_mfma_f32_16x16x32_bf16 v[40:43], v[150:153], v[212:215], v[40:43]
	v_mfma_f32_16x16x32_bf16 v[28:31], v[142:145], v[220:223], v[28:31]
	v_mfma_f32_16x16x32_bf16 v[24:27], v[150:153], v[220:223], v[24:27]
	v_mfma_f32_16x16x32_bf16 v[12:15], v[142:145], v[228:231], v[12:15]
	v_mfma_f32_16x16x32_bf16 v[8:11], v[150:153], v[228:231], v[8:11]
	v_mfma_f32_16x16x32_bf16 v[60:63], v[146:149], v[208:211], v[60:63]
	v_mfma_f32_16x16x32_bf16 v[56:59], v[154:157], v[208:211], v[56:59]
	v_mfma_f32_16x16x32_bf16 v[44:47], v[146:149], v[216:219], v[44:47]
	v_mfma_f32_16x16x32_bf16 v[40:43], v[154:157], v[216:219], v[40:43]
	v_mfma_f32_16x16x32_bf16 v[28:31], v[146:149], v[224:227], v[28:31]
	v_mfma_f32_16x16x32_bf16 v[24:27], v[154:157], v[224:227], v[24:27]
	v_mfma_f32_16x16x32_bf16 v[12:15], v[146:149], v[232:235], v[12:15]
	v_mfma_f32_16x16x32_bf16 v[8:11], v[154:157], v[232:235], v[8:11]
	s_setprio 0
	s_setprio 1
	v_mfma_f32_16x16x32_bf16 v[52:55], v[158:161], v[204:207], v[52:55]
	v_mfma_f32_16x16x32_bf16 v[48:51], v[196:199], v[204:207], v[48:51]
	v_mfma_f32_16x16x32_bf16 v[36:39], v[158:161], v[212:215], v[36:39]
	v_mfma_f32_16x16x32_bf16 v[32:35], v[196:199], v[212:215], v[32:35]
	v_mfma_f32_16x16x32_bf16 v[20:23], v[158:161], v[220:223], v[20:23]
	v_mfma_f32_16x16x32_bf16 v[16:19], v[196:199], v[220:223], v[16:19]
	v_mfma_f32_16x16x32_bf16 v[4:7], v[158:161], v[228:231], v[4:7]
	v_mfma_f32_16x16x32_bf16 v[0:3], v[196:199], v[228:231], v[0:3]
	v_mfma_f32_16x16x32_bf16 v[52:55], v[188:191], v[208:211], v[52:55]
	v_mfma_f32_16x16x32_bf16 v[48:51], v[200:203], v[208:211], v[48:51]
	v_mfma_f32_16x16x32_bf16 v[36:39], v[188:191], v[216:219], v[36:39]
	v_mfma_f32_16x16x32_bf16 v[32:35], v[200:203], v[216:219], v[32:35]
	v_mfma_f32_16x16x32_bf16 v[20:23], v[188:191], v[224:227], v[20:23]
	v_mfma_f32_16x16x32_bf16 v[16:19], v[200:203], v[224:227], v[16:19]
	v_mfma_f32_16x16x32_bf16 v[4:7], v[188:191], v[232:235], v[4:7]
	v_mfma_f32_16x16x32_bf16 v[0:3], v[200:203], v[232:235], v[0:3]
	s_setprio 0
	s_barrier
	s_add_i32 s9, 0, 0x18000
	s_add_i32 s10, 0, 0x1c000
	v_add_u32_e32 v154, s9, v165
	v_add_u32_e32 v187, s10, v165
	ds_read_b128 v[142:145], v154
	ds_read_b128 v[146:149], v154 offset:1024
	ds_read_b128 v[150:153], v154 offset:2048
	ds_read_b128 v[154:157], v154 offset:3072
	ds_read_b128 v[158:161], v187
	ds_read_b128 v[188:191], v187 offset:1024
	ds_read_b128 v[196:199], v187 offset:2048
	ds_read_b128 v[200:203], v187 offset:3072
	s_add_u32 s86, s86, 0x40000
	s_addc_u32 s87, s87, 0
	s_mov_b32 m0, s76
	ds_read_b128 v[204:207], v170 offset:32768
	ds_read_b128 v[208:211], v170 offset:33792
	ds_read_b128 v[212:215], v170 offset:34816
	ds_read_b128 v[216:219], v170 offset:35840
	ds_read_b128 v[220:223], v170 offset:36864
	ds_read_b128 v[224:227], v170 offset:37888
	ds_read_b128 v[228:231], v170 offset:38912
	ds_read_b128 v[232:235], v170 offset:39936
	global_load_lds_dwordx4 v128, s[86:87]
	v_lshl_add_u64 v[248:249], s[86:87], 0, v[132:133]
	s_mov_b32 m0, s77
	s_nop 0
	global_load_lds_dwordx4 v[248:249], off
	s_waitcnt vmcnt(8)
	s_waitcnt lgkmcnt(0)
	s_barrier
	s_setprio 1
	s_waitcnt lgkmcnt(0)
	v_mfma_f32_16x16x32_bf16 v[124:127], v[142:145], v[204:207], v[124:127]
	v_mfma_f32_16x16x32_bf16 v[120:123], v[150:153], v[204:207], v[120:123]
	v_mfma_f32_16x16x32_bf16 v[108:111], v[142:145], v[212:215], v[108:111]
	v_mfma_f32_16x16x32_bf16 v[104:107], v[150:153], v[212:215], v[104:107]
	v_mfma_f32_16x16x32_bf16 v[92:95], v[142:145], v[220:223], v[92:95]
	v_mfma_f32_16x16x32_bf16 v[88:91], v[150:153], v[220:223], v[88:91]
	v_mfma_f32_16x16x32_bf16 v[76:79], v[142:145], v[228:231], v[76:79]
	v_mfma_f32_16x16x32_bf16 v[72:75], v[150:153], v[228:231], v[72:75]
	v_mfma_f32_16x16x32_bf16 v[124:127], v[146:149], v[208:211], v[124:127]
	v_mfma_f32_16x16x32_bf16 v[120:123], v[154:157], v[208:211], v[120:123]
	v_mfma_f32_16x16x32_bf16 v[108:111], v[146:149], v[216:219], v[108:111]
	v_mfma_f32_16x16x32_bf16 v[104:107], v[154:157], v[216:219], v[104:107]
	v_mfma_f32_16x16x32_bf16 v[92:95], v[146:149], v[224:227], v[92:95]
	v_mfma_f32_16x16x32_bf16 v[88:91], v[154:157], v[224:227], v[88:91]
	v_mfma_f32_16x16x32_bf16 v[76:79], v[146:149], v[232:235], v[76:79]
	v_mfma_f32_16x16x32_bf16 v[72:75], v[154:157], v[232:235], v[72:75]
	s_setprio 0
	s_setprio 1
	v_mfma_f32_16x16x32_bf16 v[116:119], v[158:161], v[204:207], v[116:119]
	v_mfma_f32_16x16x32_bf16 v[112:115], v[196:199], v[204:207], v[112:115]
	v_mfma_f32_16x16x32_bf16 v[100:103], v[158:161], v[212:215], v[100:103]
	v_mfma_f32_16x16x32_bf16 v[96:99], v[196:199], v[212:215], v[96:99]
	v_mfma_f32_16x16x32_bf16 v[84:87], v[158:161], v[220:223], v[84:87]
	v_mfma_f32_16x16x32_bf16 v[80:83], v[196:199], v[220:223], v[80:83]
	v_mfma_f32_16x16x32_bf16 v[68:71], v[158:161], v[228:231], v[68:71]
	v_mfma_f32_16x16x32_bf16 v[64:67], v[196:199], v[228:231], v[64:67]
	v_mfma_f32_16x16x32_bf16 v[116:119], v[188:191], v[208:211], v[116:119]
	v_mfma_f32_16x16x32_bf16 v[112:115], v[200:203], v[208:211], v[112:115]
	v_mfma_f32_16x16x32_bf16 v[100:103], v[188:191], v[216:219], v[100:103]
	v_mfma_f32_16x16x32_bf16 v[96:99], v[200:203], v[216:219], v[96:99]
	v_mfma_f32_16x16x32_bf16 v[84:87], v[188:191], v[224:227], v[84:87]
	v_mfma_f32_16x16x32_bf16 v[80:83], v[200:203], v[224:227], v[80:83]
	v_mfma_f32_16x16x32_bf16 v[68:71], v[188:191], v[232:235], v[68:71]
	v_mfma_f32_16x16x32_bf16 v[64:67], v[200:203], v[232:235], v[64:67]
	s_setprio 0
	s_barrier
; #define PG8_STAGE(bufoff, gbase, voff) do { _Pragma("unroll") for (int _i = 0; _i < 2; ++_i) \
;         __builtin_amdgcn_global_load_lds((const unsigned*)((const char*)(gbase) + (voff)[_i]), (PG8_LAS unsigned*)(lds + (bufoff) + ldsw + _i * 8192), 16, 0, 0); } while (0)
; #define PG8_LDA(dst, b, h) do { _Pragma("unroll") for (int m = 0; m < 4; ++m) _Pragma("unroll") for (int k = 0; k < 2; ++k) dst[m][k] = *(const PG8_LAS bf16x8*)(lds + PG8_SA(b, h) + aoff + m * 2048 + k * 1024); } while (0)
; #define PG8_MMA(ai, bj, At, Bt) do { __builtin_amdgcn_s_setprio(1); _Pragma("unroll") for (int m = 0; m < 4; ++m) _Pragma("unroll") for (int n = 0; n < 2; ++n) _Pragma("unroll") for (int k = 0; k < 2; ++k) \
;         acc[ai][bj][m][n] = __builtin_amdgcn_mfma_f32_16x16x32_bf16(Bt[n][k], At[m][k], acc[ai][bj][m][n], 0, 0, 0); __builtin_amdgcn_s_setprio(0); } while (0)
; #define PG8_WAIT_V(n) asm volatile("s_waitcnt vmcnt(" #n ")" ::: "memory")
; #define PG8_WAIT_L(n) asm volatile("s_waitcnt lgkmcnt(" #n ")" ::: "memory")
; #define PG8_BAR __builtin_amdgcn_s_barrier()
; #define PG8_SCHED __builtin_amdgcn_sched_barrier(0)
; template <class Epi, class Sched, bool ALIGN_EPI = false, bool SP2 = false>
; __device__ __forceinline__ void gemm_phase(PG8_LAS unsigned char* lds, const Gemm g, const Sched& S, const Epi& E, const int tid) {
;     ...
;             PG8_LDA(At, 1, 1); PG8_STAGE(PG8_SB(1, 0), b3, voffB); PG8_STAGE(PG8_SB(1, 1), b3 + hstep, voffB); PG8_STAGE(PG8_SA(1, 0), a3, voffA);
;             PG8_WAIT_V(8); PG8_WAIT_L(0); PG8_BAR; PG8_MMA(1, 0, At, B0); PG8_MMA(1, 1, At, B1); PG8_BAR; PG8_SCHED;
	s_add_i32 s9, s9, s95
	v_lshl_add_u64 v[162:163], v[162:163], 0, s[22:23]
	s_mov_b32 m0, s9
	ds_read_b128 v[204:207], v170 offset:49152
	ds_read_b128 v[208:211], v170 offset:50176
	ds_read_b128 v[212:215], v170 offset:51200
	ds_read_b128 v[216:219], v170 offset:52224
	ds_read_b128 v[220:223], v170 offset:53248
	ds_read_b128 v[224:227], v170 offset:54272
	ds_read_b128 v[228:231], v170 offset:55296
	ds_read_b128 v[232:235], v170 offset:56320
	global_load_lds_dwordx4 v[162:163], off
	s_add_i32 m0, s9, 0x2000
	s_add_u32 s42, s42, 0x40080
	v_lshl_add_u64 v[162:163], v[236:237], 0, s[22:23]
	s_addc_u32 s43, s43, 0
	s_add_i32 s9, s10, s95
	global_load_lds_dwordx4 v[162:163], off
	s_mov_b32 m0, s9
	s_nop 0
	global_load_lds_dwordx4 v130, s[42:43]
	s_add_i32 m0, s9, 0x2000
	s_nop 0
	global_load_lds_dwordx4 v134, s[42:43]
	v_lshl_add_u64 v[162:163], v[238:239], 0, s[22:23]
	s_mov_b32 m0, s5
	s_nop 0
	global_load_lds_dwordx4 v[162:163], off
	v_lshl_add_u64 v[162:163], v[240:241], 0, s[22:23]
	s_mov_b32 m0, s6
	s_nop 0
	global_load_lds_dwordx4 v[162:163], off
	s_waitcnt vmcnt(8)
	s_waitcnt lgkmcnt(0)
	s_barrier
	s_setprio 1
	s_waitcnt lgkmcnt(0)
	v_mfma_f32_16x16x32_bf16 v[60:63], v[142:145], v[204:207], v[60:63]
	v_mfma_f32_16x16x32_bf16 v[56:59], v[150:153], v[204:207], v[56:59]
	v_mfma_f32_16x16x32_bf16 v[44:47], v[142:145], v[212:215], v[44:47]
	v_mfma_f32_16x16x32_bf16 v[40:43], v[150:153], v[212:215], v[40:43]
	v_mfma_f32_16x16x32_bf16 v[28:31], v[142:145], v[220:223], v[28:31]
	v_mfma_f32_16x16x32_bf16 v[24:27], v[150:153], v[220:223], v[24:27]
	v_mfma_f32_16x16x32_bf16 v[12:15], v[142:145], v[228:231], v[12:15]
	v_mfma_f32_16x16x32_bf16 v[8:11], v[150:153], v[228:231], v[8:11]
	v_mfma_f32_16x16x32_bf16 v[60:63], v[146:149], v[208:211], v[60:63]
	v_mfma_f32_16x16x32_bf16 v[56:59], v[154:157], v[208:211], v[56:59]
	v_mfma_f32_16x16x32_bf16 v[44:47], v[146:149], v[216:219], v[44:47]
	v_mfma_f32_16x16x32_bf16 v[40:43], v[154:157], v[216:219], v[40:43]
	v_mfma_f32_16x16x32_bf16 v[28:31], v[146:149], v[224:227], v[28:31]
	v_mfma_f32_16x16x32_bf16 v[24:27], v[154:157], v[224:227], v[24:27]
	v_mfma_f32_16x16x32_bf16 v[12:15], v[146:149], v[232:235], v[12:15]
	v_mfma_f32_16x16x32_bf16 v[8:11], v[154:157], v[232:235], v[8:11]
	s_setprio 0
	s_setprio 1
	v_mfma_f32_16x16x32_bf16 v[52:55], v[158:161], v[204:207], v[52:55]
	v_mfma_f32_16x16x32_bf16 v[48:51], v[196:199], v[204:207], v[48:51]
	v_mfma_f32_16x16x32_bf16 v[36:39], v[158:161], v[212:215], v[36:39]
	v_mfma_f32_16x16x32_bf16 v[32:35], v[196:199], v[212:215], v[32:35]
	v_mfma_f32_16x16x32_bf16 v[20:23], v[158:161], v[220:223], v[20:23]
	v_mfma_f32_16x16x32_bf16 v[16:19], v[196:199], v[220:223], v[16:19]
	v_mfma_f32_16x16x32_bf16 v[4:7], v[158:161], v[228:231], v[4:7]
	v_mfma_f32_16x16x32_bf16 v[0:3], v[196:199], v[228:231], v[0:3]
	v_mfma_f32_16x16x32_bf16 v[52:55], v[188:191], v[208:211], v[52:55]
	v_mfma_f32_16x16x32_bf16 v[48:51], v[200:203], v[208:211], v[48:51]
	v_mfma_f32_16x16x32_bf16 v[36:39], v[188:191], v[216:219], v[36:39]
	v_mfma_f32_16x16x32_bf16 v[32:35], v[200:203], v[216:219], v[32:35]
	v_mfma_f32_16x16x32_bf16 v[20:23], v[188:191], v[224:227], v[20:23]
	v_mfma_f32_16x16x32_bf16 v[16:19], v[200:203], v[224:227], v[16:19]
	v_mfma_f32_16x16x32_bf16 v[4:7], v[188:191], v[232:235], v[4:7]
	v_mfma_f32_16x16x32_bf16 v[0:3], v[200:203], v[232:235], v[0:3]
	s_setprio 0
	s_barrier
	s_add_i32 s8, s8, 2
	s_add_u32 s0, s0, 0x100
	s_addc_u32 s1, s1, 0
	s_add_u32 s56, s56, 0x100
	s_addc_u32 s57, s57, 0
	s_cmp_gt_u32 s8, 13
	s_cbranch_scc0 .LBB0_459
	s_and_b64 vcc, exec, s[66:67]
	s_cbranch_vccz .LBB0_462
	s_barrier
